# plus mod_item loops software-pipelined (16 ada_w loads in flight, 33 c loads up front)
# speedup vs baseline: 1.0179x; 1.0119x over previous
; __device__ void mod_item(const Params& p, int item, float* lds, int wave) {
;     ...
;     for (int half = 0; half < 2; ++half) {
;         __syncthreads();
;         for (int e = tid; e < NB * 512; e += NTHR) { const int b = e >> 9, kk = e & 511;
;             const float c = b < 32 ? p.c_prompt[b * D + half * 512 + kk] : p.c_sample[half * 512 + kk];
;             lds[kk * 36 + b] = c / (1.f + __expf(-c)); }
.LBB0_36:
	s_andn2_b64 vcc, exec, s[0:1]
	s_cbranch_vccnz .LBB0_51
	v_mov_b32_e32 v2, s70
	v_mbcnt_lo_u32_b32 v0, -1, 0
	v_mbcnt_hi_u32_b32 v0, -1, v0
	s_movk_i32 s0, 0x4200
	v_or_b32_e32 v65, s70, v0
	v_bitop3_b32 v70, v0, s42, v2 bitop3:0xc8
	v_cmp_gt_i32_e64 s[0:1], s0, v65
	v_lshlrev_b32_e32 v36, 2, v70
	v_mad_u32_u24 v71, v70, s43, 0
	s_barrier
	s_and_saveexec_b64 s[4:5], s[0:1]
	v_readlane_b32 s8, v253, 12
	v_readlane_b32 s12, v253, 16
	v_readlane_b32 s13, v253, 17
	v_readlane_b32 s14, v253, 18
	v_readlane_b32 s15, v253, 19
	v_readlane_b32 s9, v253, 13
	v_readlane_b32 s10, v253, 14
	v_readlane_b32 s11, v253, 15
	v_readlane_b32 s16, v253, 20
	v_readlane_b32 s17, v253, 21
	v_readlane_b32 s18, v253, 22
	v_readlane_b32 s19, v253, 23
	v_readlane_b32 s20, v253, 24
	v_readlane_b32 s21, v253, 25
	v_readlane_b32 s22, v253, 26
	v_readlane_b32 s23, v253, 27
	s_cbranch_execz .LBB0_40
	v_mov_b32_e32 v37, v1
	v_lshl_add_u64 v[2:3], s[14:15], 0, v[36:37]
	s_mov_b64 s[6:7], 0
	v_mov_b32_e32 v4, v65
	s_mov_b64 s[100:101], 0x1000
	v_mov_b32_e32 v185, v1
	v_lshlrev_b32_e32 v184, 2, v70
	v_lshl_add_u64 v[184:185], s[12:13], 0, v[184:185]
	global_load_dword v118, v[184:185], off
	v_lshl_add_u64 v[184:185], v[184:185], 0, s[100:101]
	global_load_dword v119, v[184:185], off
	v_lshl_add_u64 v[184:185], v[184:185], 0, s[100:101]
	global_load_dword v120, v[184:185], off
	v_lshl_add_u64 v[184:185], v[184:185], 0, s[100:101]
	global_load_dword v121, v[184:185], off
	v_lshl_add_u64 v[184:185], v[184:185], 0, s[100:101]
	global_load_dword v122, v[184:185], off
	v_lshl_add_u64 v[184:185], v[184:185], 0, s[100:101]
	global_load_dword v123, v[184:185], off
	v_lshl_add_u64 v[184:185], v[184:185], 0, s[100:101]
	global_load_dword v124, v[184:185], off
	v_lshl_add_u64 v[184:185], v[184:185], 0, s[100:101]
	global_load_dword v125, v[184:185], off
	v_lshl_add_u64 v[184:185], v[184:185], 0, s[100:101]
	global_load_dword v126, v[184:185], off
	v_lshl_add_u64 v[184:185], v[184:185], 0, s[100:101]
	global_load_dword v127, v[184:185], off
	v_lshl_add_u64 v[184:185], v[184:185], 0, s[100:101]
	global_load_dword v128, v[184:185], off
	v_lshl_add_u64 v[184:185], v[184:185], 0, s[100:101]
	global_load_dword v129, v[184:185], off
	v_lshl_add_u64 v[184:185], v[184:185], 0, s[100:101]
	global_load_dword v130, v[184:185], off
	v_lshl_add_u64 v[184:185], v[184:185], 0, s[100:101]
	global_load_dword v131, v[184:185], off
	v_lshl_add_u64 v[184:185], v[184:185], 0, s[100:101]
	global_load_dword v132, v[184:185], off
	v_lshl_add_u64 v[184:185], v[184:185], 0, s[100:101]
	global_load_dword v133, v[184:185], off
	v_lshl_add_u64 v[184:185], v[184:185], 0, s[100:101]
	global_load_dword v134, v[184:185], off
	v_lshl_add_u64 v[184:185], v[184:185], 0, s[100:101]
	global_load_dword v135, v[184:185], off
	v_lshl_add_u64 v[184:185], v[184:185], 0, s[100:101]
	global_load_dword v136, v[184:185], off
	v_lshl_add_u64 v[184:185], v[184:185], 0, s[100:101]
	global_load_dword v137, v[184:185], off
	v_lshl_add_u64 v[184:185], v[184:185], 0, s[100:101]
	global_load_dword v138, v[184:185], off
	v_lshl_add_u64 v[184:185], v[184:185], 0, s[100:101]
	global_load_dword v139, v[184:185], off
	v_lshl_add_u64 v[184:185], v[184:185], 0, s[100:101]
	global_load_dword v140, v[184:185], off
	v_lshl_add_u64 v[184:185], v[184:185], 0, s[100:101]
	global_load_dword v141, v[184:185], off
	v_lshl_add_u64 v[184:185], v[184:185], 0, s[100:101]
	global_load_dword v142, v[184:185], off
	v_lshl_add_u64 v[184:185], v[184:185], 0, s[100:101]
	global_load_dword v143, v[184:185], off
	v_lshl_add_u64 v[184:185], v[184:185], 0, s[100:101]
	global_load_dword v144, v[184:185], off
	v_lshl_add_u64 v[184:185], v[184:185], 0, s[100:101]
	global_load_dword v145, v[184:185], off
	v_lshl_add_u64 v[184:185], v[184:185], 0, s[100:101]
	global_load_dword v146, v[184:185], off
	v_lshl_add_u64 v[184:185], v[184:185], 0, s[100:101]
	global_load_dword v147, v[184:185], off
	v_lshl_add_u64 v[184:185], v[184:185], 0, s[100:101]
	global_load_dword v148, v[184:185], off
	v_lshl_add_u64 v[184:185], v[184:185], 0, s[100:101]
	global_load_dword v149, v[184:185], off
	v_lshl_add_u64 v[184:185], v[184:185], 0, s[100:101]
	global_load_dword v150, v[2:3], off
	s_waitcnt vmcnt(32)
	v_mul_f32_e32 v184, 0xbfb8aa3b, v118
	v_exp_f32_e32 v185, v184
	s_nop 0
	v_add_f32_e32 v186, 1.0, v185
	v_div_scale_f32 v185, s[8:9], v186, v186, v118
	v_rcp_f32_e32 v187, v185
	v_div_scale_f32 v188, vcc, v118, v186, v118
	v_fma_f32 v189, -v185, v187, 1.0
	v_fmac_f32_e32 v187, v189, v187
	v_mul_f32_e32 v189, v188, v187
	v_fma_f32 v190, -v185, v189, v188
	v_fmac_f32_e32 v189, v190, v187
	v_fma_f32 v185, -v185, v189, v188
	v_div_fmas_f32 v185, v185, v187, v189
	v_div_fixup_f32 v118, v185, v186, v118
	ds_write_b32 v71, v118 offset:0
	s_waitcnt vmcnt(31)
	v_mul_f32_e32 v184, 0xbfb8aa3b, v119
	v_exp_f32_e32 v185, v184
	s_nop 0
	v_add_f32_e32 v186, 1.0, v185
	v_div_scale_f32 v185, s[8:9], v186, v186, v119
	v_rcp_f32_e32 v187, v185
	v_div_scale_f32 v188, vcc, v119, v186, v119
	v_fma_f32 v189, -v185, v187, 1.0
	v_fmac_f32_e32 v187, v189, v187
	v_mul_f32_e32 v189, v188, v187
	v_fma_f32 v190, -v185, v189, v188
	v_fmac_f32_e32 v189, v190, v187
	v_fma_f32 v185, -v185, v189, v188
	v_div_fmas_f32 v185, v185, v187, v189
	v_div_fixup_f32 v119, v185, v186, v119
	ds_write_b32 v71, v119 offset:4
	s_waitcnt vmcnt(30)
	v_mul_f32_e32 v184, 0xbfb8aa3b, v120
	v_exp_f32_e32 v185, v184
	s_nop 0
	v_add_f32_e32 v186, 1.0, v185
	v_div_scale_f32 v185, s[8:9], v186, v186, v120
	v_rcp_f32_e32 v187, v185
	v_div_scale_f32 v188, vcc, v120, v186, v120
	v_fma_f32 v189, -v185, v187, 1.0
	v_fmac_f32_e32 v187, v189, v187
	v_mul_f32_e32 v189, v188, v187
	v_fma_f32 v190, -v185, v189, v188
	v_fmac_f32_e32 v189, v190, v187
	v_fma_f32 v185, -v185, v189, v188
	v_div_fmas_f32 v185, v185, v187, v189
	v_div_fixup_f32 v120, v185, v186, v120
	ds_write_b32 v71, v120 offset:8
	s_waitcnt vmcnt(29)
; __device__ void mod_item(const Params& p, int item, float* lds, int wave) {
;     ...
;         for (int e = tid; e < NB * 512; e += NTHR) { const int b = e >> 9, kk = e & 511;
;             const float c = b < 32 ? p.c_prompt[b * D + half * 512 + kk] : p.c_sample[half * 512 + kk];
;             lds[kk * 36 + b] = c / (1.f + __expf(-c)); }
	v_mul_f32_e32 v184, 0xbfb8aa3b, v121
	v_exp_f32_e32 v185, v184
	s_nop 0
	v_add_f32_e32 v186, 1.0, v185
	v_div_scale_f32 v185, s[8:9], v186, v186, v121
	v_rcp_f32_e32 v187, v185
	v_div_scale_f32 v188, vcc, v121, v186, v121
	v_fma_f32 v189, -v185, v187, 1.0
	v_fmac_f32_e32 v187, v189, v187
	v_mul_f32_e32 v189, v188, v187
	v_fma_f32 v190, -v185, v189, v188
	v_fmac_f32_e32 v189, v190, v187
	v_fma_f32 v185, -v185, v189, v188
	v_div_fmas_f32 v185, v185, v187, v189
	v_div_fixup_f32 v121, v185, v186, v121
	ds_write_b32 v71, v121 offset:12
	s_waitcnt vmcnt(28)
	v_mul_f32_e32 v184, 0xbfb8aa3b, v122
	v_exp_f32_e32 v185, v184
	s_nop 0
	v_add_f32_e32 v186, 1.0, v185
	v_div_scale_f32 v185, s[8:9], v186, v186, v122
	v_rcp_f32_e32 v187, v185
	v_div_scale_f32 v188, vcc, v122, v186, v122
	v_fma_f32 v189, -v185, v187, 1.0
	v_fmac_f32_e32 v187, v189, v187
	v_mul_f32_e32 v189, v188, v187
	v_fma_f32 v190, -v185, v189, v188
	v_fmac_f32_e32 v189, v190, v187
	v_fma_f32 v185, -v185, v189, v188
	v_div_fmas_f32 v185, v185, v187, v189
	v_div_fixup_f32 v122, v185, v186, v122
	ds_write_b32 v71, v122 offset:16
	s_waitcnt vmcnt(27)
	v_mul_f32_e32 v184, 0xbfb8aa3b, v123
	v_exp_f32_e32 v185, v184
	s_nop 0
	v_add_f32_e32 v186, 1.0, v185
	v_div_scale_f32 v185, s[8:9], v186, v186, v123
	v_rcp_f32_e32 v187, v185
	v_div_scale_f32 v188, vcc, v123, v186, v123
	v_fma_f32 v189, -v185, v187, 1.0
	v_fmac_f32_e32 v187, v189, v187
	v_mul_f32_e32 v189, v188, v187
	v_fma_f32 v190, -v185, v189, v188
	v_fmac_f32_e32 v189, v190, v187
	v_fma_f32 v185, -v185, v189, v188
	v_div_fmas_f32 v185, v185, v187, v189
	v_div_fixup_f32 v123, v185, v186, v123
	ds_write_b32 v71, v123 offset:20
	s_waitcnt vmcnt(26)
	v_mul_f32_e32 v184, 0xbfb8aa3b, v124
	v_exp_f32_e32 v185, v184
	s_nop 0
	v_add_f32_e32 v186, 1.0, v185
	v_div_scale_f32 v185, s[8:9], v186, v186, v124
	v_rcp_f32_e32 v187, v185
	v_div_scale_f32 v188, vcc, v124, v186, v124
	v_fma_f32 v189, -v185, v187, 1.0
	v_fmac_f32_e32 v187, v189, v187
	v_mul_f32_e32 v189, v188, v187
	v_fma_f32 v190, -v185, v189, v188
	v_fmac_f32_e32 v189, v190, v187
	v_fma_f32 v185, -v185, v189, v188
	v_div_fmas_f32 v185, v185, v187, v189
	v_div_fixup_f32 v124, v185, v186, v124
	ds_write_b32 v71, v124 offset:24
	s_waitcnt vmcnt(25)
	v_mul_f32_e32 v184, 0xbfb8aa3b, v125
	v_exp_f32_e32 v185, v184
	s_nop 0
	v_add_f32_e32 v186, 1.0, v185
	v_div_scale_f32 v185, s[8:9], v186, v186, v125
	v_rcp_f32_e32 v187, v185
	v_div_scale_f32 v188, vcc, v125, v186, v125
	v_fma_f32 v189, -v185, v187, 1.0
	v_fmac_f32_e32 v187, v189, v187
	v_mul_f32_e32 v189, v188, v187
	v_fma_f32 v190, -v185, v189, v188
	v_fmac_f32_e32 v189, v190, v187
	v_fma_f32 v185, -v185, v189, v188
	v_div_fmas_f32 v185, v185, v187, v189
	v_div_fixup_f32 v125, v185, v186, v125
	ds_write_b32 v71, v125 offset:28
	s_waitcnt vmcnt(24)
	v_mul_f32_e32 v184, 0xbfb8aa3b, v126
	v_exp_f32_e32 v185, v184
	s_nop 0
	v_add_f32_e32 v186, 1.0, v185
	v_div_scale_f32 v185, s[8:9], v186, v186, v126
	v_rcp_f32_e32 v187, v185
	v_div_scale_f32 v188, vcc, v126, v186, v126
	v_fma_f32 v189, -v185, v187, 1.0
	v_fmac_f32_e32 v187, v189, v187
	v_mul_f32_e32 v189, v188, v187
	v_fma_f32 v190, -v185, v189, v188
	v_fmac_f32_e32 v189, v190, v187
	v_fma_f32 v185, -v185, v189, v188
	v_div_fmas_f32 v185, v185, v187, v189
	v_div_fixup_f32 v126, v185, v186, v126
	ds_write_b32 v71, v126 offset:32
	s_waitcnt vmcnt(23)
	v_mul_f32_e32 v184, 0xbfb8aa3b, v127
	v_exp_f32_e32 v185, v184
	s_nop 0
	v_add_f32_e32 v186, 1.0, v185
	v_div_scale_f32 v185, s[8:9], v186, v186, v127
	v_rcp_f32_e32 v187, v185
	v_div_scale_f32 v188, vcc, v127, v186, v127
	v_fma_f32 v189, -v185, v187, 1.0
	v_fmac_f32_e32 v187, v189, v187
	v_mul_f32_e32 v189, v188, v187
	v_fma_f32 v190, -v185, v189, v188
	v_fmac_f32_e32 v189, v190, v187
	v_fma_f32 v185, -v185, v189, v188
	v_div_fmas_f32 v185, v185, v187, v189
	v_div_fixup_f32 v127, v185, v186, v127
	ds_write_b32 v71, v127 offset:36
	s_waitcnt vmcnt(22)
	v_mul_f32_e32 v184, 0xbfb8aa3b, v128
	v_exp_f32_e32 v185, v184
	s_nop 0
	v_add_f32_e32 v186, 1.0, v185
	v_div_scale_f32 v185, s[8:9], v186, v186, v128
	v_rcp_f32_e32 v187, v185
	v_div_scale_f32 v188, vcc, v128, v186, v128
	v_fma_f32 v189, -v185, v187, 1.0
	v_fmac_f32_e32 v187, v189, v187
	v_mul_f32_e32 v189, v188, v187
	v_fma_f32 v190, -v185, v189, v188
	v_fmac_f32_e32 v189, v190, v187
	v_fma_f32 v185, -v185, v189, v188
	v_div_fmas_f32 v185, v185, v187, v189
	v_div_fixup_f32 v128, v185, v186, v128
	ds_write_b32 v71, v128 offset:40
	s_waitcnt vmcnt(21)
	v_mul_f32_e32 v184, 0xbfb8aa3b, v129
	v_exp_f32_e32 v185, v184
	s_nop 0
	v_add_f32_e32 v186, 1.0, v185
	v_div_scale_f32 v185, s[8:9], v186, v186, v129
	v_rcp_f32_e32 v187, v185
	v_div_scale_f32 v188, vcc, v129, v186, v129
	v_fma_f32 v189, -v185, v187, 1.0
	v_fmac_f32_e32 v187, v189, v187
	v_mul_f32_e32 v189, v188, v187
	v_fma_f32 v190, -v185, v189, v188
	v_fmac_f32_e32 v189, v190, v187
	v_fma_f32 v185, -v185, v189, v188
	v_div_fmas_f32 v185, v185, v187, v189
	v_div_fixup_f32 v129, v185, v186, v129
	ds_write_b32 v71, v129 offset:44
	s_waitcnt vmcnt(20)
	v_mul_f32_e32 v184, 0xbfb8aa3b, v130
	v_exp_f32_e32 v185, v184
	s_nop 0
	v_add_f32_e32 v186, 1.0, v185
	v_div_scale_f32 v185, s[8:9], v186, v186, v130
	v_rcp_f32_e32 v187, v185
	v_div_scale_f32 v188, vcc, v130, v186, v130
	v_fma_f32 v189, -v185, v187, 1.0
	v_fmac_f32_e32 v187, v189, v187
	v_mul_f32_e32 v189, v188, v187
	v_fma_f32 v190, -v185, v189, v188
	v_fmac_f32_e32 v189, v190, v187
	v_fma_f32 v185, -v185, v189, v188
	v_div_fmas_f32 v185, v185, v187, v189
	v_div_fixup_f32 v130, v185, v186, v130
	ds_write_b32 v71, v130 offset:48
	s_waitcnt vmcnt(19)
; __device__ void mod_item(const Params& p, int item, float* lds, int wave) {
;     ...
;         for (int e = tid; e < NB * 512; e += NTHR) { const int b = e >> 9, kk = e & 511;
;             const float c = b < 32 ? p.c_prompt[b * D + half * 512 + kk] : p.c_sample[half * 512 + kk];
;             lds[kk * 36 + b] = c / (1.f + __expf(-c)); }
	v_mul_f32_e32 v184, 0xbfb8aa3b, v131
	v_exp_f32_e32 v185, v184
	s_nop 0
	v_add_f32_e32 v186, 1.0, v185
	v_div_scale_f32 v185, s[8:9], v186, v186, v131
	v_rcp_f32_e32 v187, v185
	v_div_scale_f32 v188, vcc, v131, v186, v131
	v_fma_f32 v189, -v185, v187, 1.0
	v_fmac_f32_e32 v187, v189, v187
	v_mul_f32_e32 v189, v188, v187
	v_fma_f32 v190, -v185, v189, v188
	v_fmac_f32_e32 v189, v190, v187
	v_fma_f32 v185, -v185, v189, v188
	v_div_fmas_f32 v185, v185, v187, v189
	v_div_fixup_f32 v131, v185, v186, v131
	ds_write_b32 v71, v131 offset:52
	s_waitcnt vmcnt(18)
	v_mul_f32_e32 v184, 0xbfb8aa3b, v132
	v_exp_f32_e32 v185, v184
	s_nop 0
	v_add_f32_e32 v186, 1.0, v185
	v_div_scale_f32 v185, s[8:9], v186, v186, v132
	v_rcp_f32_e32 v187, v185
	v_div_scale_f32 v188, vcc, v132, v186, v132
	v_fma_f32 v189, -v185, v187, 1.0
	v_fmac_f32_e32 v187, v189, v187
	v_mul_f32_e32 v189, v188, v187
	v_fma_f32 v190, -v185, v189, v188
	v_fmac_f32_e32 v189, v190, v187
	v_fma_f32 v185, -v185, v189, v188
	v_div_fmas_f32 v185, v185, v187, v189
	v_div_fixup_f32 v132, v185, v186, v132
	ds_write_b32 v71, v132 offset:56
	s_waitcnt vmcnt(17)
	v_mul_f32_e32 v184, 0xbfb8aa3b, v133
	v_exp_f32_e32 v185, v184
	s_nop 0
	v_add_f32_e32 v186, 1.0, v185
	v_div_scale_f32 v185, s[8:9], v186, v186, v133
	v_rcp_f32_e32 v187, v185
	v_div_scale_f32 v188, vcc, v133, v186, v133
	v_fma_f32 v189, -v185, v187, 1.0
	v_fmac_f32_e32 v187, v189, v187
	v_mul_f32_e32 v189, v188, v187
	v_fma_f32 v190, -v185, v189, v188
	v_fmac_f32_e32 v189, v190, v187
	v_fma_f32 v185, -v185, v189, v188
	v_div_fmas_f32 v185, v185, v187, v189
	v_div_fixup_f32 v133, v185, v186, v133
	ds_write_b32 v71, v133 offset:60
	s_waitcnt vmcnt(16)
	v_mul_f32_e32 v184, 0xbfb8aa3b, v134
	v_exp_f32_e32 v185, v184
	s_nop 0
	v_add_f32_e32 v186, 1.0, v185
	v_div_scale_f32 v185, s[8:9], v186, v186, v134
	v_rcp_f32_e32 v187, v185
	v_div_scale_f32 v188, vcc, v134, v186, v134
	v_fma_f32 v189, -v185, v187, 1.0
	v_fmac_f32_e32 v187, v189, v187
	v_mul_f32_e32 v189, v188, v187
	v_fma_f32 v190, -v185, v189, v188
	v_fmac_f32_e32 v189, v190, v187
	v_fma_f32 v185, -v185, v189, v188
	v_div_fmas_f32 v185, v185, v187, v189
	v_div_fixup_f32 v134, v185, v186, v134
	ds_write_b32 v71, v134 offset:64
	s_waitcnt vmcnt(15)
	v_mul_f32_e32 v184, 0xbfb8aa3b, v135
	v_exp_f32_e32 v185, v184
	s_nop 0
	v_add_f32_e32 v186, 1.0, v185
	v_div_scale_f32 v185, s[8:9], v186, v186, v135
	v_rcp_f32_e32 v187, v185
	v_div_scale_f32 v188, vcc, v135, v186, v135
	v_fma_f32 v189, -v185, v187, 1.0
	v_fmac_f32_e32 v187, v189, v187
	v_mul_f32_e32 v189, v188, v187
	v_fma_f32 v190, -v185, v189, v188
	v_fmac_f32_e32 v189, v190, v187
	v_fma_f32 v185, -v185, v189, v188
	v_div_fmas_f32 v185, v185, v187, v189
	v_div_fixup_f32 v135, v185, v186, v135
	ds_write_b32 v71, v135 offset:68
	s_waitcnt vmcnt(14)
	v_mul_f32_e32 v184, 0xbfb8aa3b, v136
	v_exp_f32_e32 v185, v184
	s_nop 0
	v_add_f32_e32 v186, 1.0, v185
	v_div_scale_f32 v185, s[8:9], v186, v186, v136
	v_rcp_f32_e32 v187, v185
	v_div_scale_f32 v188, vcc, v136, v186, v136
	v_fma_f32 v189, -v185, v187, 1.0
	v_fmac_f32_e32 v187, v189, v187
	v_mul_f32_e32 v189, v188, v187
	v_fma_f32 v190, -v185, v189, v188
	v_fmac_f32_e32 v189, v190, v187
	v_fma_f32 v185, -v185, v189, v188
	v_div_fmas_f32 v185, v185, v187, v189
	v_div_fixup_f32 v136, v185, v186, v136
	ds_write_b32 v71, v136 offset:72
	s_waitcnt vmcnt(13)
	v_mul_f32_e32 v184, 0xbfb8aa3b, v137
	v_exp_f32_e32 v185, v184
	s_nop 0
	v_add_f32_e32 v186, 1.0, v185
	v_div_scale_f32 v185, s[8:9], v186, v186, v137
	v_rcp_f32_e32 v187, v185
	v_div_scale_f32 v188, vcc, v137, v186, v137
	v_fma_f32 v189, -v185, v187, 1.0
	v_fmac_f32_e32 v187, v189, v187
	v_mul_f32_e32 v189, v188, v187
	v_fma_f32 v190, -v185, v189, v188
	v_fmac_f32_e32 v189, v190, v187
	v_fma_f32 v185, -v185, v189, v188
	v_div_fmas_f32 v185, v185, v187, v189
	v_div_fixup_f32 v137, v185, v186, v137
	ds_write_b32 v71, v137 offset:76
	s_waitcnt vmcnt(12)
	v_mul_f32_e32 v184, 0xbfb8aa3b, v138
	v_exp_f32_e32 v185, v184
	s_nop 0
	v_add_f32_e32 v186, 1.0, v185
	v_div_scale_f32 v185, s[8:9], v186, v186, v138
	v_rcp_f32_e32 v187, v185
	v_div_scale_f32 v188, vcc, v138, v186, v138
	v_fma_f32 v189, -v185, v187, 1.0
	v_fmac_f32_e32 v187, v189, v187
	v_mul_f32_e32 v189, v188, v187
	v_fma_f32 v190, -v185, v189, v188
	v_fmac_f32_e32 v189, v190, v187
	v_fma_f32 v185, -v185, v189, v188
	v_div_fmas_f32 v185, v185, v187, v189
	v_div_fixup_f32 v138, v185, v186, v138
	ds_write_b32 v71, v138 offset:80
	s_waitcnt vmcnt(11)
	v_mul_f32_e32 v184, 0xbfb8aa3b, v139
	v_exp_f32_e32 v185, v184
	s_nop 0
	v_add_f32_e32 v186, 1.0, v185
	v_div_scale_f32 v185, s[8:9], v186, v186, v139
	v_rcp_f32_e32 v187, v185
	v_div_scale_f32 v188, vcc, v139, v186, v139
	v_fma_f32 v189, -v185, v187, 1.0
	v_fmac_f32_e32 v187, v189, v187
	v_mul_f32_e32 v189, v188, v187
	v_fma_f32 v190, -v185, v189, v188
	v_fmac_f32_e32 v189, v190, v187
	v_fma_f32 v185, -v185, v189, v188
	v_div_fmas_f32 v185, v185, v187, v189
	v_div_fixup_f32 v139, v185, v186, v139
	ds_write_b32 v71, v139 offset:84
	s_waitcnt vmcnt(10)
	v_mul_f32_e32 v184, 0xbfb8aa3b, v140
	v_exp_f32_e32 v185, v184
	s_nop 0
	v_add_f32_e32 v186, 1.0, v185
	v_div_scale_f32 v185, s[8:9], v186, v186, v140
	v_rcp_f32_e32 v187, v185
	v_div_scale_f32 v188, vcc, v140, v186, v140
	v_fma_f32 v189, -v185, v187, 1.0
	v_fmac_f32_e32 v187, v189, v187
	v_mul_f32_e32 v189, v188, v187
	v_fma_f32 v190, -v185, v189, v188
	v_fmac_f32_e32 v189, v190, v187
	v_fma_f32 v185, -v185, v189, v188
	v_div_fmas_f32 v185, v185, v187, v189
	v_div_fixup_f32 v140, v185, v186, v140
	ds_write_b32 v71, v140 offset:88
	s_waitcnt vmcnt(9)
; __device__ void mod_item(const Params& p, int item, float* lds, int wave) {
;     ...
;         for (int e = tid; e < NB * 512; e += NTHR) { const int b = e >> 9, kk = e & 511;
;             const float c = b < 32 ? p.c_prompt[b * D + half * 512 + kk] : p.c_sample[half * 512 + kk];
;             lds[kk * 36 + b] = c / (1.f + __expf(-c)); }
	v_mul_f32_e32 v184, 0xbfb8aa3b, v141
	v_exp_f32_e32 v185, v184
	s_nop 0
	v_add_f32_e32 v186, 1.0, v185
	v_div_scale_f32 v185, s[8:9], v186, v186, v141
	v_rcp_f32_e32 v187, v185
	v_div_scale_f32 v188, vcc, v141, v186, v141
	v_fma_f32 v189, -v185, v187, 1.0
	v_fmac_f32_e32 v187, v189, v187
	v_mul_f32_e32 v189, v188, v187
	v_fma_f32 v190, -v185, v189, v188
	v_fmac_f32_e32 v189, v190, v187
	v_fma_f32 v185, -v185, v189, v188
	v_div_fmas_f32 v185, v185, v187, v189
	v_div_fixup_f32 v141, v185, v186, v141
	ds_write_b32 v71, v141 offset:92
	s_waitcnt vmcnt(8)
	v_mul_f32_e32 v184, 0xbfb8aa3b, v142
	v_exp_f32_e32 v185, v184
	s_nop 0
	v_add_f32_e32 v186, 1.0, v185
	v_div_scale_f32 v185, s[8:9], v186, v186, v142
	v_rcp_f32_e32 v187, v185
	v_div_scale_f32 v188, vcc, v142, v186, v142
	v_fma_f32 v189, -v185, v187, 1.0
	v_fmac_f32_e32 v187, v189, v187
	v_mul_f32_e32 v189, v188, v187
	v_fma_f32 v190, -v185, v189, v188
	v_fmac_f32_e32 v189, v190, v187
	v_fma_f32 v185, -v185, v189, v188
	v_div_fmas_f32 v185, v185, v187, v189
	v_div_fixup_f32 v142, v185, v186, v142
	ds_write_b32 v71, v142 offset:96
	s_waitcnt vmcnt(7)
	v_mul_f32_e32 v184, 0xbfb8aa3b, v143
	v_exp_f32_e32 v185, v184
	s_nop 0
	v_add_f32_e32 v186, 1.0, v185
	v_div_scale_f32 v185, s[8:9], v186, v186, v143
	v_rcp_f32_e32 v187, v185
	v_div_scale_f32 v188, vcc, v143, v186, v143
	v_fma_f32 v189, -v185, v187, 1.0
	v_fmac_f32_e32 v187, v189, v187
	v_mul_f32_e32 v189, v188, v187
	v_fma_f32 v190, -v185, v189, v188
	v_fmac_f32_e32 v189, v190, v187
	v_fma_f32 v185, -v185, v189, v188
	v_div_fmas_f32 v185, v185, v187, v189
	v_div_fixup_f32 v143, v185, v186, v143
	ds_write_b32 v71, v143 offset:100
	s_waitcnt vmcnt(6)
	v_mul_f32_e32 v184, 0xbfb8aa3b, v144
	v_exp_f32_e32 v185, v184
	s_nop 0
	v_add_f32_e32 v186, 1.0, v185
	v_div_scale_f32 v185, s[8:9], v186, v186, v144
	v_rcp_f32_e32 v187, v185
	v_div_scale_f32 v188, vcc, v144, v186, v144
	v_fma_f32 v189, -v185, v187, 1.0
	v_fmac_f32_e32 v187, v189, v187
	v_mul_f32_e32 v189, v188, v187
	v_fma_f32 v190, -v185, v189, v188
	v_fmac_f32_e32 v189, v190, v187
	v_fma_f32 v185, -v185, v189, v188
	v_div_fmas_f32 v185, v185, v187, v189
	v_div_fixup_f32 v144, v185, v186, v144
	ds_write_b32 v71, v144 offset:104
	s_waitcnt vmcnt(5)
	v_mul_f32_e32 v184, 0xbfb8aa3b, v145
	v_exp_f32_e32 v185, v184
	s_nop 0
	v_add_f32_e32 v186, 1.0, v185
	v_div_scale_f32 v185, s[8:9], v186, v186, v145
	v_rcp_f32_e32 v187, v185
	v_div_scale_f32 v188, vcc, v145, v186, v145
	v_fma_f32 v189, -v185, v187, 1.0
	v_fmac_f32_e32 v187, v189, v187
	v_mul_f32_e32 v189, v188, v187
	v_fma_f32 v190, -v185, v189, v188
	v_fmac_f32_e32 v189, v190, v187
	v_fma_f32 v185, -v185, v189, v188
	v_div_fmas_f32 v185, v185, v187, v189
	v_div_fixup_f32 v145, v185, v186, v145
	ds_write_b32 v71, v145 offset:108
	s_waitcnt vmcnt(4)
	v_mul_f32_e32 v184, 0xbfb8aa3b, v146
	v_exp_f32_e32 v185, v184
	s_nop 0
	v_add_f32_e32 v186, 1.0, v185
	v_div_scale_f32 v185, s[8:9], v186, v186, v146
	v_rcp_f32_e32 v187, v185
	v_div_scale_f32 v188, vcc, v146, v186, v146
	v_fma_f32 v189, -v185, v187, 1.0
	v_fmac_f32_e32 v187, v189, v187
	v_mul_f32_e32 v189, v188, v187
	v_fma_f32 v190, -v185, v189, v188
	v_fmac_f32_e32 v189, v190, v187
	v_fma_f32 v185, -v185, v189, v188
	v_div_fmas_f32 v185, v185, v187, v189
	v_div_fixup_f32 v146, v185, v186, v146
	ds_write_b32 v71, v146 offset:112
	s_waitcnt vmcnt(3)
	v_mul_f32_e32 v184, 0xbfb8aa3b, v147
	v_exp_f32_e32 v185, v184
	s_nop 0
	v_add_f32_e32 v186, 1.0, v185
	v_div_scale_f32 v185, s[8:9], v186, v186, v147
	v_rcp_f32_e32 v187, v185
	v_div_scale_f32 v188, vcc, v147, v186, v147
	v_fma_f32 v189, -v185, v187, 1.0
	v_fmac_f32_e32 v187, v189, v187
	v_mul_f32_e32 v189, v188, v187
	v_fma_f32 v190, -v185, v189, v188
	v_fmac_f32_e32 v189, v190, v187
	v_fma_f32 v185, -v185, v189, v188
	v_div_fmas_f32 v185, v185, v187, v189
	v_div_fixup_f32 v147, v185, v186, v147
	ds_write_b32 v71, v147 offset:116
	s_waitcnt vmcnt(2)
	v_mul_f32_e32 v184, 0xbfb8aa3b, v148
	v_exp_f32_e32 v185, v184
	s_nop 0
	v_add_f32_e32 v186, 1.0, v185
	v_div_scale_f32 v185, s[8:9], v186, v186, v148
	v_rcp_f32_e32 v187, v185
	v_div_scale_f32 v188, vcc, v148, v186, v148
	v_fma_f32 v189, -v185, v187, 1.0
	v_fmac_f32_e32 v187, v189, v187
	v_mul_f32_e32 v189, v188, v187
	v_fma_f32 v190, -v185, v189, v188
	v_fmac_f32_e32 v189, v190, v187
	v_fma_f32 v185, -v185, v189, v188
	v_div_fmas_f32 v185, v185, v187, v189
	v_div_fixup_f32 v148, v185, v186, v148
	ds_write_b32 v71, v148 offset:120
	s_waitcnt vmcnt(1)
	v_mul_f32_e32 v184, 0xbfb8aa3b, v149
	v_exp_f32_e32 v185, v184
	s_nop 0
	v_add_f32_e32 v186, 1.0, v185
	v_div_scale_f32 v185, s[8:9], v186, v186, v149
	v_rcp_f32_e32 v187, v185
	v_div_scale_f32 v188, vcc, v149, v186, v149
	v_fma_f32 v189, -v185, v187, 1.0
	v_fmac_f32_e32 v187, v189, v187
	v_mul_f32_e32 v189, v188, v187
	v_fma_f32 v190, -v185, v189, v188
	v_fmac_f32_e32 v189, v190, v187
	v_fma_f32 v185, -v185, v189, v188
	v_div_fmas_f32 v185, v185, v187, v189
	v_div_fixup_f32 v149, v185, v186, v149
	ds_write_b32 v71, v149 offset:124
	s_waitcnt vmcnt(0)
	v_mul_f32_e32 v184, 0xbfb8aa3b, v150
	v_exp_f32_e32 v185, v184
	s_nop 0
	v_add_f32_e32 v186, 1.0, v185
	v_div_scale_f32 v185, s[8:9], v186, v186, v150
	v_rcp_f32_e32 v187, v185
	v_div_scale_f32 v188, vcc, v150, v186, v150
	v_fma_f32 v189, -v185, v187, 1.0
	v_fmac_f32_e32 v187, v189, v187
	v_mul_f32_e32 v189, v188, v187
	v_fma_f32 v190, -v185, v189, v188
	v_fmac_f32_e32 v189, v190, v187
	v_fma_f32 v185, -v185, v189, v188
	v_div_fmas_f32 v185, v185, v187, v189
	v_div_fixup_f32 v150, v185, v186, v150
	ds_write_b32 v71, v150 offset:128
; __device__ void mod_item(const Params& p, int item, float* lds, int wave) {
;     ...
;         __syncthreads();
;         for (int kk = kg * 64; kk < kg * 64 + 64; ++kk) {
;             const float w = p.ada_w[(size_t)(half * 512 + kk) * MODW + col0 + col];
; #pragma unroll
;             for (int b = 0; b < NB; ++b) acc[b] += lds[kk * 36 + b] * w;
.LBB0_40:
	s_or_b64 exec, exec, s[4:5]
	s_lshl_b32 s3, s61, 6
	s_add_i32 s24, s3, 0xfffee000
	v_lshrrev_b32_e32 v3, 6, v65
	s_movk_i32 s3, 0x2400
	s_lshl_b64 s[4:5], s[24:25], 2
	v_and_b32_e32 v2, 63, v0
	v_and_b32_e32 v72, 0xffffffc0, v65
	v_mul_lo_u32 v0, v3, s3
	v_mov_b64_e32 v[4:5], s[4:5]
	v_add_u32_e32 v68, 0, v0
	v_mad_i64_i32 v[4:5], s[6:7], v72, s45, v[4:5]
	v_lshlrev_b32_e32 v0, 2, v2
	v_readlane_b32 s8, v253, 12
	v_add_u32_e32 v67, -1, v72
	v_or_b32_e32 v4, v4, v0
	v_readlane_b32 s16, v253, 20
	v_readlane_b32 s17, v253, 21
	v_mov_b32_e32 v69, 0
	v_or_b32_e32 v66, 63, v65
	v_lshl_add_u64 v[38:39], s[16:17], 0, v[4:5]
	s_mov_b64 s[6:7], 0
	v_mov_b32_e32 v37, v68
	v_mov_b32_e32 v73, v67
	v_mov_b32_e32 v4, 0
	v_mov_b32_e32 v5, v69
	v_mov_b32_e32 v6, 0
	v_mov_b32_e32 v7, v69
	v_mov_b32_e32 v8, 0
	v_mov_b32_e32 v9, v69
	v_mov_b32_e32 v10, 0
	v_mov_b32_e32 v11, v69
	v_mov_b32_e32 v12, 0
	v_mov_b32_e32 v13, v69
	v_mov_b32_e32 v14, 0
	v_mov_b32_e32 v15, v69
	v_mov_b32_e32 v16, 0
	v_mov_b32_e32 v17, v69
	v_mov_b32_e32 v18, 0
	v_mov_b32_e32 v19, v69
	v_mov_b32_e32 v20, 0
	v_mov_b32_e32 v21, v69
	v_mov_b32_e32 v22, 0
	v_mov_b32_e32 v23, v69
	v_mov_b32_e32 v24, 0
	v_mov_b32_e32 v25, v69
	v_mov_b32_e32 v26, 0
	v_mov_b32_e32 v27, v69
	v_mov_b32_e32 v28, 0
	v_mov_b32_e32 v29, v69
	v_mov_b32_e32 v30, 0
	v_mov_b32_e32 v31, v69
	v_mov_b32_e32 v32, 0
	v_mov_b32_e32 v33, v69
	v_mov_b32_e32 v34, 0
	v_mov_b32_e32 v35, v69
	s_waitcnt lgkmcnt(0)
	s_barrier
	v_readlane_b32 s9, v253, 13
	v_readlane_b32 s10, v253, 14
	v_readlane_b32 s11, v253, 15
	v_readlane_b32 s12, v253, 16
	v_readlane_b32 s13, v253, 17
	v_readlane_b32 s14, v253, 18
	v_readlane_b32 s15, v253, 19
	v_readlane_b32 s18, v253, 22
	v_readlane_b32 s19, v253, 23
	v_readlane_b32 s20, v253, 24
	v_readlane_b32 s21, v253, 25
	v_readlane_b32 s22, v253, 26
	v_readlane_b32 s23, v253, 27
	global_load_dword v152, v[38:39], off
	v_lshl_add_u64 v[38:39], v[38:39], 0, s[26:27]
	global_load_dword v154, v[38:39], off
	v_lshl_add_u64 v[38:39], v[38:39], 0, s[26:27]
	global_load_dword v156, v[38:39], off
	v_lshl_add_u64 v[38:39], v[38:39], 0, s[26:27]
	global_load_dword v158, v[38:39], off
	v_lshl_add_u64 v[38:39], v[38:39], 0, s[26:27]
	global_load_dword v160, v[38:39], off
	v_lshl_add_u64 v[38:39], v[38:39], 0, s[26:27]
	global_load_dword v162, v[38:39], off
	v_lshl_add_u64 v[38:39], v[38:39], 0, s[26:27]
	global_load_dword v164, v[38:39], off
	v_lshl_add_u64 v[38:39], v[38:39], 0, s[26:27]
	global_load_dword v166, v[38:39], off
	v_lshl_add_u64 v[38:39], v[38:39], 0, s[26:27]
	global_load_dword v168, v[38:39], off
	v_lshl_add_u64 v[38:39], v[38:39], 0, s[26:27]
	global_load_dword v170, v[38:39], off
	v_lshl_add_u64 v[38:39], v[38:39], 0, s[26:27]
	global_load_dword v172, v[38:39], off
	v_lshl_add_u64 v[38:39], v[38:39], 0, s[26:27]
	global_load_dword v174, v[38:39], off
	v_lshl_add_u64 v[38:39], v[38:39], 0, s[26:27]
	global_load_dword v176, v[38:39], off
	v_lshl_add_u64 v[38:39], v[38:39], 0, s[26:27]
	global_load_dword v178, v[38:39], off
	v_lshl_add_u64 v[38:39], v[38:39], 0, s[26:27]
	global_load_dword v180, v[38:39], off
	v_lshl_add_u64 v[38:39], v[38:39], 0, s[26:27]
	global_load_dword v182, v[38:39], off
	v_lshl_add_u64 v[38:39], v[38:39], 0, s[26:27]
	s_mov_b32 s98, 0
.Lmk_a_loop:
	s_cmp_eq_u32 s98, 3
	s_cbranch_scc0 .Lmk_a_go
	s_waitcnt vmcnt(0)
.Lmk_a_go:
	ds_read_b96 v[74:76], v37
	ds_read2_b32 v[80:81], v37 offset0:3 offset1:4
	ds_read2_b32 v[82:83], v37 offset0:5 offset1:6
	ds_read2_b32 v[84:85], v37 offset0:7 offset1:8
	ds_read2_b32 v[86:87], v37 offset0:9 offset1:10
	ds_read2_b32 v[88:89], v37 offset0:11 offset1:12
	ds_read2_b32 v[90:91], v37 offset0:13 offset1:14
	ds_read2_b32 v[92:93], v37 offset0:15 offset1:16
	ds_read2_b32 v[94:95], v37 offset0:17 offset1:18
	ds_read2_b32 v[96:97], v37 offset0:19 offset1:20
	ds_read2_b32 v[98:99], v37 offset0:21 offset1:22
	ds_read2_b32 v[100:101], v37 offset0:23 offset1:24
	ds_read2_b32 v[102:103], v37 offset0:25 offset1:26
	ds_read2_b32 v[104:105], v37 offset0:27 offset1:28
	ds_read2_b32 v[106:107], v37 offset0:29 offset1:30
	ds_read2_b32 v[108:109], v37 offset0:31 offset1:32
	s_waitcnt lgkmcnt(14)
	v_mov_b32_e32 v110, v75
	v_mov_b32_e32 v111, v76
	v_add_u32_e32 v37, 0x90, v37
	s_waitcnt vmcnt(15)
	v_fmac_f32_e32 v69, v152, v74
	v_pk_fma_f32 v[34:35], v[152:153], v[110:111], v[34:35] op_sel_hi:[0,1,1]
	v_pk_fma_f32 v[32:33], v[152:153], v[80:81], v[32:33] op_sel_hi:[0,1,1]
	s_waitcnt lgkmcnt(13)
	v_pk_fma_f32 v[30:31], v[152:153], v[82:83], v[30:31] op_sel_hi:[0,1,1]
	s_waitcnt lgkmcnt(12)
	v_pk_fma_f32 v[28:29], v[152:153], v[84:85], v[28:29] op_sel_hi:[0,1,1]
	s_waitcnt lgkmcnt(11)
	v_pk_fma_f32 v[26:27], v[152:153], v[86:87], v[26:27] op_sel_hi:[0,1,1]
	s_waitcnt lgkmcnt(10)
	v_pk_fma_f32 v[24:25], v[152:153], v[88:89], v[24:25] op_sel_hi:[0,1,1]
	s_waitcnt lgkmcnt(9)
	v_pk_fma_f32 v[22:23], v[152:153], v[90:91], v[22:23] op_sel_hi:[0,1,1]
	s_waitcnt lgkmcnt(8)
	v_pk_fma_f32 v[20:21], v[152:153], v[92:93], v[20:21] op_sel_hi:[0,1,1]
	s_waitcnt lgkmcnt(7)
	v_pk_fma_f32 v[18:19], v[152:153], v[94:95], v[18:19] op_sel_hi:[0,1,1]
	s_waitcnt lgkmcnt(6)
	v_pk_fma_f32 v[16:17], v[152:153], v[96:97], v[16:17] op_sel_hi:[0,1,1]
	s_waitcnt lgkmcnt(5)
	v_pk_fma_f32 v[14:15], v[152:153], v[98:99], v[14:15] op_sel_hi:[0,1,1]
	s_waitcnt lgkmcnt(4)
	v_pk_fma_f32 v[12:13], v[152:153], v[100:101], v[12:13] op_sel_hi:[0,1,1]
	s_waitcnt lgkmcnt(3)
	v_pk_fma_f32 v[10:11], v[152:153], v[102:103], v[10:11] op_sel_hi:[0,1,1]
	s_waitcnt lgkmcnt(2)
	v_pk_fma_f32 v[8:9], v[152:153], v[104:105], v[8:9] op_sel_hi:[0,1,1]
	s_waitcnt lgkmcnt(1)
	v_pk_fma_f32 v[6:7], v[152:153], v[106:107], v[6:7] op_sel_hi:[0,1,1]
	s_waitcnt lgkmcnt(0)
	v_pk_fma_f32 v[4:5], v[152:153], v[108:109], v[4:5] op_sel_hi:[0,1,1]
	s_cbranch_scc1 .Lmk_a_s0
	global_load_dword v152, v[38:39], off
	v_lshl_add_u64 v[38:39], v[38:39], 0, s[26:27]
; __device__ void mod_item(const Params& p, int item, float* lds, int wave) {
;     ...
;         for (int kk = kg * 64; kk < kg * 64 + 64; ++kk) {
;             const float w = p.ada_w[(size_t)(half * 512 + kk) * MODW + col0 + col];
; #pragma unroll
;             for (int b = 0; b < NB; ++b) acc[b] += lds[kk * 36 + b] * w;
.Lmk_a_s0:
	ds_read_b96 v[74:76], v37
	ds_read2_b32 v[80:81], v37 offset0:3 offset1:4
	ds_read2_b32 v[82:83], v37 offset0:5 offset1:6
	ds_read2_b32 v[84:85], v37 offset0:7 offset1:8
	ds_read2_b32 v[86:87], v37 offset0:9 offset1:10
	ds_read2_b32 v[88:89], v37 offset0:11 offset1:12
	ds_read2_b32 v[90:91], v37 offset0:13 offset1:14
	ds_read2_b32 v[92:93], v37 offset0:15 offset1:16
	ds_read2_b32 v[94:95], v37 offset0:17 offset1:18
	ds_read2_b32 v[96:97], v37 offset0:19 offset1:20
	ds_read2_b32 v[98:99], v37 offset0:21 offset1:22
	ds_read2_b32 v[100:101], v37 offset0:23 offset1:24
	ds_read2_b32 v[102:103], v37 offset0:25 offset1:26
	ds_read2_b32 v[104:105], v37 offset0:27 offset1:28
	ds_read2_b32 v[106:107], v37 offset0:29 offset1:30
	ds_read2_b32 v[108:109], v37 offset0:31 offset1:32
	s_waitcnt lgkmcnt(14)
	v_mov_b32_e32 v110, v75
	v_mov_b32_e32 v111, v76
	v_add_u32_e32 v37, 0x90, v37
	s_waitcnt vmcnt(15)
	v_fmac_f32_e32 v69, v154, v74
	v_pk_fma_f32 v[34:35], v[154:155], v[110:111], v[34:35] op_sel_hi:[0,1,1]
	v_pk_fma_f32 v[32:33], v[154:155], v[80:81], v[32:33] op_sel_hi:[0,1,1]
	s_waitcnt lgkmcnt(13)
	v_pk_fma_f32 v[30:31], v[154:155], v[82:83], v[30:31] op_sel_hi:[0,1,1]
	s_waitcnt lgkmcnt(12)
	v_pk_fma_f32 v[28:29], v[154:155], v[84:85], v[28:29] op_sel_hi:[0,1,1]
	s_waitcnt lgkmcnt(11)
	v_pk_fma_f32 v[26:27], v[154:155], v[86:87], v[26:27] op_sel_hi:[0,1,1]
	s_waitcnt lgkmcnt(10)
	v_pk_fma_f32 v[24:25], v[154:155], v[88:89], v[24:25] op_sel_hi:[0,1,1]
	s_waitcnt lgkmcnt(9)
	v_pk_fma_f32 v[22:23], v[154:155], v[90:91], v[22:23] op_sel_hi:[0,1,1]
	s_waitcnt lgkmcnt(8)
	v_pk_fma_f32 v[20:21], v[154:155], v[92:93], v[20:21] op_sel_hi:[0,1,1]
	s_waitcnt lgkmcnt(7)
	v_pk_fma_f32 v[18:19], v[154:155], v[94:95], v[18:19] op_sel_hi:[0,1,1]
	s_waitcnt lgkmcnt(6)
	v_pk_fma_f32 v[16:17], v[154:155], v[96:97], v[16:17] op_sel_hi:[0,1,1]
	s_waitcnt lgkmcnt(5)
	v_pk_fma_f32 v[14:15], v[154:155], v[98:99], v[14:15] op_sel_hi:[0,1,1]
	s_waitcnt lgkmcnt(4)
	v_pk_fma_f32 v[12:13], v[154:155], v[100:101], v[12:13] op_sel_hi:[0,1,1]
	s_waitcnt lgkmcnt(3)
	v_pk_fma_f32 v[10:11], v[154:155], v[102:103], v[10:11] op_sel_hi:[0,1,1]
	s_waitcnt lgkmcnt(2)
	v_pk_fma_f32 v[8:9], v[154:155], v[104:105], v[8:9] op_sel_hi:[0,1,1]
	s_waitcnt lgkmcnt(1)
	v_pk_fma_f32 v[6:7], v[154:155], v[106:107], v[6:7] op_sel_hi:[0,1,1]
	s_waitcnt lgkmcnt(0)
	v_pk_fma_f32 v[4:5], v[154:155], v[108:109], v[4:5] op_sel_hi:[0,1,1]
	s_cbranch_scc1 .Lmk_a_s1
	global_load_dword v154, v[38:39], off
	v_lshl_add_u64 v[38:39], v[38:39], 0, s[26:27]
.Lmk_a_s1:
	ds_read_b96 v[74:76], v37
	ds_read2_b32 v[80:81], v37 offset0:3 offset1:4
	ds_read2_b32 v[82:83], v37 offset0:5 offset1:6
	ds_read2_b32 v[84:85], v37 offset0:7 offset1:8
	ds_read2_b32 v[86:87], v37 offset0:9 offset1:10
	ds_read2_b32 v[88:89], v37 offset0:11 offset1:12
	ds_read2_b32 v[90:91], v37 offset0:13 offset1:14
	ds_read2_b32 v[92:93], v37 offset0:15 offset1:16
	ds_read2_b32 v[94:95], v37 offset0:17 offset1:18
	ds_read2_b32 v[96:97], v37 offset0:19 offset1:20
	ds_read2_b32 v[98:99], v37 offset0:21 offset1:22
	ds_read2_b32 v[100:101], v37 offset0:23 offset1:24
	ds_read2_b32 v[102:103], v37 offset0:25 offset1:26
	ds_read2_b32 v[104:105], v37 offset0:27 offset1:28
	ds_read2_b32 v[106:107], v37 offset0:29 offset1:30
	ds_read2_b32 v[108:109], v37 offset0:31 offset1:32
	s_waitcnt lgkmcnt(14)
	v_mov_b32_e32 v110, v75
	v_mov_b32_e32 v111, v76
	v_add_u32_e32 v37, 0x90, v37
	s_waitcnt vmcnt(15)
	v_fmac_f32_e32 v69, v156, v74
	v_pk_fma_f32 v[34:35], v[156:157], v[110:111], v[34:35] op_sel_hi:[0,1,1]
	v_pk_fma_f32 v[32:33], v[156:157], v[80:81], v[32:33] op_sel_hi:[0,1,1]
	s_waitcnt lgkmcnt(13)
	v_pk_fma_f32 v[30:31], v[156:157], v[82:83], v[30:31] op_sel_hi:[0,1,1]
	s_waitcnt lgkmcnt(12)
	v_pk_fma_f32 v[28:29], v[156:157], v[84:85], v[28:29] op_sel_hi:[0,1,1]
	s_waitcnt lgkmcnt(11)
	v_pk_fma_f32 v[26:27], v[156:157], v[86:87], v[26:27] op_sel_hi:[0,1,1]
	s_waitcnt lgkmcnt(10)
	v_pk_fma_f32 v[24:25], v[156:157], v[88:89], v[24:25] op_sel_hi:[0,1,1]
	s_waitcnt lgkmcnt(9)
	v_pk_fma_f32 v[22:23], v[156:157], v[90:91], v[22:23] op_sel_hi:[0,1,1]
	s_waitcnt lgkmcnt(8)
	v_pk_fma_f32 v[20:21], v[156:157], v[92:93], v[20:21] op_sel_hi:[0,1,1]
	s_waitcnt lgkmcnt(7)
	v_pk_fma_f32 v[18:19], v[156:157], v[94:95], v[18:19] op_sel_hi:[0,1,1]
	s_waitcnt lgkmcnt(6)
	v_pk_fma_f32 v[16:17], v[156:157], v[96:97], v[16:17] op_sel_hi:[0,1,1]
	s_waitcnt lgkmcnt(5)
	v_pk_fma_f32 v[14:15], v[156:157], v[98:99], v[14:15] op_sel_hi:[0,1,1]
	s_waitcnt lgkmcnt(4)
	v_pk_fma_f32 v[12:13], v[156:157], v[100:101], v[12:13] op_sel_hi:[0,1,1]
	s_waitcnt lgkmcnt(3)
	v_pk_fma_f32 v[10:11], v[156:157], v[102:103], v[10:11] op_sel_hi:[0,1,1]
	s_waitcnt lgkmcnt(2)
	v_pk_fma_f32 v[8:9], v[156:157], v[104:105], v[8:9] op_sel_hi:[0,1,1]
	s_waitcnt lgkmcnt(1)
	v_pk_fma_f32 v[6:7], v[156:157], v[106:107], v[6:7] op_sel_hi:[0,1,1]
	s_waitcnt lgkmcnt(0)
	v_pk_fma_f32 v[4:5], v[156:157], v[108:109], v[4:5] op_sel_hi:[0,1,1]
	s_cbranch_scc1 .Lmk_a_s2
	global_load_dword v156, v[38:39], off
	v_lshl_add_u64 v[38:39], v[38:39], 0, s[26:27]
; __device__ void mod_item(const Params& p, int item, float* lds, int wave) {
;     ...
;         for (int kk = kg * 64; kk < kg * 64 + 64; ++kk) {
;             const float w = p.ada_w[(size_t)(half * 512 + kk) * MODW + col0 + col];
; #pragma unroll
;             for (int b = 0; b < NB; ++b) acc[b] += lds[kk * 36 + b] * w;
.Lmk_a_s2:
	ds_read_b96 v[74:76], v37
	ds_read2_b32 v[80:81], v37 offset0:3 offset1:4
	ds_read2_b32 v[82:83], v37 offset0:5 offset1:6
	ds_read2_b32 v[84:85], v37 offset0:7 offset1:8
	ds_read2_b32 v[86:87], v37 offset0:9 offset1:10
	ds_read2_b32 v[88:89], v37 offset0:11 offset1:12
	ds_read2_b32 v[90:91], v37 offset0:13 offset1:14
	ds_read2_b32 v[92:93], v37 offset0:15 offset1:16
	ds_read2_b32 v[94:95], v37 offset0:17 offset1:18
	ds_read2_b32 v[96:97], v37 offset0:19 offset1:20
	ds_read2_b32 v[98:99], v37 offset0:21 offset1:22
	ds_read2_b32 v[100:101], v37 offset0:23 offset1:24
	ds_read2_b32 v[102:103], v37 offset0:25 offset1:26
	ds_read2_b32 v[104:105], v37 offset0:27 offset1:28
	ds_read2_b32 v[106:107], v37 offset0:29 offset1:30
	ds_read2_b32 v[108:109], v37 offset0:31 offset1:32
	s_waitcnt lgkmcnt(14)
	v_mov_b32_e32 v110, v75
	v_mov_b32_e32 v111, v76
	v_add_u32_e32 v37, 0x90, v37
	s_waitcnt vmcnt(15)
	v_fmac_f32_e32 v69, v158, v74
	v_pk_fma_f32 v[34:35], v[158:159], v[110:111], v[34:35] op_sel_hi:[0,1,1]
	v_pk_fma_f32 v[32:33], v[158:159], v[80:81], v[32:33] op_sel_hi:[0,1,1]
	s_waitcnt lgkmcnt(13)
	v_pk_fma_f32 v[30:31], v[158:159], v[82:83], v[30:31] op_sel_hi:[0,1,1]
	s_waitcnt lgkmcnt(12)
	v_pk_fma_f32 v[28:29], v[158:159], v[84:85], v[28:29] op_sel_hi:[0,1,1]
	s_waitcnt lgkmcnt(11)
	v_pk_fma_f32 v[26:27], v[158:159], v[86:87], v[26:27] op_sel_hi:[0,1,1]
	s_waitcnt lgkmcnt(10)
	v_pk_fma_f32 v[24:25], v[158:159], v[88:89], v[24:25] op_sel_hi:[0,1,1]
	s_waitcnt lgkmcnt(9)
	v_pk_fma_f32 v[22:23], v[158:159], v[90:91], v[22:23] op_sel_hi:[0,1,1]
	s_waitcnt lgkmcnt(8)
	v_pk_fma_f32 v[20:21], v[158:159], v[92:93], v[20:21] op_sel_hi:[0,1,1]
	s_waitcnt lgkmcnt(7)
	v_pk_fma_f32 v[18:19], v[158:159], v[94:95], v[18:19] op_sel_hi:[0,1,1]
	s_waitcnt lgkmcnt(6)
	v_pk_fma_f32 v[16:17], v[158:159], v[96:97], v[16:17] op_sel_hi:[0,1,1]
	s_waitcnt lgkmcnt(5)
	v_pk_fma_f32 v[14:15], v[158:159], v[98:99], v[14:15] op_sel_hi:[0,1,1]
	s_waitcnt lgkmcnt(4)
	v_pk_fma_f32 v[12:13], v[158:159], v[100:101], v[12:13] op_sel_hi:[0,1,1]
	s_waitcnt lgkmcnt(3)
	v_pk_fma_f32 v[10:11], v[158:159], v[102:103], v[10:11] op_sel_hi:[0,1,1]
	s_waitcnt lgkmcnt(2)
	v_pk_fma_f32 v[8:9], v[158:159], v[104:105], v[8:9] op_sel_hi:[0,1,1]
	s_waitcnt lgkmcnt(1)
	v_pk_fma_f32 v[6:7], v[158:159], v[106:107], v[6:7] op_sel_hi:[0,1,1]
	s_waitcnt lgkmcnt(0)
	v_pk_fma_f32 v[4:5], v[158:159], v[108:109], v[4:5] op_sel_hi:[0,1,1]
	s_cbranch_scc1 .Lmk_a_s3
	global_load_dword v158, v[38:39], off
	v_lshl_add_u64 v[38:39], v[38:39], 0, s[26:27]
.Lmk_a_s3:
	ds_read_b96 v[74:76], v37
	ds_read2_b32 v[80:81], v37 offset0:3 offset1:4
	ds_read2_b32 v[82:83], v37 offset0:5 offset1:6
	ds_read2_b32 v[84:85], v37 offset0:7 offset1:8
	ds_read2_b32 v[86:87], v37 offset0:9 offset1:10
	ds_read2_b32 v[88:89], v37 offset0:11 offset1:12
	ds_read2_b32 v[90:91], v37 offset0:13 offset1:14
	ds_read2_b32 v[92:93], v37 offset0:15 offset1:16
	ds_read2_b32 v[94:95], v37 offset0:17 offset1:18
	ds_read2_b32 v[96:97], v37 offset0:19 offset1:20
	ds_read2_b32 v[98:99], v37 offset0:21 offset1:22
	ds_read2_b32 v[100:101], v37 offset0:23 offset1:24
	ds_read2_b32 v[102:103], v37 offset0:25 offset1:26
	ds_read2_b32 v[104:105], v37 offset0:27 offset1:28
	ds_read2_b32 v[106:107], v37 offset0:29 offset1:30
	ds_read2_b32 v[108:109], v37 offset0:31 offset1:32
	s_waitcnt lgkmcnt(14)
	v_mov_b32_e32 v110, v75
	v_mov_b32_e32 v111, v76
	v_add_u32_e32 v37, 0x90, v37
	s_waitcnt vmcnt(15)
	v_fmac_f32_e32 v69, v160, v74
	v_pk_fma_f32 v[34:35], v[160:161], v[110:111], v[34:35] op_sel_hi:[0,1,1]
	v_pk_fma_f32 v[32:33], v[160:161], v[80:81], v[32:33] op_sel_hi:[0,1,1]
	s_waitcnt lgkmcnt(13)
	v_pk_fma_f32 v[30:31], v[160:161], v[82:83], v[30:31] op_sel_hi:[0,1,1]
	s_waitcnt lgkmcnt(12)
	v_pk_fma_f32 v[28:29], v[160:161], v[84:85], v[28:29] op_sel_hi:[0,1,1]
	s_waitcnt lgkmcnt(11)
	v_pk_fma_f32 v[26:27], v[160:161], v[86:87], v[26:27] op_sel_hi:[0,1,1]
	s_waitcnt lgkmcnt(10)
	v_pk_fma_f32 v[24:25], v[160:161], v[88:89], v[24:25] op_sel_hi:[0,1,1]
	s_waitcnt lgkmcnt(9)
	v_pk_fma_f32 v[22:23], v[160:161], v[90:91], v[22:23] op_sel_hi:[0,1,1]
	s_waitcnt lgkmcnt(8)
	v_pk_fma_f32 v[20:21], v[160:161], v[92:93], v[20:21] op_sel_hi:[0,1,1]
	s_waitcnt lgkmcnt(7)
	v_pk_fma_f32 v[18:19], v[160:161], v[94:95], v[18:19] op_sel_hi:[0,1,1]
	s_waitcnt lgkmcnt(6)
	v_pk_fma_f32 v[16:17], v[160:161], v[96:97], v[16:17] op_sel_hi:[0,1,1]
	s_waitcnt lgkmcnt(5)
	v_pk_fma_f32 v[14:15], v[160:161], v[98:99], v[14:15] op_sel_hi:[0,1,1]
	s_waitcnt lgkmcnt(4)
	v_pk_fma_f32 v[12:13], v[160:161], v[100:101], v[12:13] op_sel_hi:[0,1,1]
	s_waitcnt lgkmcnt(3)
	v_pk_fma_f32 v[10:11], v[160:161], v[102:103], v[10:11] op_sel_hi:[0,1,1]
	s_waitcnt lgkmcnt(2)
	v_pk_fma_f32 v[8:9], v[160:161], v[104:105], v[8:9] op_sel_hi:[0,1,1]
	s_waitcnt lgkmcnt(1)
	v_pk_fma_f32 v[6:7], v[160:161], v[106:107], v[6:7] op_sel_hi:[0,1,1]
	s_waitcnt lgkmcnt(0)
	v_pk_fma_f32 v[4:5], v[160:161], v[108:109], v[4:5] op_sel_hi:[0,1,1]
	s_cbranch_scc1 .Lmk_a_s4
	global_load_dword v160, v[38:39], off
	v_lshl_add_u64 v[38:39], v[38:39], 0, s[26:27]
; __device__ void mod_item(const Params& p, int item, float* lds, int wave) {
;     ...
;         for (int kk = kg * 64; kk < kg * 64 + 64; ++kk) {
;             const float w = p.ada_w[(size_t)(half * 512 + kk) * MODW + col0 + col];
; #pragma unroll
;             for (int b = 0; b < NB; ++b) acc[b] += lds[kk * 36 + b] * w;
.Lmk_a_s4:
	ds_read_b96 v[74:76], v37
	ds_read2_b32 v[80:81], v37 offset0:3 offset1:4
	ds_read2_b32 v[82:83], v37 offset0:5 offset1:6
	ds_read2_b32 v[84:85], v37 offset0:7 offset1:8
	ds_read2_b32 v[86:87], v37 offset0:9 offset1:10
	ds_read2_b32 v[88:89], v37 offset0:11 offset1:12
	ds_read2_b32 v[90:91], v37 offset0:13 offset1:14
	ds_read2_b32 v[92:93], v37 offset0:15 offset1:16
	ds_read2_b32 v[94:95], v37 offset0:17 offset1:18
	ds_read2_b32 v[96:97], v37 offset0:19 offset1:20
	ds_read2_b32 v[98:99], v37 offset0:21 offset1:22
	ds_read2_b32 v[100:101], v37 offset0:23 offset1:24
	ds_read2_b32 v[102:103], v37 offset0:25 offset1:26
	ds_read2_b32 v[104:105], v37 offset0:27 offset1:28
	ds_read2_b32 v[106:107], v37 offset0:29 offset1:30
	ds_read2_b32 v[108:109], v37 offset0:31 offset1:32
	s_waitcnt lgkmcnt(14)
	v_mov_b32_e32 v110, v75
	v_mov_b32_e32 v111, v76
	v_add_u32_e32 v37, 0x90, v37
	s_waitcnt vmcnt(15)
	v_fmac_f32_e32 v69, v162, v74
	v_pk_fma_f32 v[34:35], v[162:163], v[110:111], v[34:35] op_sel_hi:[0,1,1]
	v_pk_fma_f32 v[32:33], v[162:163], v[80:81], v[32:33] op_sel_hi:[0,1,1]
	s_waitcnt lgkmcnt(13)
	v_pk_fma_f32 v[30:31], v[162:163], v[82:83], v[30:31] op_sel_hi:[0,1,1]
	s_waitcnt lgkmcnt(12)
	v_pk_fma_f32 v[28:29], v[162:163], v[84:85], v[28:29] op_sel_hi:[0,1,1]
	s_waitcnt lgkmcnt(11)
	v_pk_fma_f32 v[26:27], v[162:163], v[86:87], v[26:27] op_sel_hi:[0,1,1]
	s_waitcnt lgkmcnt(10)
	v_pk_fma_f32 v[24:25], v[162:163], v[88:89], v[24:25] op_sel_hi:[0,1,1]
	s_waitcnt lgkmcnt(9)
	v_pk_fma_f32 v[22:23], v[162:163], v[90:91], v[22:23] op_sel_hi:[0,1,1]
	s_waitcnt lgkmcnt(8)
	v_pk_fma_f32 v[20:21], v[162:163], v[92:93], v[20:21] op_sel_hi:[0,1,1]
	s_waitcnt lgkmcnt(7)
	v_pk_fma_f32 v[18:19], v[162:163], v[94:95], v[18:19] op_sel_hi:[0,1,1]
	s_waitcnt lgkmcnt(6)
	v_pk_fma_f32 v[16:17], v[162:163], v[96:97], v[16:17] op_sel_hi:[0,1,1]
	s_waitcnt lgkmcnt(5)
	v_pk_fma_f32 v[14:15], v[162:163], v[98:99], v[14:15] op_sel_hi:[0,1,1]
	s_waitcnt lgkmcnt(4)
	v_pk_fma_f32 v[12:13], v[162:163], v[100:101], v[12:13] op_sel_hi:[0,1,1]
	s_waitcnt lgkmcnt(3)
	v_pk_fma_f32 v[10:11], v[162:163], v[102:103], v[10:11] op_sel_hi:[0,1,1]
	s_waitcnt lgkmcnt(2)
	v_pk_fma_f32 v[8:9], v[162:163], v[104:105], v[8:9] op_sel_hi:[0,1,1]
	s_waitcnt lgkmcnt(1)
	v_pk_fma_f32 v[6:7], v[162:163], v[106:107], v[6:7] op_sel_hi:[0,1,1]
	s_waitcnt lgkmcnt(0)
	v_pk_fma_f32 v[4:5], v[162:163], v[108:109], v[4:5] op_sel_hi:[0,1,1]
	s_cbranch_scc1 .Lmk_a_s5
	global_load_dword v162, v[38:39], off
	v_lshl_add_u64 v[38:39], v[38:39], 0, s[26:27]
.Lmk_a_s5:
	ds_read_b96 v[74:76], v37
	ds_read2_b32 v[80:81], v37 offset0:3 offset1:4
	ds_read2_b32 v[82:83], v37 offset0:5 offset1:6
	ds_read2_b32 v[84:85], v37 offset0:7 offset1:8
	ds_read2_b32 v[86:87], v37 offset0:9 offset1:10
	ds_read2_b32 v[88:89], v37 offset0:11 offset1:12
	ds_read2_b32 v[90:91], v37 offset0:13 offset1:14
	ds_read2_b32 v[92:93], v37 offset0:15 offset1:16
	ds_read2_b32 v[94:95], v37 offset0:17 offset1:18
	ds_read2_b32 v[96:97], v37 offset0:19 offset1:20
	ds_read2_b32 v[98:99], v37 offset0:21 offset1:22
	ds_read2_b32 v[100:101], v37 offset0:23 offset1:24
	ds_read2_b32 v[102:103], v37 offset0:25 offset1:26
	ds_read2_b32 v[104:105], v37 offset0:27 offset1:28
	ds_read2_b32 v[106:107], v37 offset0:29 offset1:30
	ds_read2_b32 v[108:109], v37 offset0:31 offset1:32
	s_waitcnt lgkmcnt(14)
	v_mov_b32_e32 v110, v75
	v_mov_b32_e32 v111, v76
	v_add_u32_e32 v37, 0x90, v37
	s_waitcnt vmcnt(15)
	v_fmac_f32_e32 v69, v164, v74
	v_pk_fma_f32 v[34:35], v[164:165], v[110:111], v[34:35] op_sel_hi:[0,1,1]
	v_pk_fma_f32 v[32:33], v[164:165], v[80:81], v[32:33] op_sel_hi:[0,1,1]
	s_waitcnt lgkmcnt(13)
	v_pk_fma_f32 v[30:31], v[164:165], v[82:83], v[30:31] op_sel_hi:[0,1,1]
	s_waitcnt lgkmcnt(12)
	v_pk_fma_f32 v[28:29], v[164:165], v[84:85], v[28:29] op_sel_hi:[0,1,1]
	s_waitcnt lgkmcnt(11)
	v_pk_fma_f32 v[26:27], v[164:165], v[86:87], v[26:27] op_sel_hi:[0,1,1]
	s_waitcnt lgkmcnt(10)
	v_pk_fma_f32 v[24:25], v[164:165], v[88:89], v[24:25] op_sel_hi:[0,1,1]
	s_waitcnt lgkmcnt(9)
	v_pk_fma_f32 v[22:23], v[164:165], v[90:91], v[22:23] op_sel_hi:[0,1,1]
	s_waitcnt lgkmcnt(8)
	v_pk_fma_f32 v[20:21], v[164:165], v[92:93], v[20:21] op_sel_hi:[0,1,1]
	s_waitcnt lgkmcnt(7)
	v_pk_fma_f32 v[18:19], v[164:165], v[94:95], v[18:19] op_sel_hi:[0,1,1]
	s_waitcnt lgkmcnt(6)
	v_pk_fma_f32 v[16:17], v[164:165], v[96:97], v[16:17] op_sel_hi:[0,1,1]
	s_waitcnt lgkmcnt(5)
	v_pk_fma_f32 v[14:15], v[164:165], v[98:99], v[14:15] op_sel_hi:[0,1,1]
	s_waitcnt lgkmcnt(4)
	v_pk_fma_f32 v[12:13], v[164:165], v[100:101], v[12:13] op_sel_hi:[0,1,1]
	s_waitcnt lgkmcnt(3)
	v_pk_fma_f32 v[10:11], v[164:165], v[102:103], v[10:11] op_sel_hi:[0,1,1]
	s_waitcnt lgkmcnt(2)
	v_pk_fma_f32 v[8:9], v[164:165], v[104:105], v[8:9] op_sel_hi:[0,1,1]
	s_waitcnt lgkmcnt(1)
	v_pk_fma_f32 v[6:7], v[164:165], v[106:107], v[6:7] op_sel_hi:[0,1,1]
	s_waitcnt lgkmcnt(0)
	v_pk_fma_f32 v[4:5], v[164:165], v[108:109], v[4:5] op_sel_hi:[0,1,1]
	s_cbranch_scc1 .Lmk_a_s6
	global_load_dword v164, v[38:39], off
	v_lshl_add_u64 v[38:39], v[38:39], 0, s[26:27]
; __device__ void mod_item(const Params& p, int item, float* lds, int wave) {
;     ...
;         for (int kk = kg * 64; kk < kg * 64 + 64; ++kk) {
;             const float w = p.ada_w[(size_t)(half * 512 + kk) * MODW + col0 + col];
; #pragma unroll
;             for (int b = 0; b < NB; ++b) acc[b] += lds[kk * 36 + b] * w;
.Lmk_a_s6:
	ds_read_b96 v[74:76], v37
	ds_read2_b32 v[80:81], v37 offset0:3 offset1:4
	ds_read2_b32 v[82:83], v37 offset0:5 offset1:6
	ds_read2_b32 v[84:85], v37 offset0:7 offset1:8
	ds_read2_b32 v[86:87], v37 offset0:9 offset1:10
	ds_read2_b32 v[88:89], v37 offset0:11 offset1:12
	ds_read2_b32 v[90:91], v37 offset0:13 offset1:14
	ds_read2_b32 v[92:93], v37 offset0:15 offset1:16
	ds_read2_b32 v[94:95], v37 offset0:17 offset1:18
	ds_read2_b32 v[96:97], v37 offset0:19 offset1:20
	ds_read2_b32 v[98:99], v37 offset0:21 offset1:22
	ds_read2_b32 v[100:101], v37 offset0:23 offset1:24
	ds_read2_b32 v[102:103], v37 offset0:25 offset1:26
	ds_read2_b32 v[104:105], v37 offset0:27 offset1:28
	ds_read2_b32 v[106:107], v37 offset0:29 offset1:30
	ds_read2_b32 v[108:109], v37 offset0:31 offset1:32
	s_waitcnt lgkmcnt(14)
	v_mov_b32_e32 v110, v75
	v_mov_b32_e32 v111, v76
	v_add_u32_e32 v37, 0x90, v37
	s_waitcnt vmcnt(15)
	v_fmac_f32_e32 v69, v166, v74
	v_pk_fma_f32 v[34:35], v[166:167], v[110:111], v[34:35] op_sel_hi:[0,1,1]
	v_pk_fma_f32 v[32:33], v[166:167], v[80:81], v[32:33] op_sel_hi:[0,1,1]
	s_waitcnt lgkmcnt(13)
	v_pk_fma_f32 v[30:31], v[166:167], v[82:83], v[30:31] op_sel_hi:[0,1,1]
	s_waitcnt lgkmcnt(12)
	v_pk_fma_f32 v[28:29], v[166:167], v[84:85], v[28:29] op_sel_hi:[0,1,1]
	s_waitcnt lgkmcnt(11)
	v_pk_fma_f32 v[26:27], v[166:167], v[86:87], v[26:27] op_sel_hi:[0,1,1]
	s_waitcnt lgkmcnt(10)
	v_pk_fma_f32 v[24:25], v[166:167], v[88:89], v[24:25] op_sel_hi:[0,1,1]
	s_waitcnt lgkmcnt(9)
	v_pk_fma_f32 v[22:23], v[166:167], v[90:91], v[22:23] op_sel_hi:[0,1,1]
	s_waitcnt lgkmcnt(8)
	v_pk_fma_f32 v[20:21], v[166:167], v[92:93], v[20:21] op_sel_hi:[0,1,1]
	s_waitcnt lgkmcnt(7)
	v_pk_fma_f32 v[18:19], v[166:167], v[94:95], v[18:19] op_sel_hi:[0,1,1]
	s_waitcnt lgkmcnt(6)
	v_pk_fma_f32 v[16:17], v[166:167], v[96:97], v[16:17] op_sel_hi:[0,1,1]
	s_waitcnt lgkmcnt(5)
	v_pk_fma_f32 v[14:15], v[166:167], v[98:99], v[14:15] op_sel_hi:[0,1,1]
	s_waitcnt lgkmcnt(4)
	v_pk_fma_f32 v[12:13], v[166:167], v[100:101], v[12:13] op_sel_hi:[0,1,1]
	s_waitcnt lgkmcnt(3)
	v_pk_fma_f32 v[10:11], v[166:167], v[102:103], v[10:11] op_sel_hi:[0,1,1]
	s_waitcnt lgkmcnt(2)
	v_pk_fma_f32 v[8:9], v[166:167], v[104:105], v[8:9] op_sel_hi:[0,1,1]
	s_waitcnt lgkmcnt(1)
	v_pk_fma_f32 v[6:7], v[166:167], v[106:107], v[6:7] op_sel_hi:[0,1,1]
	s_waitcnt lgkmcnt(0)
	v_pk_fma_f32 v[4:5], v[166:167], v[108:109], v[4:5] op_sel_hi:[0,1,1]
	s_cbranch_scc1 .Lmk_a_s7
	global_load_dword v166, v[38:39], off
	v_lshl_add_u64 v[38:39], v[38:39], 0, s[26:27]
.Lmk_a_s7:
	ds_read_b96 v[74:76], v37
	ds_read2_b32 v[80:81], v37 offset0:3 offset1:4
	ds_read2_b32 v[82:83], v37 offset0:5 offset1:6
	ds_read2_b32 v[84:85], v37 offset0:7 offset1:8
	ds_read2_b32 v[86:87], v37 offset0:9 offset1:10
	ds_read2_b32 v[88:89], v37 offset0:11 offset1:12
	ds_read2_b32 v[90:91], v37 offset0:13 offset1:14
	ds_read2_b32 v[92:93], v37 offset0:15 offset1:16
	ds_read2_b32 v[94:95], v37 offset0:17 offset1:18
	ds_read2_b32 v[96:97], v37 offset0:19 offset1:20
	ds_read2_b32 v[98:99], v37 offset0:21 offset1:22
	ds_read2_b32 v[100:101], v37 offset0:23 offset1:24
	ds_read2_b32 v[102:103], v37 offset0:25 offset1:26
	ds_read2_b32 v[104:105], v37 offset0:27 offset1:28
	ds_read2_b32 v[106:107], v37 offset0:29 offset1:30
	ds_read2_b32 v[108:109], v37 offset0:31 offset1:32
	s_waitcnt lgkmcnt(14)
	v_mov_b32_e32 v110, v75
	v_mov_b32_e32 v111, v76
	v_add_u32_e32 v37, 0x90, v37
	s_waitcnt vmcnt(15)
	v_fmac_f32_e32 v69, v168, v74
	v_pk_fma_f32 v[34:35], v[168:169], v[110:111], v[34:35] op_sel_hi:[0,1,1]
	v_pk_fma_f32 v[32:33], v[168:169], v[80:81], v[32:33] op_sel_hi:[0,1,1]
	s_waitcnt lgkmcnt(13)
	v_pk_fma_f32 v[30:31], v[168:169], v[82:83], v[30:31] op_sel_hi:[0,1,1]
	s_waitcnt lgkmcnt(12)
	v_pk_fma_f32 v[28:29], v[168:169], v[84:85], v[28:29] op_sel_hi:[0,1,1]
	s_waitcnt lgkmcnt(11)
	v_pk_fma_f32 v[26:27], v[168:169], v[86:87], v[26:27] op_sel_hi:[0,1,1]
	s_waitcnt lgkmcnt(10)
	v_pk_fma_f32 v[24:25], v[168:169], v[88:89], v[24:25] op_sel_hi:[0,1,1]
	s_waitcnt lgkmcnt(9)
	v_pk_fma_f32 v[22:23], v[168:169], v[90:91], v[22:23] op_sel_hi:[0,1,1]
	s_waitcnt lgkmcnt(8)
	v_pk_fma_f32 v[20:21], v[168:169], v[92:93], v[20:21] op_sel_hi:[0,1,1]
	s_waitcnt lgkmcnt(7)
	v_pk_fma_f32 v[18:19], v[168:169], v[94:95], v[18:19] op_sel_hi:[0,1,1]
	s_waitcnt lgkmcnt(6)
	v_pk_fma_f32 v[16:17], v[168:169], v[96:97], v[16:17] op_sel_hi:[0,1,1]
	s_waitcnt lgkmcnt(5)
	v_pk_fma_f32 v[14:15], v[168:169], v[98:99], v[14:15] op_sel_hi:[0,1,1]
	s_waitcnt lgkmcnt(4)
	v_pk_fma_f32 v[12:13], v[168:169], v[100:101], v[12:13] op_sel_hi:[0,1,1]
	s_waitcnt lgkmcnt(3)
	v_pk_fma_f32 v[10:11], v[168:169], v[102:103], v[10:11] op_sel_hi:[0,1,1]
	s_waitcnt lgkmcnt(2)
	v_pk_fma_f32 v[8:9], v[168:169], v[104:105], v[8:9] op_sel_hi:[0,1,1]
	s_waitcnt lgkmcnt(1)
	v_pk_fma_f32 v[6:7], v[168:169], v[106:107], v[6:7] op_sel_hi:[0,1,1]
	s_waitcnt lgkmcnt(0)
	v_pk_fma_f32 v[4:5], v[168:169], v[108:109], v[4:5] op_sel_hi:[0,1,1]
	s_cbranch_scc1 .Lmk_a_s8
	global_load_dword v168, v[38:39], off
	v_lshl_add_u64 v[38:39], v[38:39], 0, s[26:27]
; __device__ void mod_item(const Params& p, int item, float* lds, int wave) {
;     ...
;         for (int kk = kg * 64; kk < kg * 64 + 64; ++kk) {
;             const float w = p.ada_w[(size_t)(half * 512 + kk) * MODW + col0 + col];
; #pragma unroll
;             for (int b = 0; b < NB; ++b) acc[b] += lds[kk * 36 + b] * w;
.Lmk_a_s8:
	ds_read_b96 v[74:76], v37
	ds_read2_b32 v[80:81], v37 offset0:3 offset1:4
	ds_read2_b32 v[82:83], v37 offset0:5 offset1:6
	ds_read2_b32 v[84:85], v37 offset0:7 offset1:8
	ds_read2_b32 v[86:87], v37 offset0:9 offset1:10
	ds_read2_b32 v[88:89], v37 offset0:11 offset1:12
	ds_read2_b32 v[90:91], v37 offset0:13 offset1:14
	ds_read2_b32 v[92:93], v37 offset0:15 offset1:16
	ds_read2_b32 v[94:95], v37 offset0:17 offset1:18
	ds_read2_b32 v[96:97], v37 offset0:19 offset1:20
	ds_read2_b32 v[98:99], v37 offset0:21 offset1:22
	ds_read2_b32 v[100:101], v37 offset0:23 offset1:24
	ds_read2_b32 v[102:103], v37 offset0:25 offset1:26
	ds_read2_b32 v[104:105], v37 offset0:27 offset1:28
	ds_read2_b32 v[106:107], v37 offset0:29 offset1:30
	ds_read2_b32 v[108:109], v37 offset0:31 offset1:32
	s_waitcnt lgkmcnt(14)
	v_mov_b32_e32 v110, v75
	v_mov_b32_e32 v111, v76
	v_add_u32_e32 v37, 0x90, v37
	s_waitcnt vmcnt(15)
	v_fmac_f32_e32 v69, v170, v74
	v_pk_fma_f32 v[34:35], v[170:171], v[110:111], v[34:35] op_sel_hi:[0,1,1]
	v_pk_fma_f32 v[32:33], v[170:171], v[80:81], v[32:33] op_sel_hi:[0,1,1]
	s_waitcnt lgkmcnt(13)
	v_pk_fma_f32 v[30:31], v[170:171], v[82:83], v[30:31] op_sel_hi:[0,1,1]
	s_waitcnt lgkmcnt(12)
	v_pk_fma_f32 v[28:29], v[170:171], v[84:85], v[28:29] op_sel_hi:[0,1,1]
	s_waitcnt lgkmcnt(11)
	v_pk_fma_f32 v[26:27], v[170:171], v[86:87], v[26:27] op_sel_hi:[0,1,1]
	s_waitcnt lgkmcnt(10)
	v_pk_fma_f32 v[24:25], v[170:171], v[88:89], v[24:25] op_sel_hi:[0,1,1]
	s_waitcnt lgkmcnt(9)
	v_pk_fma_f32 v[22:23], v[170:171], v[90:91], v[22:23] op_sel_hi:[0,1,1]
	s_waitcnt lgkmcnt(8)
	v_pk_fma_f32 v[20:21], v[170:171], v[92:93], v[20:21] op_sel_hi:[0,1,1]
	s_waitcnt lgkmcnt(7)
	v_pk_fma_f32 v[18:19], v[170:171], v[94:95], v[18:19] op_sel_hi:[0,1,1]
	s_waitcnt lgkmcnt(6)
	v_pk_fma_f32 v[16:17], v[170:171], v[96:97], v[16:17] op_sel_hi:[0,1,1]
	s_waitcnt lgkmcnt(5)
	v_pk_fma_f32 v[14:15], v[170:171], v[98:99], v[14:15] op_sel_hi:[0,1,1]
	s_waitcnt lgkmcnt(4)
	v_pk_fma_f32 v[12:13], v[170:171], v[100:101], v[12:13] op_sel_hi:[0,1,1]
	s_waitcnt lgkmcnt(3)
	v_pk_fma_f32 v[10:11], v[170:171], v[102:103], v[10:11] op_sel_hi:[0,1,1]
	s_waitcnt lgkmcnt(2)
	v_pk_fma_f32 v[8:9], v[170:171], v[104:105], v[8:9] op_sel_hi:[0,1,1]
	s_waitcnt lgkmcnt(1)
	v_pk_fma_f32 v[6:7], v[170:171], v[106:107], v[6:7] op_sel_hi:[0,1,1]
	s_waitcnt lgkmcnt(0)
	v_pk_fma_f32 v[4:5], v[170:171], v[108:109], v[4:5] op_sel_hi:[0,1,1]
	s_cbranch_scc1 .Lmk_a_s9
	global_load_dword v170, v[38:39], off
	v_lshl_add_u64 v[38:39], v[38:39], 0, s[26:27]
.Lmk_a_s9:
	ds_read_b96 v[74:76], v37
	ds_read2_b32 v[80:81], v37 offset0:3 offset1:4
	ds_read2_b32 v[82:83], v37 offset0:5 offset1:6
	ds_read2_b32 v[84:85], v37 offset0:7 offset1:8
	ds_read2_b32 v[86:87], v37 offset0:9 offset1:10
	ds_read2_b32 v[88:89], v37 offset0:11 offset1:12
	ds_read2_b32 v[90:91], v37 offset0:13 offset1:14
	ds_read2_b32 v[92:93], v37 offset0:15 offset1:16
	ds_read2_b32 v[94:95], v37 offset0:17 offset1:18
	ds_read2_b32 v[96:97], v37 offset0:19 offset1:20
	ds_read2_b32 v[98:99], v37 offset0:21 offset1:22
	ds_read2_b32 v[100:101], v37 offset0:23 offset1:24
	ds_read2_b32 v[102:103], v37 offset0:25 offset1:26
	ds_read2_b32 v[104:105], v37 offset0:27 offset1:28
	ds_read2_b32 v[106:107], v37 offset0:29 offset1:30
	ds_read2_b32 v[108:109], v37 offset0:31 offset1:32
	s_waitcnt lgkmcnt(14)
	v_mov_b32_e32 v110, v75
	v_mov_b32_e32 v111, v76
	v_add_u32_e32 v37, 0x90, v37
	s_waitcnt vmcnt(15)
	v_fmac_f32_e32 v69, v172, v74
	v_pk_fma_f32 v[34:35], v[172:173], v[110:111], v[34:35] op_sel_hi:[0,1,1]
	v_pk_fma_f32 v[32:33], v[172:173], v[80:81], v[32:33] op_sel_hi:[0,1,1]
	s_waitcnt lgkmcnt(13)
	v_pk_fma_f32 v[30:31], v[172:173], v[82:83], v[30:31] op_sel_hi:[0,1,1]
	s_waitcnt lgkmcnt(12)
	v_pk_fma_f32 v[28:29], v[172:173], v[84:85], v[28:29] op_sel_hi:[0,1,1]
	s_waitcnt lgkmcnt(11)
	v_pk_fma_f32 v[26:27], v[172:173], v[86:87], v[26:27] op_sel_hi:[0,1,1]
	s_waitcnt lgkmcnt(10)
	v_pk_fma_f32 v[24:25], v[172:173], v[88:89], v[24:25] op_sel_hi:[0,1,1]
	s_waitcnt lgkmcnt(9)
	v_pk_fma_f32 v[22:23], v[172:173], v[90:91], v[22:23] op_sel_hi:[0,1,1]
	s_waitcnt lgkmcnt(8)
	v_pk_fma_f32 v[20:21], v[172:173], v[92:93], v[20:21] op_sel_hi:[0,1,1]
	s_waitcnt lgkmcnt(7)
	v_pk_fma_f32 v[18:19], v[172:173], v[94:95], v[18:19] op_sel_hi:[0,1,1]
	s_waitcnt lgkmcnt(6)
	v_pk_fma_f32 v[16:17], v[172:173], v[96:97], v[16:17] op_sel_hi:[0,1,1]
	s_waitcnt lgkmcnt(5)
	v_pk_fma_f32 v[14:15], v[172:173], v[98:99], v[14:15] op_sel_hi:[0,1,1]
	s_waitcnt lgkmcnt(4)
	v_pk_fma_f32 v[12:13], v[172:173], v[100:101], v[12:13] op_sel_hi:[0,1,1]
	s_waitcnt lgkmcnt(3)
	v_pk_fma_f32 v[10:11], v[172:173], v[102:103], v[10:11] op_sel_hi:[0,1,1]
	s_waitcnt lgkmcnt(2)
	v_pk_fma_f32 v[8:9], v[172:173], v[104:105], v[8:9] op_sel_hi:[0,1,1]
	s_waitcnt lgkmcnt(1)
	v_pk_fma_f32 v[6:7], v[172:173], v[106:107], v[6:7] op_sel_hi:[0,1,1]
	s_waitcnt lgkmcnt(0)
	v_pk_fma_f32 v[4:5], v[172:173], v[108:109], v[4:5] op_sel_hi:[0,1,1]
	s_cbranch_scc1 .Lmk_a_s10
	global_load_dword v172, v[38:39], off
	v_lshl_add_u64 v[38:39], v[38:39], 0, s[26:27]
; __device__ void mod_item(const Params& p, int item, float* lds, int wave) {
;     ...
;         for (int kk = kg * 64; kk < kg * 64 + 64; ++kk) {
;             const float w = p.ada_w[(size_t)(half * 512 + kk) * MODW + col0 + col];
; #pragma unroll
;             for (int b = 0; b < NB; ++b) acc[b] += lds[kk * 36 + b] * w;
.Lmk_a_s10:
	ds_read_b96 v[74:76], v37
	ds_read2_b32 v[80:81], v37 offset0:3 offset1:4
	ds_read2_b32 v[82:83], v37 offset0:5 offset1:6
	ds_read2_b32 v[84:85], v37 offset0:7 offset1:8
	ds_read2_b32 v[86:87], v37 offset0:9 offset1:10
	ds_read2_b32 v[88:89], v37 offset0:11 offset1:12
	ds_read2_b32 v[90:91], v37 offset0:13 offset1:14
	ds_read2_b32 v[92:93], v37 offset0:15 offset1:16
	ds_read2_b32 v[94:95], v37 offset0:17 offset1:18
	ds_read2_b32 v[96:97], v37 offset0:19 offset1:20
	ds_read2_b32 v[98:99], v37 offset0:21 offset1:22
	ds_read2_b32 v[100:101], v37 offset0:23 offset1:24
	ds_read2_b32 v[102:103], v37 offset0:25 offset1:26
	ds_read2_b32 v[104:105], v37 offset0:27 offset1:28
	ds_read2_b32 v[106:107], v37 offset0:29 offset1:30
	ds_read2_b32 v[108:109], v37 offset0:31 offset1:32
	s_waitcnt lgkmcnt(14)
	v_mov_b32_e32 v110, v75
	v_mov_b32_e32 v111, v76
	v_add_u32_e32 v37, 0x90, v37
	s_waitcnt vmcnt(15)
	v_fmac_f32_e32 v69, v174, v74
	v_pk_fma_f32 v[34:35], v[174:175], v[110:111], v[34:35] op_sel_hi:[0,1,1]
	v_pk_fma_f32 v[32:33], v[174:175], v[80:81], v[32:33] op_sel_hi:[0,1,1]
	s_waitcnt lgkmcnt(13)
	v_pk_fma_f32 v[30:31], v[174:175], v[82:83], v[30:31] op_sel_hi:[0,1,1]
	s_waitcnt lgkmcnt(12)
	v_pk_fma_f32 v[28:29], v[174:175], v[84:85], v[28:29] op_sel_hi:[0,1,1]
	s_waitcnt lgkmcnt(11)
	v_pk_fma_f32 v[26:27], v[174:175], v[86:87], v[26:27] op_sel_hi:[0,1,1]
	s_waitcnt lgkmcnt(10)
	v_pk_fma_f32 v[24:25], v[174:175], v[88:89], v[24:25] op_sel_hi:[0,1,1]
	s_waitcnt lgkmcnt(9)
	v_pk_fma_f32 v[22:23], v[174:175], v[90:91], v[22:23] op_sel_hi:[0,1,1]
	s_waitcnt lgkmcnt(8)
	v_pk_fma_f32 v[20:21], v[174:175], v[92:93], v[20:21] op_sel_hi:[0,1,1]
	s_waitcnt lgkmcnt(7)
	v_pk_fma_f32 v[18:19], v[174:175], v[94:95], v[18:19] op_sel_hi:[0,1,1]
	s_waitcnt lgkmcnt(6)
	v_pk_fma_f32 v[16:17], v[174:175], v[96:97], v[16:17] op_sel_hi:[0,1,1]
	s_waitcnt lgkmcnt(5)
	v_pk_fma_f32 v[14:15], v[174:175], v[98:99], v[14:15] op_sel_hi:[0,1,1]
	s_waitcnt lgkmcnt(4)
	v_pk_fma_f32 v[12:13], v[174:175], v[100:101], v[12:13] op_sel_hi:[0,1,1]
	s_waitcnt lgkmcnt(3)
	v_pk_fma_f32 v[10:11], v[174:175], v[102:103], v[10:11] op_sel_hi:[0,1,1]
	s_waitcnt lgkmcnt(2)
	v_pk_fma_f32 v[8:9], v[174:175], v[104:105], v[8:9] op_sel_hi:[0,1,1]
	s_waitcnt lgkmcnt(1)
	v_pk_fma_f32 v[6:7], v[174:175], v[106:107], v[6:7] op_sel_hi:[0,1,1]
	s_waitcnt lgkmcnt(0)
	v_pk_fma_f32 v[4:5], v[174:175], v[108:109], v[4:5] op_sel_hi:[0,1,1]
	s_cbranch_scc1 .Lmk_a_s11
	global_load_dword v174, v[38:39], off
	v_lshl_add_u64 v[38:39], v[38:39], 0, s[26:27]
.Lmk_a_s11:
	ds_read_b96 v[74:76], v37
	ds_read2_b32 v[80:81], v37 offset0:3 offset1:4
	ds_read2_b32 v[82:83], v37 offset0:5 offset1:6
	ds_read2_b32 v[84:85], v37 offset0:7 offset1:8
	ds_read2_b32 v[86:87], v37 offset0:9 offset1:10
	ds_read2_b32 v[88:89], v37 offset0:11 offset1:12
	ds_read2_b32 v[90:91], v37 offset0:13 offset1:14
	ds_read2_b32 v[92:93], v37 offset0:15 offset1:16
	ds_read2_b32 v[94:95], v37 offset0:17 offset1:18
	ds_read2_b32 v[96:97], v37 offset0:19 offset1:20
	ds_read2_b32 v[98:99], v37 offset0:21 offset1:22
	ds_read2_b32 v[100:101], v37 offset0:23 offset1:24
	ds_read2_b32 v[102:103], v37 offset0:25 offset1:26
	ds_read2_b32 v[104:105], v37 offset0:27 offset1:28
	ds_read2_b32 v[106:107], v37 offset0:29 offset1:30
	ds_read2_b32 v[108:109], v37 offset0:31 offset1:32
	s_waitcnt lgkmcnt(14)
	v_mov_b32_e32 v110, v75
	v_mov_b32_e32 v111, v76
	v_add_u32_e32 v37, 0x90, v37
	s_waitcnt vmcnt(15)
	v_fmac_f32_e32 v69, v176, v74
	v_pk_fma_f32 v[34:35], v[176:177], v[110:111], v[34:35] op_sel_hi:[0,1,1]
	v_pk_fma_f32 v[32:33], v[176:177], v[80:81], v[32:33] op_sel_hi:[0,1,1]
	s_waitcnt lgkmcnt(13)
	v_pk_fma_f32 v[30:31], v[176:177], v[82:83], v[30:31] op_sel_hi:[0,1,1]
	s_waitcnt lgkmcnt(12)
	v_pk_fma_f32 v[28:29], v[176:177], v[84:85], v[28:29] op_sel_hi:[0,1,1]
	s_waitcnt lgkmcnt(11)
	v_pk_fma_f32 v[26:27], v[176:177], v[86:87], v[26:27] op_sel_hi:[0,1,1]
	s_waitcnt lgkmcnt(10)
	v_pk_fma_f32 v[24:25], v[176:177], v[88:89], v[24:25] op_sel_hi:[0,1,1]
	s_waitcnt lgkmcnt(9)
	v_pk_fma_f32 v[22:23], v[176:177], v[90:91], v[22:23] op_sel_hi:[0,1,1]
	s_waitcnt lgkmcnt(8)
	v_pk_fma_f32 v[20:21], v[176:177], v[92:93], v[20:21] op_sel_hi:[0,1,1]
	s_waitcnt lgkmcnt(7)
	v_pk_fma_f32 v[18:19], v[176:177], v[94:95], v[18:19] op_sel_hi:[0,1,1]
	s_waitcnt lgkmcnt(6)
	v_pk_fma_f32 v[16:17], v[176:177], v[96:97], v[16:17] op_sel_hi:[0,1,1]
	s_waitcnt lgkmcnt(5)
	v_pk_fma_f32 v[14:15], v[176:177], v[98:99], v[14:15] op_sel_hi:[0,1,1]
	s_waitcnt lgkmcnt(4)
	v_pk_fma_f32 v[12:13], v[176:177], v[100:101], v[12:13] op_sel_hi:[0,1,1]
	s_waitcnt lgkmcnt(3)
	v_pk_fma_f32 v[10:11], v[176:177], v[102:103], v[10:11] op_sel_hi:[0,1,1]
	s_waitcnt lgkmcnt(2)
	v_pk_fma_f32 v[8:9], v[176:177], v[104:105], v[8:9] op_sel_hi:[0,1,1]
	s_waitcnt lgkmcnt(1)
	v_pk_fma_f32 v[6:7], v[176:177], v[106:107], v[6:7] op_sel_hi:[0,1,1]
	s_waitcnt lgkmcnt(0)
	v_pk_fma_f32 v[4:5], v[176:177], v[108:109], v[4:5] op_sel_hi:[0,1,1]
	s_cbranch_scc1 .Lmk_a_s12
	global_load_dword v176, v[38:39], off
	v_lshl_add_u64 v[38:39], v[38:39], 0, s[26:27]
; __device__ void mod_item(const Params& p, int item, float* lds, int wave) {
;     ...
;         for (int kk = kg * 64; kk < kg * 64 + 64; ++kk) {
;             const float w = p.ada_w[(size_t)(half * 512 + kk) * MODW + col0 + col];
; #pragma unroll
;             for (int b = 0; b < NB; ++b) acc[b] += lds[kk * 36 + b] * w;
.Lmk_a_s12:
	ds_read_b96 v[74:76], v37
	ds_read2_b32 v[80:81], v37 offset0:3 offset1:4
	ds_read2_b32 v[82:83], v37 offset0:5 offset1:6
	ds_read2_b32 v[84:85], v37 offset0:7 offset1:8
	ds_read2_b32 v[86:87], v37 offset0:9 offset1:10
	ds_read2_b32 v[88:89], v37 offset0:11 offset1:12
	ds_read2_b32 v[90:91], v37 offset0:13 offset1:14
	ds_read2_b32 v[92:93], v37 offset0:15 offset1:16
	ds_read2_b32 v[94:95], v37 offset0:17 offset1:18
	ds_read2_b32 v[96:97], v37 offset0:19 offset1:20
	ds_read2_b32 v[98:99], v37 offset0:21 offset1:22
	ds_read2_b32 v[100:101], v37 offset0:23 offset1:24
	ds_read2_b32 v[102:103], v37 offset0:25 offset1:26
	ds_read2_b32 v[104:105], v37 offset0:27 offset1:28
	ds_read2_b32 v[106:107], v37 offset0:29 offset1:30
	ds_read2_b32 v[108:109], v37 offset0:31 offset1:32
	s_waitcnt lgkmcnt(14)
	v_mov_b32_e32 v110, v75
	v_mov_b32_e32 v111, v76
	v_add_u32_e32 v37, 0x90, v37
	s_waitcnt vmcnt(15)
	v_fmac_f32_e32 v69, v178, v74
	v_pk_fma_f32 v[34:35], v[178:179], v[110:111], v[34:35] op_sel_hi:[0,1,1]
	v_pk_fma_f32 v[32:33], v[178:179], v[80:81], v[32:33] op_sel_hi:[0,1,1]
	s_waitcnt lgkmcnt(13)
	v_pk_fma_f32 v[30:31], v[178:179], v[82:83], v[30:31] op_sel_hi:[0,1,1]
	s_waitcnt lgkmcnt(12)
	v_pk_fma_f32 v[28:29], v[178:179], v[84:85], v[28:29] op_sel_hi:[0,1,1]
	s_waitcnt lgkmcnt(11)
	v_pk_fma_f32 v[26:27], v[178:179], v[86:87], v[26:27] op_sel_hi:[0,1,1]
	s_waitcnt lgkmcnt(10)
	v_pk_fma_f32 v[24:25], v[178:179], v[88:89], v[24:25] op_sel_hi:[0,1,1]
	s_waitcnt lgkmcnt(9)
	v_pk_fma_f32 v[22:23], v[178:179], v[90:91], v[22:23] op_sel_hi:[0,1,1]
	s_waitcnt lgkmcnt(8)
	v_pk_fma_f32 v[20:21], v[178:179], v[92:93], v[20:21] op_sel_hi:[0,1,1]
	s_waitcnt lgkmcnt(7)
	v_pk_fma_f32 v[18:19], v[178:179], v[94:95], v[18:19] op_sel_hi:[0,1,1]
	s_waitcnt lgkmcnt(6)
	v_pk_fma_f32 v[16:17], v[178:179], v[96:97], v[16:17] op_sel_hi:[0,1,1]
	s_waitcnt lgkmcnt(5)
	v_pk_fma_f32 v[14:15], v[178:179], v[98:99], v[14:15] op_sel_hi:[0,1,1]
	s_waitcnt lgkmcnt(4)
	v_pk_fma_f32 v[12:13], v[178:179], v[100:101], v[12:13] op_sel_hi:[0,1,1]
	s_waitcnt lgkmcnt(3)
	v_pk_fma_f32 v[10:11], v[178:179], v[102:103], v[10:11] op_sel_hi:[0,1,1]
	s_waitcnt lgkmcnt(2)
	v_pk_fma_f32 v[8:9], v[178:179], v[104:105], v[8:9] op_sel_hi:[0,1,1]
	s_waitcnt lgkmcnt(1)
	v_pk_fma_f32 v[6:7], v[178:179], v[106:107], v[6:7] op_sel_hi:[0,1,1]
	s_waitcnt lgkmcnt(0)
	v_pk_fma_f32 v[4:5], v[178:179], v[108:109], v[4:5] op_sel_hi:[0,1,1]
	s_cbranch_scc1 .Lmk_a_s13
	global_load_dword v178, v[38:39], off
	v_lshl_add_u64 v[38:39], v[38:39], 0, s[26:27]
.Lmk_a_s13:
	ds_read_b96 v[74:76], v37
	ds_read2_b32 v[80:81], v37 offset0:3 offset1:4
	ds_read2_b32 v[82:83], v37 offset0:5 offset1:6
	ds_read2_b32 v[84:85], v37 offset0:7 offset1:8
	ds_read2_b32 v[86:87], v37 offset0:9 offset1:10
	ds_read2_b32 v[88:89], v37 offset0:11 offset1:12
	ds_read2_b32 v[90:91], v37 offset0:13 offset1:14
	ds_read2_b32 v[92:93], v37 offset0:15 offset1:16
	ds_read2_b32 v[94:95], v37 offset0:17 offset1:18
	ds_read2_b32 v[96:97], v37 offset0:19 offset1:20
	ds_read2_b32 v[98:99], v37 offset0:21 offset1:22
	ds_read2_b32 v[100:101], v37 offset0:23 offset1:24
	ds_read2_b32 v[102:103], v37 offset0:25 offset1:26
	ds_read2_b32 v[104:105], v37 offset0:27 offset1:28
	ds_read2_b32 v[106:107], v37 offset0:29 offset1:30
	ds_read2_b32 v[108:109], v37 offset0:31 offset1:32
	s_waitcnt lgkmcnt(14)
	v_mov_b32_e32 v110, v75
	v_mov_b32_e32 v111, v76
	v_add_u32_e32 v37, 0x90, v37
	s_waitcnt vmcnt(15)
	v_fmac_f32_e32 v69, v180, v74
	v_pk_fma_f32 v[34:35], v[180:181], v[110:111], v[34:35] op_sel_hi:[0,1,1]
	v_pk_fma_f32 v[32:33], v[180:181], v[80:81], v[32:33] op_sel_hi:[0,1,1]
	s_waitcnt lgkmcnt(13)
	v_pk_fma_f32 v[30:31], v[180:181], v[82:83], v[30:31] op_sel_hi:[0,1,1]
	s_waitcnt lgkmcnt(12)
	v_pk_fma_f32 v[28:29], v[180:181], v[84:85], v[28:29] op_sel_hi:[0,1,1]
	s_waitcnt lgkmcnt(11)
	v_pk_fma_f32 v[26:27], v[180:181], v[86:87], v[26:27] op_sel_hi:[0,1,1]
	s_waitcnt lgkmcnt(10)
	v_pk_fma_f32 v[24:25], v[180:181], v[88:89], v[24:25] op_sel_hi:[0,1,1]
	s_waitcnt lgkmcnt(9)
	v_pk_fma_f32 v[22:23], v[180:181], v[90:91], v[22:23] op_sel_hi:[0,1,1]
	s_waitcnt lgkmcnt(8)
	v_pk_fma_f32 v[20:21], v[180:181], v[92:93], v[20:21] op_sel_hi:[0,1,1]
	s_waitcnt lgkmcnt(7)
	v_pk_fma_f32 v[18:19], v[180:181], v[94:95], v[18:19] op_sel_hi:[0,1,1]
	s_waitcnt lgkmcnt(6)
	v_pk_fma_f32 v[16:17], v[180:181], v[96:97], v[16:17] op_sel_hi:[0,1,1]
	s_waitcnt lgkmcnt(5)
	v_pk_fma_f32 v[14:15], v[180:181], v[98:99], v[14:15] op_sel_hi:[0,1,1]
	s_waitcnt lgkmcnt(4)
	v_pk_fma_f32 v[12:13], v[180:181], v[100:101], v[12:13] op_sel_hi:[0,1,1]
	s_waitcnt lgkmcnt(3)
	v_pk_fma_f32 v[10:11], v[180:181], v[102:103], v[10:11] op_sel_hi:[0,1,1]
	s_waitcnt lgkmcnt(2)
	v_pk_fma_f32 v[8:9], v[180:181], v[104:105], v[8:9] op_sel_hi:[0,1,1]
	s_waitcnt lgkmcnt(1)
	v_pk_fma_f32 v[6:7], v[180:181], v[106:107], v[6:7] op_sel_hi:[0,1,1]
	s_waitcnt lgkmcnt(0)
	v_pk_fma_f32 v[4:5], v[180:181], v[108:109], v[4:5] op_sel_hi:[0,1,1]
	s_cbranch_scc1 .Lmk_a_s14
	global_load_dword v180, v[38:39], off
	v_lshl_add_u64 v[38:39], v[38:39], 0, s[26:27]
; __device__ void mod_item(const Params& p, int item, float* lds, int wave) {
;     ...
;     for (int half = 0; half < 2; ++half) {
;         __syncthreads();
;         for (int e = tid; e < NB * 512; e += NTHR) { const int b = e >> 9, kk = e & 511;
;             const float c = b < 32 ? p.c_prompt[b * D + half * 512 + kk] : p.c_sample[half * 512 + kk];
;             lds[kk * 36 + b] = c / (1.f + __expf(-c)); }
;         __syncthreads();
;         for (int kk = kg * 64; kk < kg * 64 + 64; ++kk) {
;             const float w = p.ada_w[(size_t)(half * 512 + kk) * MODW + col0 + col];
; #pragma unroll
;             for (int b = 0; b < NB; ++b) acc[b] += lds[kk * 36 + b] * w;
.Lmk_a_s14:
	ds_read_b96 v[74:76], v37
	ds_read2_b32 v[80:81], v37 offset0:3 offset1:4
	ds_read2_b32 v[82:83], v37 offset0:5 offset1:6
	ds_read2_b32 v[84:85], v37 offset0:7 offset1:8
	ds_read2_b32 v[86:87], v37 offset0:9 offset1:10
	ds_read2_b32 v[88:89], v37 offset0:11 offset1:12
	ds_read2_b32 v[90:91], v37 offset0:13 offset1:14
	ds_read2_b32 v[92:93], v37 offset0:15 offset1:16
	ds_read2_b32 v[94:95], v37 offset0:17 offset1:18
	ds_read2_b32 v[96:97], v37 offset0:19 offset1:20
	ds_read2_b32 v[98:99], v37 offset0:21 offset1:22
	ds_read2_b32 v[100:101], v37 offset0:23 offset1:24
	ds_read2_b32 v[102:103], v37 offset0:25 offset1:26
	ds_read2_b32 v[104:105], v37 offset0:27 offset1:28
	ds_read2_b32 v[106:107], v37 offset0:29 offset1:30
	ds_read2_b32 v[108:109], v37 offset0:31 offset1:32
	s_waitcnt lgkmcnt(14)
	v_mov_b32_e32 v110, v75
	v_mov_b32_e32 v111, v76
	v_add_u32_e32 v37, 0x90, v37
	s_waitcnt vmcnt(15)
	v_fmac_f32_e32 v69, v182, v74
	v_pk_fma_f32 v[34:35], v[182:183], v[110:111], v[34:35] op_sel_hi:[0,1,1]
	v_pk_fma_f32 v[32:33], v[182:183], v[80:81], v[32:33] op_sel_hi:[0,1,1]
	s_waitcnt lgkmcnt(13)
	v_pk_fma_f32 v[30:31], v[182:183], v[82:83], v[30:31] op_sel_hi:[0,1,1]
	s_waitcnt lgkmcnt(12)
	v_pk_fma_f32 v[28:29], v[182:183], v[84:85], v[28:29] op_sel_hi:[0,1,1]
	s_waitcnt lgkmcnt(11)
	v_pk_fma_f32 v[26:27], v[182:183], v[86:87], v[26:27] op_sel_hi:[0,1,1]
	s_waitcnt lgkmcnt(10)
	v_pk_fma_f32 v[24:25], v[182:183], v[88:89], v[24:25] op_sel_hi:[0,1,1]
	s_waitcnt lgkmcnt(9)
	v_pk_fma_f32 v[22:23], v[182:183], v[90:91], v[22:23] op_sel_hi:[0,1,1]
	s_waitcnt lgkmcnt(8)
	v_pk_fma_f32 v[20:21], v[182:183], v[92:93], v[20:21] op_sel_hi:[0,1,1]
	s_waitcnt lgkmcnt(7)
	v_pk_fma_f32 v[18:19], v[182:183], v[94:95], v[18:19] op_sel_hi:[0,1,1]
	s_waitcnt lgkmcnt(6)
	v_pk_fma_f32 v[16:17], v[182:183], v[96:97], v[16:17] op_sel_hi:[0,1,1]
	s_waitcnt lgkmcnt(5)
	v_pk_fma_f32 v[14:15], v[182:183], v[98:99], v[14:15] op_sel_hi:[0,1,1]
	s_waitcnt lgkmcnt(4)
	v_pk_fma_f32 v[12:13], v[182:183], v[100:101], v[12:13] op_sel_hi:[0,1,1]
	s_waitcnt lgkmcnt(3)
	v_pk_fma_f32 v[10:11], v[182:183], v[102:103], v[10:11] op_sel_hi:[0,1,1]
	s_waitcnt lgkmcnt(2)
	v_pk_fma_f32 v[8:9], v[182:183], v[104:105], v[8:9] op_sel_hi:[0,1,1]
	s_waitcnt lgkmcnt(1)
	v_pk_fma_f32 v[6:7], v[182:183], v[106:107], v[6:7] op_sel_hi:[0,1,1]
	s_waitcnt lgkmcnt(0)
	v_pk_fma_f32 v[4:5], v[182:183], v[108:109], v[4:5] op_sel_hi:[0,1,1]
	s_cbranch_scc1 .Lmk_a_s15
	global_load_dword v182, v[38:39], off
	v_lshl_add_u64 v[38:39], v[38:39], 0, s[26:27]
.Lmk_a_s15:
	s_add_i32 s98, s98, 1
	s_cmp_lt_u32 s98, 4
	s_cbranch_scc1 .Lmk_a_loop
	s_or_b64 exec, exec, s[6:7]
	s_barrier
	s_and_saveexec_b64 s[6:7], s[0:1]
	v_readlane_b32 s8, v253, 12
	v_readlane_b32 s12, v253, 16
	v_readlane_b32 s13, v253, 17
	v_readlane_b32 s14, v253, 18
	v_readlane_b32 s15, v253, 19
	v_readlane_b32 s9, v253, 13
	v_readlane_b32 s10, v253, 14
	v_readlane_b32 s11, v253, 15
	v_readlane_b32 s16, v253, 20
	v_readlane_b32 s17, v253, 21
	v_readlane_b32 s18, v253, 22
	v_readlane_b32 s19, v253, 23
	v_readlane_b32 s20, v253, 24
	v_readlane_b32 s21, v253, 25
	v_readlane_b32 s22, v253, 26
	v_readlane_b32 s23, v253, 27
	s_cbranch_execz .LBB0_45
	v_mov_b32_e32 v37, v1
	v_lshl_add_u64 v[36:37], s[14:15], 0, v[36:37]
	s_mov_b64 s[0:1], 0
	v_mov_b32_e32 v38, v65
	s_mov_b64 s[100:101], 0x1000
	v_mov_b32_e32 v185, v1
	v_lshlrev_b32_e32 v184, 2, v70
	v_lshl_add_u64 v[184:185], s[12:13], 0, v[184:185]
	global_load_dword v118, v[184:185], off offset:2048
	v_lshl_add_u64 v[184:185], v[184:185], 0, s[100:101]
	global_load_dword v119, v[184:185], off offset:2048
	v_lshl_add_u64 v[184:185], v[184:185], 0, s[100:101]
	global_load_dword v120, v[184:185], off offset:2048
	v_lshl_add_u64 v[184:185], v[184:185], 0, s[100:101]
	global_load_dword v121, v[184:185], off offset:2048
	v_lshl_add_u64 v[184:185], v[184:185], 0, s[100:101]
	global_load_dword v122, v[184:185], off offset:2048
	v_lshl_add_u64 v[184:185], v[184:185], 0, s[100:101]
	global_load_dword v123, v[184:185], off offset:2048
	v_lshl_add_u64 v[184:185], v[184:185], 0, s[100:101]
	global_load_dword v124, v[184:185], off offset:2048
	v_lshl_add_u64 v[184:185], v[184:185], 0, s[100:101]
	global_load_dword v125, v[184:185], off offset:2048
	v_lshl_add_u64 v[184:185], v[184:185], 0, s[100:101]
	global_load_dword v126, v[184:185], off offset:2048
	v_lshl_add_u64 v[184:185], v[184:185], 0, s[100:101]
	global_load_dword v127, v[184:185], off offset:2048
	v_lshl_add_u64 v[184:185], v[184:185], 0, s[100:101]
	global_load_dword v128, v[184:185], off offset:2048
	v_lshl_add_u64 v[184:185], v[184:185], 0, s[100:101]
	global_load_dword v129, v[184:185], off offset:2048
	v_lshl_add_u64 v[184:185], v[184:185], 0, s[100:101]
	global_load_dword v130, v[184:185], off offset:2048
	v_lshl_add_u64 v[184:185], v[184:185], 0, s[100:101]
	global_load_dword v131, v[184:185], off offset:2048
	v_lshl_add_u64 v[184:185], v[184:185], 0, s[100:101]
	global_load_dword v132, v[184:185], off offset:2048
	v_lshl_add_u64 v[184:185], v[184:185], 0, s[100:101]
	global_load_dword v133, v[184:185], off offset:2048
	v_lshl_add_u64 v[184:185], v[184:185], 0, s[100:101]
	global_load_dword v134, v[184:185], off offset:2048
	v_lshl_add_u64 v[184:185], v[184:185], 0, s[100:101]
	global_load_dword v135, v[184:185], off offset:2048
	v_lshl_add_u64 v[184:185], v[184:185], 0, s[100:101]
	global_load_dword v136, v[184:185], off offset:2048
	v_lshl_add_u64 v[184:185], v[184:185], 0, s[100:101]
	global_load_dword v137, v[184:185], off offset:2048
	v_lshl_add_u64 v[184:185], v[184:185], 0, s[100:101]
	global_load_dword v138, v[184:185], off offset:2048
	v_lshl_add_u64 v[184:185], v[184:185], 0, s[100:101]
	global_load_dword v139, v[184:185], off offset:2048
	v_lshl_add_u64 v[184:185], v[184:185], 0, s[100:101]
	global_load_dword v140, v[184:185], off offset:2048
	v_lshl_add_u64 v[184:185], v[184:185], 0, s[100:101]
	global_load_dword v141, v[184:185], off offset:2048
	v_lshl_add_u64 v[184:185], v[184:185], 0, s[100:101]
	global_load_dword v142, v[184:185], off offset:2048
	v_lshl_add_u64 v[184:185], v[184:185], 0, s[100:101]
	global_load_dword v143, v[184:185], off offset:2048
	v_lshl_add_u64 v[184:185], v[184:185], 0, s[100:101]
	global_load_dword v144, v[184:185], off offset:2048
	v_lshl_add_u64 v[184:185], v[184:185], 0, s[100:101]
	global_load_dword v145, v[184:185], off offset:2048
	v_lshl_add_u64 v[184:185], v[184:185], 0, s[100:101]
	global_load_dword v146, v[184:185], off offset:2048
	v_lshl_add_u64 v[184:185], v[184:185], 0, s[100:101]
	global_load_dword v147, v[184:185], off offset:2048
	v_lshl_add_u64 v[184:185], v[184:185], 0, s[100:101]
	global_load_dword v148, v[184:185], off offset:2048
	v_lshl_add_u64 v[184:185], v[184:185], 0, s[100:101]
	global_load_dword v149, v[184:185], off offset:2048
	v_lshl_add_u64 v[184:185], v[184:185], 0, s[100:101]
	global_load_dword v150, v[36:37], off offset:2048
	s_waitcnt vmcnt(32)
; __device__ void mod_item(const Params& p, int item, float* lds, int wave) {
;     ...
;         for (int e = tid; e < NB * 512; e += NTHR) { const int b = e >> 9, kk = e & 511;
;             const float c = b < 32 ? p.c_prompt[b * D + half * 512 + kk] : p.c_sample[half * 512 + kk];
;             lds[kk * 36 + b] = c / (1.f + __expf(-c)); }
	v_mul_f32_e32 v184, 0xbfb8aa3b, v118
	v_exp_f32_e32 v185, v184
	s_nop 0
	v_add_f32_e32 v186, 1.0, v185
	v_div_scale_f32 v185, s[8:9], v186, v186, v118
	v_rcp_f32_e32 v187, v185
	v_div_scale_f32 v188, vcc, v118, v186, v118
	v_fma_f32 v189, -v185, v187, 1.0
	v_fmac_f32_e32 v187, v189, v187
	v_mul_f32_e32 v189, v188, v187
	v_fma_f32 v190, -v185, v189, v188
	v_fmac_f32_e32 v189, v190, v187
	v_fma_f32 v185, -v185, v189, v188
	v_div_fmas_f32 v185, v185, v187, v189
	v_div_fixup_f32 v118, v185, v186, v118
	ds_write_b32 v71, v118 offset:0
	s_waitcnt vmcnt(31)
	v_mul_f32_e32 v184, 0xbfb8aa3b, v119
	v_exp_f32_e32 v185, v184
	s_nop 0
	v_add_f32_e32 v186, 1.0, v185
	v_div_scale_f32 v185, s[8:9], v186, v186, v119
	v_rcp_f32_e32 v187, v185
	v_div_scale_f32 v188, vcc, v119, v186, v119
	v_fma_f32 v189, -v185, v187, 1.0
	v_fmac_f32_e32 v187, v189, v187
	v_mul_f32_e32 v189, v188, v187
	v_fma_f32 v190, -v185, v189, v188
	v_fmac_f32_e32 v189, v190, v187
	v_fma_f32 v185, -v185, v189, v188
	v_div_fmas_f32 v185, v185, v187, v189
	v_div_fixup_f32 v119, v185, v186, v119
	ds_write_b32 v71, v119 offset:4
	s_waitcnt vmcnt(30)
	v_mul_f32_e32 v184, 0xbfb8aa3b, v120
	v_exp_f32_e32 v185, v184
	s_nop 0
	v_add_f32_e32 v186, 1.0, v185
	v_div_scale_f32 v185, s[8:9], v186, v186, v120
	v_rcp_f32_e32 v187, v185
	v_div_scale_f32 v188, vcc, v120, v186, v120
	v_fma_f32 v189, -v185, v187, 1.0
	v_fmac_f32_e32 v187, v189, v187
	v_mul_f32_e32 v189, v188, v187
	v_fma_f32 v190, -v185, v189, v188
	v_fmac_f32_e32 v189, v190, v187
	v_fma_f32 v185, -v185, v189, v188
	v_div_fmas_f32 v185, v185, v187, v189
	v_div_fixup_f32 v120, v185, v186, v120
	ds_write_b32 v71, v120 offset:8
	s_waitcnt vmcnt(29)
	v_mul_f32_e32 v184, 0xbfb8aa3b, v121
	v_exp_f32_e32 v185, v184
	s_nop 0
	v_add_f32_e32 v186, 1.0, v185
	v_div_scale_f32 v185, s[8:9], v186, v186, v121
	v_rcp_f32_e32 v187, v185
	v_div_scale_f32 v188, vcc, v121, v186, v121
	v_fma_f32 v189, -v185, v187, 1.0
	v_fmac_f32_e32 v187, v189, v187
	v_mul_f32_e32 v189, v188, v187
	v_fma_f32 v190, -v185, v189, v188
	v_fmac_f32_e32 v189, v190, v187
	v_fma_f32 v185, -v185, v189, v188
	v_div_fmas_f32 v185, v185, v187, v189
	v_div_fixup_f32 v121, v185, v186, v121
	ds_write_b32 v71, v121 offset:12
	s_waitcnt vmcnt(28)
	v_mul_f32_e32 v184, 0xbfb8aa3b, v122
	v_exp_f32_e32 v185, v184
	s_nop 0
	v_add_f32_e32 v186, 1.0, v185
	v_div_scale_f32 v185, s[8:9], v186, v186, v122
	v_rcp_f32_e32 v187, v185
	v_div_scale_f32 v188, vcc, v122, v186, v122
	v_fma_f32 v189, -v185, v187, 1.0
	v_fmac_f32_e32 v187, v189, v187
	v_mul_f32_e32 v189, v188, v187
	v_fma_f32 v190, -v185, v189, v188
	v_fmac_f32_e32 v189, v190, v187
	v_fma_f32 v185, -v185, v189, v188
	v_div_fmas_f32 v185, v185, v187, v189
	v_div_fixup_f32 v122, v185, v186, v122
	ds_write_b32 v71, v122 offset:16
	s_waitcnt vmcnt(27)
	v_mul_f32_e32 v184, 0xbfb8aa3b, v123
	v_exp_f32_e32 v185, v184
	s_nop 0
	v_add_f32_e32 v186, 1.0, v185
	v_div_scale_f32 v185, s[8:9], v186, v186, v123
	v_rcp_f32_e32 v187, v185
	v_div_scale_f32 v188, vcc, v123, v186, v123
	v_fma_f32 v189, -v185, v187, 1.0
	v_fmac_f32_e32 v187, v189, v187
	v_mul_f32_e32 v189, v188, v187
	v_fma_f32 v190, -v185, v189, v188
	v_fmac_f32_e32 v189, v190, v187
	v_fma_f32 v185, -v185, v189, v188
	v_div_fmas_f32 v185, v185, v187, v189
	v_div_fixup_f32 v123, v185, v186, v123
	ds_write_b32 v71, v123 offset:20
	s_waitcnt vmcnt(26)
	v_mul_f32_e32 v184, 0xbfb8aa3b, v124
	v_exp_f32_e32 v185, v184
	s_nop 0
	v_add_f32_e32 v186, 1.0, v185
	v_div_scale_f32 v185, s[8:9], v186, v186, v124
	v_rcp_f32_e32 v187, v185
	v_div_scale_f32 v188, vcc, v124, v186, v124
	v_fma_f32 v189, -v185, v187, 1.0
	v_fmac_f32_e32 v187, v189, v187
	v_mul_f32_e32 v189, v188, v187
	v_fma_f32 v190, -v185, v189, v188
	v_fmac_f32_e32 v189, v190, v187
	v_fma_f32 v185, -v185, v189, v188
	v_div_fmas_f32 v185, v185, v187, v189
	v_div_fixup_f32 v124, v185, v186, v124
	ds_write_b32 v71, v124 offset:24
	s_waitcnt vmcnt(25)
	v_mul_f32_e32 v184, 0xbfb8aa3b, v125
	v_exp_f32_e32 v185, v184
	s_nop 0
	v_add_f32_e32 v186, 1.0, v185
	v_div_scale_f32 v185, s[8:9], v186, v186, v125
	v_rcp_f32_e32 v187, v185
	v_div_scale_f32 v188, vcc, v125, v186, v125
	v_fma_f32 v189, -v185, v187, 1.0
	v_fmac_f32_e32 v187, v189, v187
	v_mul_f32_e32 v189, v188, v187
	v_fma_f32 v190, -v185, v189, v188
	v_fmac_f32_e32 v189, v190, v187
	v_fma_f32 v185, -v185, v189, v188
	v_div_fmas_f32 v185, v185, v187, v189
	v_div_fixup_f32 v125, v185, v186, v125
	ds_write_b32 v71, v125 offset:28
	s_waitcnt vmcnt(24)
	v_mul_f32_e32 v184, 0xbfb8aa3b, v126
	v_exp_f32_e32 v185, v184
	s_nop 0
	v_add_f32_e32 v186, 1.0, v185
	v_div_scale_f32 v185, s[8:9], v186, v186, v126
	v_rcp_f32_e32 v187, v185
	v_div_scale_f32 v188, vcc, v126, v186, v126
	v_fma_f32 v189, -v185, v187, 1.0
	v_fmac_f32_e32 v187, v189, v187
	v_mul_f32_e32 v189, v188, v187
	v_fma_f32 v190, -v185, v189, v188
	v_fmac_f32_e32 v189, v190, v187
	v_fma_f32 v185, -v185, v189, v188
	v_div_fmas_f32 v185, v185, v187, v189
	v_div_fixup_f32 v126, v185, v186, v126
	ds_write_b32 v71, v126 offset:32
	s_waitcnt vmcnt(23)
	v_mul_f32_e32 v184, 0xbfb8aa3b, v127
	v_exp_f32_e32 v185, v184
	s_nop 0
	v_add_f32_e32 v186, 1.0, v185
	v_div_scale_f32 v185, s[8:9], v186, v186, v127
	v_rcp_f32_e32 v187, v185
	v_div_scale_f32 v188, vcc, v127, v186, v127
	v_fma_f32 v189, -v185, v187, 1.0
	v_fmac_f32_e32 v187, v189, v187
	v_mul_f32_e32 v189, v188, v187
	v_fma_f32 v190, -v185, v189, v188
	v_fmac_f32_e32 v189, v190, v187
	v_fma_f32 v185, -v185, v189, v188
	v_div_fmas_f32 v185, v185, v187, v189
	v_div_fixup_f32 v127, v185, v186, v127
	ds_write_b32 v71, v127 offset:36
	s_waitcnt vmcnt(22)
; __device__ void mod_item(const Params& p, int item, float* lds, int wave) {
;     ...
;         for (int e = tid; e < NB * 512; e += NTHR) { const int b = e >> 9, kk = e & 511;
;             const float c = b < 32 ? p.c_prompt[b * D + half * 512 + kk] : p.c_sample[half * 512 + kk];
;             lds[kk * 36 + b] = c / (1.f + __expf(-c)); }
	v_mul_f32_e32 v184, 0xbfb8aa3b, v128
	v_exp_f32_e32 v185, v184
	s_nop 0
	v_add_f32_e32 v186, 1.0, v185
	v_div_scale_f32 v185, s[8:9], v186, v186, v128
	v_rcp_f32_e32 v187, v185
	v_div_scale_f32 v188, vcc, v128, v186, v128
	v_fma_f32 v189, -v185, v187, 1.0
	v_fmac_f32_e32 v187, v189, v187
	v_mul_f32_e32 v189, v188, v187
	v_fma_f32 v190, -v185, v189, v188
	v_fmac_f32_e32 v189, v190, v187
	v_fma_f32 v185, -v185, v189, v188
	v_div_fmas_f32 v185, v185, v187, v189
	v_div_fixup_f32 v128, v185, v186, v128
	ds_write_b32 v71, v128 offset:40
	s_waitcnt vmcnt(21)
	v_mul_f32_e32 v184, 0xbfb8aa3b, v129
	v_exp_f32_e32 v185, v184
	s_nop 0
	v_add_f32_e32 v186, 1.0, v185
	v_div_scale_f32 v185, s[8:9], v186, v186, v129
	v_rcp_f32_e32 v187, v185
	v_div_scale_f32 v188, vcc, v129, v186, v129
	v_fma_f32 v189, -v185, v187, 1.0
	v_fmac_f32_e32 v187, v189, v187
	v_mul_f32_e32 v189, v188, v187
	v_fma_f32 v190, -v185, v189, v188
	v_fmac_f32_e32 v189, v190, v187
	v_fma_f32 v185, -v185, v189, v188
	v_div_fmas_f32 v185, v185, v187, v189
	v_div_fixup_f32 v129, v185, v186, v129
	ds_write_b32 v71, v129 offset:44
	s_waitcnt vmcnt(20)
	v_mul_f32_e32 v184, 0xbfb8aa3b, v130
	v_exp_f32_e32 v185, v184
	s_nop 0
	v_add_f32_e32 v186, 1.0, v185
	v_div_scale_f32 v185, s[8:9], v186, v186, v130
	v_rcp_f32_e32 v187, v185
	v_div_scale_f32 v188, vcc, v130, v186, v130
	v_fma_f32 v189, -v185, v187, 1.0
	v_fmac_f32_e32 v187, v189, v187
	v_mul_f32_e32 v189, v188, v187
	v_fma_f32 v190, -v185, v189, v188
	v_fmac_f32_e32 v189, v190, v187
	v_fma_f32 v185, -v185, v189, v188
	v_div_fmas_f32 v185, v185, v187, v189
	v_div_fixup_f32 v130, v185, v186, v130
	ds_write_b32 v71, v130 offset:48
	s_waitcnt vmcnt(19)
	v_mul_f32_e32 v184, 0xbfb8aa3b, v131
	v_exp_f32_e32 v185, v184
	s_nop 0
	v_add_f32_e32 v186, 1.0, v185
	v_div_scale_f32 v185, s[8:9], v186, v186, v131
	v_rcp_f32_e32 v187, v185
	v_div_scale_f32 v188, vcc, v131, v186, v131
	v_fma_f32 v189, -v185, v187, 1.0
	v_fmac_f32_e32 v187, v189, v187
	v_mul_f32_e32 v189, v188, v187
	v_fma_f32 v190, -v185, v189, v188
	v_fmac_f32_e32 v189, v190, v187
	v_fma_f32 v185, -v185, v189, v188
	v_div_fmas_f32 v185, v185, v187, v189
	v_div_fixup_f32 v131, v185, v186, v131
	ds_write_b32 v71, v131 offset:52
	s_waitcnt vmcnt(18)
	v_mul_f32_e32 v184, 0xbfb8aa3b, v132
	v_exp_f32_e32 v185, v184
	s_nop 0
	v_add_f32_e32 v186, 1.0, v185
	v_div_scale_f32 v185, s[8:9], v186, v186, v132
	v_rcp_f32_e32 v187, v185
	v_div_scale_f32 v188, vcc, v132, v186, v132
	v_fma_f32 v189, -v185, v187, 1.0
	v_fmac_f32_e32 v187, v189, v187
	v_mul_f32_e32 v189, v188, v187
	v_fma_f32 v190, -v185, v189, v188
	v_fmac_f32_e32 v189, v190, v187
	v_fma_f32 v185, -v185, v189, v188
	v_div_fmas_f32 v185, v185, v187, v189
	v_div_fixup_f32 v132, v185, v186, v132
	ds_write_b32 v71, v132 offset:56
	s_waitcnt vmcnt(17)
	v_mul_f32_e32 v184, 0xbfb8aa3b, v133
	v_exp_f32_e32 v185, v184
	s_nop 0
	v_add_f32_e32 v186, 1.0, v185
	v_div_scale_f32 v185, s[8:9], v186, v186, v133
	v_rcp_f32_e32 v187, v185
	v_div_scale_f32 v188, vcc, v133, v186, v133
	v_fma_f32 v189, -v185, v187, 1.0
	v_fmac_f32_e32 v187, v189, v187
	v_mul_f32_e32 v189, v188, v187
	v_fma_f32 v190, -v185, v189, v188
	v_fmac_f32_e32 v189, v190, v187
	v_fma_f32 v185, -v185, v189, v188
	v_div_fmas_f32 v185, v185, v187, v189
	v_div_fixup_f32 v133, v185, v186, v133
	ds_write_b32 v71, v133 offset:60
	s_waitcnt vmcnt(16)
	v_mul_f32_e32 v184, 0xbfb8aa3b, v134
	v_exp_f32_e32 v185, v184
	s_nop 0
	v_add_f32_e32 v186, 1.0, v185
	v_div_scale_f32 v185, s[8:9], v186, v186, v134
	v_rcp_f32_e32 v187, v185
	v_div_scale_f32 v188, vcc, v134, v186, v134
	v_fma_f32 v189, -v185, v187, 1.0
	v_fmac_f32_e32 v187, v189, v187
	v_mul_f32_e32 v189, v188, v187
	v_fma_f32 v190, -v185, v189, v188
	v_fmac_f32_e32 v189, v190, v187
	v_fma_f32 v185, -v185, v189, v188
	v_div_fmas_f32 v185, v185, v187, v189
	v_div_fixup_f32 v134, v185, v186, v134
	ds_write_b32 v71, v134 offset:64
	s_waitcnt vmcnt(15)
	v_mul_f32_e32 v184, 0xbfb8aa3b, v135
	v_exp_f32_e32 v185, v184
	s_nop 0
	v_add_f32_e32 v186, 1.0, v185
	v_div_scale_f32 v185, s[8:9], v186, v186, v135
	v_rcp_f32_e32 v187, v185
	v_div_scale_f32 v188, vcc, v135, v186, v135
	v_fma_f32 v189, -v185, v187, 1.0
	v_fmac_f32_e32 v187, v189, v187
	v_mul_f32_e32 v189, v188, v187
	v_fma_f32 v190, -v185, v189, v188
	v_fmac_f32_e32 v189, v190, v187
	v_fma_f32 v185, -v185, v189, v188
	v_div_fmas_f32 v185, v185, v187, v189
	v_div_fixup_f32 v135, v185, v186, v135
	ds_write_b32 v71, v135 offset:68
	s_waitcnt vmcnt(14)
	v_mul_f32_e32 v184, 0xbfb8aa3b, v136
	v_exp_f32_e32 v185, v184
	s_nop 0
	v_add_f32_e32 v186, 1.0, v185
	v_div_scale_f32 v185, s[8:9], v186, v186, v136
	v_rcp_f32_e32 v187, v185
	v_div_scale_f32 v188, vcc, v136, v186, v136
	v_fma_f32 v189, -v185, v187, 1.0
	v_fmac_f32_e32 v187, v189, v187
	v_mul_f32_e32 v189, v188, v187
	v_fma_f32 v190, -v185, v189, v188
	v_fmac_f32_e32 v189, v190, v187
	v_fma_f32 v185, -v185, v189, v188
	v_div_fmas_f32 v185, v185, v187, v189
	v_div_fixup_f32 v136, v185, v186, v136
	ds_write_b32 v71, v136 offset:72
	s_waitcnt vmcnt(13)
	v_mul_f32_e32 v184, 0xbfb8aa3b, v137
	v_exp_f32_e32 v185, v184
	s_nop 0
	v_add_f32_e32 v186, 1.0, v185
	v_div_scale_f32 v185, s[8:9], v186, v186, v137
	v_rcp_f32_e32 v187, v185
	v_div_scale_f32 v188, vcc, v137, v186, v137
	v_fma_f32 v189, -v185, v187, 1.0
	v_fmac_f32_e32 v187, v189, v187
	v_mul_f32_e32 v189, v188, v187
	v_fma_f32 v190, -v185, v189, v188
	v_fmac_f32_e32 v189, v190, v187
	v_fma_f32 v185, -v185, v189, v188
	v_div_fmas_f32 v185, v185, v187, v189
	v_div_fixup_f32 v137, v185, v186, v137
	ds_write_b32 v71, v137 offset:76
	s_waitcnt vmcnt(12)
; __device__ void mod_item(const Params& p, int item, float* lds, int wave) {
;     ...
;         for (int e = tid; e < NB * 512; e += NTHR) { const int b = e >> 9, kk = e & 511;
;             const float c = b < 32 ? p.c_prompt[b * D + half * 512 + kk] : p.c_sample[half * 512 + kk];
;             lds[kk * 36 + b] = c / (1.f + __expf(-c)); }
	v_mul_f32_e32 v184, 0xbfb8aa3b, v138
	v_exp_f32_e32 v185, v184
	s_nop 0
	v_add_f32_e32 v186, 1.0, v185
	v_div_scale_f32 v185, s[8:9], v186, v186, v138
	v_rcp_f32_e32 v187, v185
	v_div_scale_f32 v188, vcc, v138, v186, v138
	v_fma_f32 v189, -v185, v187, 1.0
	v_fmac_f32_e32 v187, v189, v187
	v_mul_f32_e32 v189, v188, v187
	v_fma_f32 v190, -v185, v189, v188
	v_fmac_f32_e32 v189, v190, v187
	v_fma_f32 v185, -v185, v189, v188
	v_div_fmas_f32 v185, v185, v187, v189
	v_div_fixup_f32 v138, v185, v186, v138
	ds_write_b32 v71, v138 offset:80
	s_waitcnt vmcnt(11)
	v_mul_f32_e32 v184, 0xbfb8aa3b, v139
	v_exp_f32_e32 v185, v184
	s_nop 0
	v_add_f32_e32 v186, 1.0, v185
	v_div_scale_f32 v185, s[8:9], v186, v186, v139
	v_rcp_f32_e32 v187, v185
	v_div_scale_f32 v188, vcc, v139, v186, v139
	v_fma_f32 v189, -v185, v187, 1.0
	v_fmac_f32_e32 v187, v189, v187
	v_mul_f32_e32 v189, v188, v187
	v_fma_f32 v190, -v185, v189, v188
	v_fmac_f32_e32 v189, v190, v187
	v_fma_f32 v185, -v185, v189, v188
	v_div_fmas_f32 v185, v185, v187, v189
	v_div_fixup_f32 v139, v185, v186, v139
	ds_write_b32 v71, v139 offset:84
	s_waitcnt vmcnt(10)
	v_mul_f32_e32 v184, 0xbfb8aa3b, v140
	v_exp_f32_e32 v185, v184
	s_nop 0
	v_add_f32_e32 v186, 1.0, v185
	v_div_scale_f32 v185, s[8:9], v186, v186, v140
	v_rcp_f32_e32 v187, v185
	v_div_scale_f32 v188, vcc, v140, v186, v140
	v_fma_f32 v189, -v185, v187, 1.0
	v_fmac_f32_e32 v187, v189, v187
	v_mul_f32_e32 v189, v188, v187
	v_fma_f32 v190, -v185, v189, v188
	v_fmac_f32_e32 v189, v190, v187
	v_fma_f32 v185, -v185, v189, v188
	v_div_fmas_f32 v185, v185, v187, v189
	v_div_fixup_f32 v140, v185, v186, v140
	ds_write_b32 v71, v140 offset:88
	s_waitcnt vmcnt(9)
	v_mul_f32_e32 v184, 0xbfb8aa3b, v141
	v_exp_f32_e32 v185, v184
	s_nop 0
	v_add_f32_e32 v186, 1.0, v185
	v_div_scale_f32 v185, s[8:9], v186, v186, v141
	v_rcp_f32_e32 v187, v185
	v_div_scale_f32 v188, vcc, v141, v186, v141
	v_fma_f32 v189, -v185, v187, 1.0
	v_fmac_f32_e32 v187, v189, v187
	v_mul_f32_e32 v189, v188, v187
	v_fma_f32 v190, -v185, v189, v188
	v_fmac_f32_e32 v189, v190, v187
	v_fma_f32 v185, -v185, v189, v188
	v_div_fmas_f32 v185, v185, v187, v189
	v_div_fixup_f32 v141, v185, v186, v141
	ds_write_b32 v71, v141 offset:92
	s_waitcnt vmcnt(8)
	v_mul_f32_e32 v184, 0xbfb8aa3b, v142
	v_exp_f32_e32 v185, v184
	s_nop 0
	v_add_f32_e32 v186, 1.0, v185
	v_div_scale_f32 v185, s[8:9], v186, v186, v142
	v_rcp_f32_e32 v187, v185
	v_div_scale_f32 v188, vcc, v142, v186, v142
	v_fma_f32 v189, -v185, v187, 1.0
	v_fmac_f32_e32 v187, v189, v187
	v_mul_f32_e32 v189, v188, v187
	v_fma_f32 v190, -v185, v189, v188
	v_fmac_f32_e32 v189, v190, v187
	v_fma_f32 v185, -v185, v189, v188
	v_div_fmas_f32 v185, v185, v187, v189
	v_div_fixup_f32 v142, v185, v186, v142
	ds_write_b32 v71, v142 offset:96
	s_waitcnt vmcnt(7)
	v_mul_f32_e32 v184, 0xbfb8aa3b, v143
	v_exp_f32_e32 v185, v184
	s_nop 0
	v_add_f32_e32 v186, 1.0, v185
	v_div_scale_f32 v185, s[8:9], v186, v186, v143
	v_rcp_f32_e32 v187, v185
	v_div_scale_f32 v188, vcc, v143, v186, v143
	v_fma_f32 v189, -v185, v187, 1.0
	v_fmac_f32_e32 v187, v189, v187
	v_mul_f32_e32 v189, v188, v187
	v_fma_f32 v190, -v185, v189, v188
	v_fmac_f32_e32 v189, v190, v187
	v_fma_f32 v185, -v185, v189, v188
	v_div_fmas_f32 v185, v185, v187, v189
	v_div_fixup_f32 v143, v185, v186, v143
	ds_write_b32 v71, v143 offset:100
	s_waitcnt vmcnt(6)
	v_mul_f32_e32 v184, 0xbfb8aa3b, v144
	v_exp_f32_e32 v185, v184
	s_nop 0
	v_add_f32_e32 v186, 1.0, v185
	v_div_scale_f32 v185, s[8:9], v186, v186, v144
	v_rcp_f32_e32 v187, v185
	v_div_scale_f32 v188, vcc, v144, v186, v144
	v_fma_f32 v189, -v185, v187, 1.0
	v_fmac_f32_e32 v187, v189, v187
	v_mul_f32_e32 v189, v188, v187
	v_fma_f32 v190, -v185, v189, v188
	v_fmac_f32_e32 v189, v190, v187
	v_fma_f32 v185, -v185, v189, v188
	v_div_fmas_f32 v185, v185, v187, v189
	v_div_fixup_f32 v144, v185, v186, v144
	ds_write_b32 v71, v144 offset:104
	s_waitcnt vmcnt(5)
	v_mul_f32_e32 v184, 0xbfb8aa3b, v145
	v_exp_f32_e32 v185, v184
	s_nop 0
	v_add_f32_e32 v186, 1.0, v185
	v_div_scale_f32 v185, s[8:9], v186, v186, v145
	v_rcp_f32_e32 v187, v185
	v_div_scale_f32 v188, vcc, v145, v186, v145
	v_fma_f32 v189, -v185, v187, 1.0
	v_fmac_f32_e32 v187, v189, v187
	v_mul_f32_e32 v189, v188, v187
	v_fma_f32 v190, -v185, v189, v188
	v_fmac_f32_e32 v189, v190, v187
	v_fma_f32 v185, -v185, v189, v188
	v_div_fmas_f32 v185, v185, v187, v189
	v_div_fixup_f32 v145, v185, v186, v145
	ds_write_b32 v71, v145 offset:108
	s_waitcnt vmcnt(4)
; __device__ void mod_item(const Params& p, int item, float* lds, int wave) {
;     ...
;     for (int half = 0; half < 2; ++half) {
;         __syncthreads();
;         for (int e = tid; e < NB * 512; e += NTHR) { const int b = e >> 9, kk = e & 511;
;             const float c = b < 32 ? p.c_prompt[b * D + half * 512 + kk] : p.c_sample[half * 512 + kk];
;             lds[kk * 36 + b] = c / (1.f + __expf(-c)); }
;         __syncthreads();
;         for (int kk = kg * 64; kk < kg * 64 + 64; ++kk) {
;             const float w = p.ada_w[(size_t)(half * 512 + kk) * MODW + col0 + col];
; #pragma unroll
;             for (int b = 0; b < NB; ++b) acc[b] += lds[kk * 36 + b] * w;
	v_mul_f32_e32 v184, 0xbfb8aa3b, v146
	v_exp_f32_e32 v185, v184
	s_nop 0
	v_add_f32_e32 v186, 1.0, v185
	v_div_scale_f32 v185, s[8:9], v186, v186, v146
	v_rcp_f32_e32 v187, v185
	v_div_scale_f32 v188, vcc, v146, v186, v146
	v_fma_f32 v189, -v185, v187, 1.0
	v_fmac_f32_e32 v187, v189, v187
	v_mul_f32_e32 v189, v188, v187
	v_fma_f32 v190, -v185, v189, v188
	v_fmac_f32_e32 v189, v190, v187
	v_fma_f32 v185, -v185, v189, v188
	v_div_fmas_f32 v185, v185, v187, v189
	v_div_fixup_f32 v146, v185, v186, v146
	ds_write_b32 v71, v146 offset:112
	s_waitcnt vmcnt(3)
	v_mul_f32_e32 v184, 0xbfb8aa3b, v147
	v_exp_f32_e32 v185, v184
	s_nop 0
	v_add_f32_e32 v186, 1.0, v185
	v_div_scale_f32 v185, s[8:9], v186, v186, v147
	v_rcp_f32_e32 v187, v185
	v_div_scale_f32 v188, vcc, v147, v186, v147
	v_fma_f32 v189, -v185, v187, 1.0
	v_fmac_f32_e32 v187, v189, v187
	v_mul_f32_e32 v189, v188, v187
	v_fma_f32 v190, -v185, v189, v188
	v_fmac_f32_e32 v189, v190, v187
	v_fma_f32 v185, -v185, v189, v188
	v_div_fmas_f32 v185, v185, v187, v189
	v_div_fixup_f32 v147, v185, v186, v147
	ds_write_b32 v71, v147 offset:116
	s_waitcnt vmcnt(2)
	v_mul_f32_e32 v184, 0xbfb8aa3b, v148
	v_exp_f32_e32 v185, v184
	s_nop 0
	v_add_f32_e32 v186, 1.0, v185
	v_div_scale_f32 v185, s[8:9], v186, v186, v148
	v_rcp_f32_e32 v187, v185
	v_div_scale_f32 v188, vcc, v148, v186, v148
	v_fma_f32 v189, -v185, v187, 1.0
	v_fmac_f32_e32 v187, v189, v187
	v_mul_f32_e32 v189, v188, v187
	v_fma_f32 v190, -v185, v189, v188
	v_fmac_f32_e32 v189, v190, v187
	v_fma_f32 v185, -v185, v189, v188
	v_div_fmas_f32 v185, v185, v187, v189
	v_div_fixup_f32 v148, v185, v186, v148
	ds_write_b32 v71, v148 offset:120
	s_waitcnt vmcnt(1)
	v_mul_f32_e32 v184, 0xbfb8aa3b, v149
	v_exp_f32_e32 v185, v184
	s_nop 0
	v_add_f32_e32 v186, 1.0, v185
	v_div_scale_f32 v185, s[8:9], v186, v186, v149
	v_rcp_f32_e32 v187, v185
	v_div_scale_f32 v188, vcc, v149, v186, v149
	v_fma_f32 v189, -v185, v187, 1.0
	v_fmac_f32_e32 v187, v189, v187
	v_mul_f32_e32 v189, v188, v187
	v_fma_f32 v190, -v185, v189, v188
	v_fmac_f32_e32 v189, v190, v187
	v_fma_f32 v185, -v185, v189, v188
	v_div_fmas_f32 v185, v185, v187, v189
	v_div_fixup_f32 v149, v185, v186, v149
	ds_write_b32 v71, v149 offset:124
	s_waitcnt vmcnt(0)
	v_mul_f32_e32 v184, 0xbfb8aa3b, v150
	v_exp_f32_e32 v185, v184
	s_nop 0
	v_add_f32_e32 v186, 1.0, v185
	v_div_scale_f32 v185, s[8:9], v186, v186, v150
	v_rcp_f32_e32 v187, v185
	v_div_scale_f32 v188, vcc, v150, v186, v150
	v_fma_f32 v189, -v185, v187, 1.0
	v_fmac_f32_e32 v187, v189, v187
	v_mul_f32_e32 v189, v188, v187
	v_fma_f32 v190, -v185, v189, v188
	v_fmac_f32_e32 v189, v190, v187
	v_fma_f32 v185, -v185, v189, v188
	v_div_fmas_f32 v185, v185, v187, v189
	v_div_fixup_f32 v150, v185, v186, v150
	ds_write_b32 v71, v150 offset:128
.LBB0_45:
	s_or_b64 exec, exec, s[6:7]
	v_add_u32_e32 v38, 0x200, v72
	v_mov_b64_e32 v[36:37], s[4:5]
	v_mad_i64_i32 v[36:37], s[0:1], v38, s45, v[36:37]
	v_readlane_b32 s4, v253, 12
	v_lshl_add_u64 v[36:37], v[36:37], 0, v[0:1]
	v_readlane_b32 s12, v253, 20
	v_readlane_b32 s13, v253, 21
	s_mov_b64 s[0:1], 0
	s_waitcnt lgkmcnt(0)
	v_lshl_add_u64 v[36:37], s[12:13], 0, v[36:37]
	s_barrier
	v_readlane_b32 s5, v253, 13
	v_readlane_b32 s6, v253, 14
	v_readlane_b32 s7, v253, 15
	v_readlane_b32 s8, v253, 16
	v_readlane_b32 s9, v253, 17
	v_readlane_b32 s10, v253, 18
	v_readlane_b32 s11, v253, 19
	v_readlane_b32 s14, v253, 22
	v_readlane_b32 s15, v253, 23
	v_readlane_b32 s16, v253, 24
	v_readlane_b32 s17, v253, 25
	v_readlane_b32 s18, v253, 26
	v_readlane_b32 s19, v253, 27
	global_load_dword v152, v[36:37], off
	v_lshl_add_u64 v[36:37], v[36:37], 0, s[26:27]
	global_load_dword v154, v[36:37], off
	v_lshl_add_u64 v[36:37], v[36:37], 0, s[26:27]
	global_load_dword v156, v[36:37], off
	v_lshl_add_u64 v[36:37], v[36:37], 0, s[26:27]
	global_load_dword v158, v[36:37], off
	v_lshl_add_u64 v[36:37], v[36:37], 0, s[26:27]
	global_load_dword v160, v[36:37], off
	v_lshl_add_u64 v[36:37], v[36:37], 0, s[26:27]
	global_load_dword v162, v[36:37], off
	v_lshl_add_u64 v[36:37], v[36:37], 0, s[26:27]
	global_load_dword v164, v[36:37], off
	v_lshl_add_u64 v[36:37], v[36:37], 0, s[26:27]
	global_load_dword v166, v[36:37], off
	v_lshl_add_u64 v[36:37], v[36:37], 0, s[26:27]
	global_load_dword v168, v[36:37], off
	v_lshl_add_u64 v[36:37], v[36:37], 0, s[26:27]
	global_load_dword v170, v[36:37], off
	v_lshl_add_u64 v[36:37], v[36:37], 0, s[26:27]
	global_load_dword v172, v[36:37], off
	v_lshl_add_u64 v[36:37], v[36:37], 0, s[26:27]
	global_load_dword v174, v[36:37], off
	v_lshl_add_u64 v[36:37], v[36:37], 0, s[26:27]
	global_load_dword v176, v[36:37], off
	v_lshl_add_u64 v[36:37], v[36:37], 0, s[26:27]
	global_load_dword v178, v[36:37], off
	v_lshl_add_u64 v[36:37], v[36:37], 0, s[26:27]
	global_load_dword v180, v[36:37], off
	v_lshl_add_u64 v[36:37], v[36:37], 0, s[26:27]
	global_load_dword v182, v[36:37], off
	v_lshl_add_u64 v[36:37], v[36:37], 0, s[26:27]
	s_mov_b32 s98, 0

; __device__ void mod_item(const Params& p, int item, float* lds, int wave) {
;     ...
;         for (int kk = kg * 64; kk < kg * 64 + 64; ++kk) {
;             const float w = p.ada_w[(size_t)(half * 512 + kk) * MODW + col0 + col];
; #pragma unroll
;             for (int b = 0; b < NB; ++b) acc[b] += lds[kk * 36 + b] * w;
.Lmk_b_go:
	ds_read_b96 v[70:72], v68
	ds_read2_b32 v[38:39], v68 offset0:3 offset1:4
	ds_read2_b32 v[74:75], v68 offset0:5 offset1:6
	ds_read2_b32 v[76:77], v68 offset0:7 offset1:8
	ds_read2_b32 v[78:79], v68 offset0:9 offset1:10
	ds_read2_b32 v[80:81], v68 offset0:11 offset1:12
	ds_read2_b32 v[82:83], v68 offset0:13 offset1:14
	ds_read2_b32 v[84:85], v68 offset0:15 offset1:16
	ds_read2_b32 v[86:87], v68 offset0:17 offset1:18
	ds_read2_b32 v[88:89], v68 offset0:19 offset1:20
	ds_read2_b32 v[90:91], v68 offset0:21 offset1:22
	ds_read2_b32 v[92:93], v68 offset0:23 offset1:24
	ds_read2_b32 v[94:95], v68 offset0:25 offset1:26
	ds_read2_b32 v[96:97], v68 offset0:27 offset1:28
	ds_read2_b32 v[98:99], v68 offset0:29 offset1:30
	ds_read2_b32 v[100:101], v68 offset0:31 offset1:32
	s_waitcnt lgkmcnt(14)
	v_mov_b32_e32 v102, v71
	v_mov_b32_e32 v103, v72
	v_add_u32_e32 v68, 0x90, v68
	s_waitcnt vmcnt(15)
	v_fmac_f32_e32 v69, v152, v70
	v_pk_fma_f32 v[34:35], v[152:153], v[102:103], v[34:35] op_sel_hi:[0,1,1]
	v_pk_fma_f32 v[32:33], v[152:153], v[38:39], v[32:33] op_sel_hi:[0,1,1]
	s_waitcnt lgkmcnt(13)
	v_pk_fma_f32 v[30:31], v[152:153], v[74:75], v[30:31] op_sel_hi:[0,1,1]
	s_waitcnt lgkmcnt(12)
	v_pk_fma_f32 v[28:29], v[152:153], v[76:77], v[28:29] op_sel_hi:[0,1,1]
	s_waitcnt lgkmcnt(11)
	v_pk_fma_f32 v[26:27], v[152:153], v[78:79], v[26:27] op_sel_hi:[0,1,1]
	s_waitcnt lgkmcnt(10)
	v_pk_fma_f32 v[24:25], v[152:153], v[80:81], v[24:25] op_sel_hi:[0,1,1]
	s_waitcnt lgkmcnt(9)
	v_pk_fma_f32 v[22:23], v[152:153], v[82:83], v[22:23] op_sel_hi:[0,1,1]
	s_waitcnt lgkmcnt(8)
	v_pk_fma_f32 v[20:21], v[152:153], v[84:85], v[20:21] op_sel_hi:[0,1,1]
	s_waitcnt lgkmcnt(7)
	v_pk_fma_f32 v[18:19], v[152:153], v[86:87], v[18:19] op_sel_hi:[0,1,1]
	s_waitcnt lgkmcnt(6)
	v_pk_fma_f32 v[16:17], v[152:153], v[88:89], v[16:17] op_sel_hi:[0,1,1]
	s_waitcnt lgkmcnt(5)
	v_pk_fma_f32 v[14:15], v[152:153], v[90:91], v[14:15] op_sel_hi:[0,1,1]
	s_waitcnt lgkmcnt(4)
	v_pk_fma_f32 v[12:13], v[152:153], v[92:93], v[12:13] op_sel_hi:[0,1,1]
	s_waitcnt lgkmcnt(3)
	v_pk_fma_f32 v[10:11], v[152:153], v[94:95], v[10:11] op_sel_hi:[0,1,1]
	s_waitcnt lgkmcnt(2)
	v_pk_fma_f32 v[8:9], v[152:153], v[96:97], v[8:9] op_sel_hi:[0,1,1]
	s_waitcnt lgkmcnt(1)
	v_pk_fma_f32 v[6:7], v[152:153], v[98:99], v[6:7] op_sel_hi:[0,1,1]
	s_waitcnt lgkmcnt(0)
	v_pk_fma_f32 v[4:5], v[152:153], v[100:101], v[4:5] op_sel_hi:[0,1,1]
	s_cbranch_scc1 .Lmk_b_s0
	global_load_dword v152, v[36:37], off
	v_lshl_add_u64 v[36:37], v[36:37], 0, s[26:27]
.Lmk_b_s0:
	ds_read_b96 v[70:72], v68
	ds_read2_b32 v[38:39], v68 offset0:3 offset1:4
	ds_read2_b32 v[74:75], v68 offset0:5 offset1:6
	ds_read2_b32 v[76:77], v68 offset0:7 offset1:8
	ds_read2_b32 v[78:79], v68 offset0:9 offset1:10
	ds_read2_b32 v[80:81], v68 offset0:11 offset1:12
	ds_read2_b32 v[82:83], v68 offset0:13 offset1:14
	ds_read2_b32 v[84:85], v68 offset0:15 offset1:16
	ds_read2_b32 v[86:87], v68 offset0:17 offset1:18
	ds_read2_b32 v[88:89], v68 offset0:19 offset1:20
	ds_read2_b32 v[90:91], v68 offset0:21 offset1:22
	ds_read2_b32 v[92:93], v68 offset0:23 offset1:24
	ds_read2_b32 v[94:95], v68 offset0:25 offset1:26
	ds_read2_b32 v[96:97], v68 offset0:27 offset1:28
	ds_read2_b32 v[98:99], v68 offset0:29 offset1:30
	ds_read2_b32 v[100:101], v68 offset0:31 offset1:32
	s_waitcnt lgkmcnt(14)
	v_mov_b32_e32 v102, v71
	v_mov_b32_e32 v103, v72
	v_add_u32_e32 v68, 0x90, v68
	s_waitcnt vmcnt(15)
	v_fmac_f32_e32 v69, v154, v70
	v_pk_fma_f32 v[34:35], v[154:155], v[102:103], v[34:35] op_sel_hi:[0,1,1]
	v_pk_fma_f32 v[32:33], v[154:155], v[38:39], v[32:33] op_sel_hi:[0,1,1]
	s_waitcnt lgkmcnt(13)
	v_pk_fma_f32 v[30:31], v[154:155], v[74:75], v[30:31] op_sel_hi:[0,1,1]
	s_waitcnt lgkmcnt(12)
	v_pk_fma_f32 v[28:29], v[154:155], v[76:77], v[28:29] op_sel_hi:[0,1,1]
	s_waitcnt lgkmcnt(11)
	v_pk_fma_f32 v[26:27], v[154:155], v[78:79], v[26:27] op_sel_hi:[0,1,1]
	s_waitcnt lgkmcnt(10)
	v_pk_fma_f32 v[24:25], v[154:155], v[80:81], v[24:25] op_sel_hi:[0,1,1]
	s_waitcnt lgkmcnt(9)
	v_pk_fma_f32 v[22:23], v[154:155], v[82:83], v[22:23] op_sel_hi:[0,1,1]
	s_waitcnt lgkmcnt(8)
	v_pk_fma_f32 v[20:21], v[154:155], v[84:85], v[20:21] op_sel_hi:[0,1,1]
	s_waitcnt lgkmcnt(7)
	v_pk_fma_f32 v[18:19], v[154:155], v[86:87], v[18:19] op_sel_hi:[0,1,1]
	s_waitcnt lgkmcnt(6)
	v_pk_fma_f32 v[16:17], v[154:155], v[88:89], v[16:17] op_sel_hi:[0,1,1]
	s_waitcnt lgkmcnt(5)
	v_pk_fma_f32 v[14:15], v[154:155], v[90:91], v[14:15] op_sel_hi:[0,1,1]
	s_waitcnt lgkmcnt(4)
	v_pk_fma_f32 v[12:13], v[154:155], v[92:93], v[12:13] op_sel_hi:[0,1,1]
	s_waitcnt lgkmcnt(3)
	v_pk_fma_f32 v[10:11], v[154:155], v[94:95], v[10:11] op_sel_hi:[0,1,1]
	s_waitcnt lgkmcnt(2)
	v_pk_fma_f32 v[8:9], v[154:155], v[96:97], v[8:9] op_sel_hi:[0,1,1]
	s_waitcnt lgkmcnt(1)
	v_pk_fma_f32 v[6:7], v[154:155], v[98:99], v[6:7] op_sel_hi:[0,1,1]
	s_waitcnt lgkmcnt(0)
	v_pk_fma_f32 v[4:5], v[154:155], v[100:101], v[4:5] op_sel_hi:[0,1,1]
	s_cbranch_scc1 .Lmk_b_s1
	global_load_dword v154, v[36:37], off
	v_lshl_add_u64 v[36:37], v[36:37], 0, s[26:27]
; __device__ void mod_item(const Params& p, int item, float* lds, int wave) {
;     ...
;         for (int kk = kg * 64; kk < kg * 64 + 64; ++kk) {
;             const float w = p.ada_w[(size_t)(half * 512 + kk) * MODW + col0 + col];
; #pragma unroll
;             for (int b = 0; b < NB; ++b) acc[b] += lds[kk * 36 + b] * w;
.Lmk_b_s1:
	ds_read_b96 v[70:72], v68
	ds_read2_b32 v[38:39], v68 offset0:3 offset1:4
	ds_read2_b32 v[74:75], v68 offset0:5 offset1:6
	ds_read2_b32 v[76:77], v68 offset0:7 offset1:8
	ds_read2_b32 v[78:79], v68 offset0:9 offset1:10
	ds_read2_b32 v[80:81], v68 offset0:11 offset1:12
	ds_read2_b32 v[82:83], v68 offset0:13 offset1:14
	ds_read2_b32 v[84:85], v68 offset0:15 offset1:16
	ds_read2_b32 v[86:87], v68 offset0:17 offset1:18
	ds_read2_b32 v[88:89], v68 offset0:19 offset1:20
	ds_read2_b32 v[90:91], v68 offset0:21 offset1:22
	ds_read2_b32 v[92:93], v68 offset0:23 offset1:24
	ds_read2_b32 v[94:95], v68 offset0:25 offset1:26
	ds_read2_b32 v[96:97], v68 offset0:27 offset1:28
	ds_read2_b32 v[98:99], v68 offset0:29 offset1:30
	ds_read2_b32 v[100:101], v68 offset0:31 offset1:32
	s_waitcnt lgkmcnt(14)
	v_mov_b32_e32 v102, v71
	v_mov_b32_e32 v103, v72
	v_add_u32_e32 v68, 0x90, v68
	s_waitcnt vmcnt(15)
	v_fmac_f32_e32 v69, v156, v70
	v_pk_fma_f32 v[34:35], v[156:157], v[102:103], v[34:35] op_sel_hi:[0,1,1]
	v_pk_fma_f32 v[32:33], v[156:157], v[38:39], v[32:33] op_sel_hi:[0,1,1]
	s_waitcnt lgkmcnt(13)
	v_pk_fma_f32 v[30:31], v[156:157], v[74:75], v[30:31] op_sel_hi:[0,1,1]
	s_waitcnt lgkmcnt(12)
	v_pk_fma_f32 v[28:29], v[156:157], v[76:77], v[28:29] op_sel_hi:[0,1,1]
	s_waitcnt lgkmcnt(11)
	v_pk_fma_f32 v[26:27], v[156:157], v[78:79], v[26:27] op_sel_hi:[0,1,1]
	s_waitcnt lgkmcnt(10)
	v_pk_fma_f32 v[24:25], v[156:157], v[80:81], v[24:25] op_sel_hi:[0,1,1]
	s_waitcnt lgkmcnt(9)
	v_pk_fma_f32 v[22:23], v[156:157], v[82:83], v[22:23] op_sel_hi:[0,1,1]
	s_waitcnt lgkmcnt(8)
	v_pk_fma_f32 v[20:21], v[156:157], v[84:85], v[20:21] op_sel_hi:[0,1,1]
	s_waitcnt lgkmcnt(7)
	v_pk_fma_f32 v[18:19], v[156:157], v[86:87], v[18:19] op_sel_hi:[0,1,1]
	s_waitcnt lgkmcnt(6)
	v_pk_fma_f32 v[16:17], v[156:157], v[88:89], v[16:17] op_sel_hi:[0,1,1]
	s_waitcnt lgkmcnt(5)
	v_pk_fma_f32 v[14:15], v[156:157], v[90:91], v[14:15] op_sel_hi:[0,1,1]
	s_waitcnt lgkmcnt(4)
	v_pk_fma_f32 v[12:13], v[156:157], v[92:93], v[12:13] op_sel_hi:[0,1,1]
	s_waitcnt lgkmcnt(3)
	v_pk_fma_f32 v[10:11], v[156:157], v[94:95], v[10:11] op_sel_hi:[0,1,1]
	s_waitcnt lgkmcnt(2)
	v_pk_fma_f32 v[8:9], v[156:157], v[96:97], v[8:9] op_sel_hi:[0,1,1]
	s_waitcnt lgkmcnt(1)
	v_pk_fma_f32 v[6:7], v[156:157], v[98:99], v[6:7] op_sel_hi:[0,1,1]
	s_waitcnt lgkmcnt(0)
	v_pk_fma_f32 v[4:5], v[156:157], v[100:101], v[4:5] op_sel_hi:[0,1,1]
	s_cbranch_scc1 .Lmk_b_s2
	global_load_dword v156, v[36:37], off
	v_lshl_add_u64 v[36:37], v[36:37], 0, s[26:27]
.Lmk_b_s2:
	ds_read_b96 v[70:72], v68
	ds_read2_b32 v[38:39], v68 offset0:3 offset1:4
	ds_read2_b32 v[74:75], v68 offset0:5 offset1:6
	ds_read2_b32 v[76:77], v68 offset0:7 offset1:8
	ds_read2_b32 v[78:79], v68 offset0:9 offset1:10
	ds_read2_b32 v[80:81], v68 offset0:11 offset1:12
	ds_read2_b32 v[82:83], v68 offset0:13 offset1:14
	ds_read2_b32 v[84:85], v68 offset0:15 offset1:16
	ds_read2_b32 v[86:87], v68 offset0:17 offset1:18
	ds_read2_b32 v[88:89], v68 offset0:19 offset1:20
	ds_read2_b32 v[90:91], v68 offset0:21 offset1:22
	ds_read2_b32 v[92:93], v68 offset0:23 offset1:24
	ds_read2_b32 v[94:95], v68 offset0:25 offset1:26
	ds_read2_b32 v[96:97], v68 offset0:27 offset1:28
	ds_read2_b32 v[98:99], v68 offset0:29 offset1:30
	ds_read2_b32 v[100:101], v68 offset0:31 offset1:32
	s_waitcnt lgkmcnt(14)
	v_mov_b32_e32 v102, v71
	v_mov_b32_e32 v103, v72
	v_add_u32_e32 v68, 0x90, v68
	s_waitcnt vmcnt(15)
	v_fmac_f32_e32 v69, v158, v70
	v_pk_fma_f32 v[34:35], v[158:159], v[102:103], v[34:35] op_sel_hi:[0,1,1]
	v_pk_fma_f32 v[32:33], v[158:159], v[38:39], v[32:33] op_sel_hi:[0,1,1]
	s_waitcnt lgkmcnt(13)
	v_pk_fma_f32 v[30:31], v[158:159], v[74:75], v[30:31] op_sel_hi:[0,1,1]
	s_waitcnt lgkmcnt(12)
	v_pk_fma_f32 v[28:29], v[158:159], v[76:77], v[28:29] op_sel_hi:[0,1,1]
	s_waitcnt lgkmcnt(11)
	v_pk_fma_f32 v[26:27], v[158:159], v[78:79], v[26:27] op_sel_hi:[0,1,1]
	s_waitcnt lgkmcnt(10)
	v_pk_fma_f32 v[24:25], v[158:159], v[80:81], v[24:25] op_sel_hi:[0,1,1]
	s_waitcnt lgkmcnt(9)
	v_pk_fma_f32 v[22:23], v[158:159], v[82:83], v[22:23] op_sel_hi:[0,1,1]
	s_waitcnt lgkmcnt(8)
	v_pk_fma_f32 v[20:21], v[158:159], v[84:85], v[20:21] op_sel_hi:[0,1,1]
	s_waitcnt lgkmcnt(7)
	v_pk_fma_f32 v[18:19], v[158:159], v[86:87], v[18:19] op_sel_hi:[0,1,1]
	s_waitcnt lgkmcnt(6)
	v_pk_fma_f32 v[16:17], v[158:159], v[88:89], v[16:17] op_sel_hi:[0,1,1]
	s_waitcnt lgkmcnt(5)
	v_pk_fma_f32 v[14:15], v[158:159], v[90:91], v[14:15] op_sel_hi:[0,1,1]
	s_waitcnt lgkmcnt(4)
	v_pk_fma_f32 v[12:13], v[158:159], v[92:93], v[12:13] op_sel_hi:[0,1,1]
	s_waitcnt lgkmcnt(3)
	v_pk_fma_f32 v[10:11], v[158:159], v[94:95], v[10:11] op_sel_hi:[0,1,1]
	s_waitcnt lgkmcnt(2)
	v_pk_fma_f32 v[8:9], v[158:159], v[96:97], v[8:9] op_sel_hi:[0,1,1]
	s_waitcnt lgkmcnt(1)
	v_pk_fma_f32 v[6:7], v[158:159], v[98:99], v[6:7] op_sel_hi:[0,1,1]
	s_waitcnt lgkmcnt(0)
	v_pk_fma_f32 v[4:5], v[158:159], v[100:101], v[4:5] op_sel_hi:[0,1,1]
	s_cbranch_scc1 .Lmk_b_s3
	global_load_dword v158, v[36:37], off
	v_lshl_add_u64 v[36:37], v[36:37], 0, s[26:27]
; __device__ void mod_item(const Params& p, int item, float* lds, int wave) {
;     ...
;         for (int kk = kg * 64; kk < kg * 64 + 64; ++kk) {
;             const float w = p.ada_w[(size_t)(half * 512 + kk) * MODW + col0 + col];
; #pragma unroll
;             for (int b = 0; b < NB; ++b) acc[b] += lds[kk * 36 + b] * w;
.Lmk_b_s3:
	ds_read_b96 v[70:72], v68
	ds_read2_b32 v[38:39], v68 offset0:3 offset1:4
	ds_read2_b32 v[74:75], v68 offset0:5 offset1:6
	ds_read2_b32 v[76:77], v68 offset0:7 offset1:8
	ds_read2_b32 v[78:79], v68 offset0:9 offset1:10
	ds_read2_b32 v[80:81], v68 offset0:11 offset1:12
	ds_read2_b32 v[82:83], v68 offset0:13 offset1:14
	ds_read2_b32 v[84:85], v68 offset0:15 offset1:16
	ds_read2_b32 v[86:87], v68 offset0:17 offset1:18
	ds_read2_b32 v[88:89], v68 offset0:19 offset1:20
	ds_read2_b32 v[90:91], v68 offset0:21 offset1:22
	ds_read2_b32 v[92:93], v68 offset0:23 offset1:24
	ds_read2_b32 v[94:95], v68 offset0:25 offset1:26
	ds_read2_b32 v[96:97], v68 offset0:27 offset1:28
	ds_read2_b32 v[98:99], v68 offset0:29 offset1:30
	ds_read2_b32 v[100:101], v68 offset0:31 offset1:32
	s_waitcnt lgkmcnt(14)
	v_mov_b32_e32 v102, v71
	v_mov_b32_e32 v103, v72
	v_add_u32_e32 v68, 0x90, v68
	s_waitcnt vmcnt(15)
	v_fmac_f32_e32 v69, v160, v70
	v_pk_fma_f32 v[34:35], v[160:161], v[102:103], v[34:35] op_sel_hi:[0,1,1]
	v_pk_fma_f32 v[32:33], v[160:161], v[38:39], v[32:33] op_sel_hi:[0,1,1]
	s_waitcnt lgkmcnt(13)
	v_pk_fma_f32 v[30:31], v[160:161], v[74:75], v[30:31] op_sel_hi:[0,1,1]
	s_waitcnt lgkmcnt(12)
	v_pk_fma_f32 v[28:29], v[160:161], v[76:77], v[28:29] op_sel_hi:[0,1,1]
	s_waitcnt lgkmcnt(11)
	v_pk_fma_f32 v[26:27], v[160:161], v[78:79], v[26:27] op_sel_hi:[0,1,1]
	s_waitcnt lgkmcnt(10)
	v_pk_fma_f32 v[24:25], v[160:161], v[80:81], v[24:25] op_sel_hi:[0,1,1]
	s_waitcnt lgkmcnt(9)
	v_pk_fma_f32 v[22:23], v[160:161], v[82:83], v[22:23] op_sel_hi:[0,1,1]
	s_waitcnt lgkmcnt(8)
	v_pk_fma_f32 v[20:21], v[160:161], v[84:85], v[20:21] op_sel_hi:[0,1,1]
	s_waitcnt lgkmcnt(7)
	v_pk_fma_f32 v[18:19], v[160:161], v[86:87], v[18:19] op_sel_hi:[0,1,1]
	s_waitcnt lgkmcnt(6)
	v_pk_fma_f32 v[16:17], v[160:161], v[88:89], v[16:17] op_sel_hi:[0,1,1]
	s_waitcnt lgkmcnt(5)
	v_pk_fma_f32 v[14:15], v[160:161], v[90:91], v[14:15] op_sel_hi:[0,1,1]
	s_waitcnt lgkmcnt(4)
	v_pk_fma_f32 v[12:13], v[160:161], v[92:93], v[12:13] op_sel_hi:[0,1,1]
	s_waitcnt lgkmcnt(3)
	v_pk_fma_f32 v[10:11], v[160:161], v[94:95], v[10:11] op_sel_hi:[0,1,1]
	s_waitcnt lgkmcnt(2)
	v_pk_fma_f32 v[8:9], v[160:161], v[96:97], v[8:9] op_sel_hi:[0,1,1]
	s_waitcnt lgkmcnt(1)
	v_pk_fma_f32 v[6:7], v[160:161], v[98:99], v[6:7] op_sel_hi:[0,1,1]
	s_waitcnt lgkmcnt(0)
	v_pk_fma_f32 v[4:5], v[160:161], v[100:101], v[4:5] op_sel_hi:[0,1,1]
	s_cbranch_scc1 .Lmk_b_s4
	global_load_dword v160, v[36:37], off
	v_lshl_add_u64 v[36:37], v[36:37], 0, s[26:27]
.Lmk_b_s4:
	ds_read_b96 v[70:72], v68
	ds_read2_b32 v[38:39], v68 offset0:3 offset1:4
	ds_read2_b32 v[74:75], v68 offset0:5 offset1:6
	ds_read2_b32 v[76:77], v68 offset0:7 offset1:8
	ds_read2_b32 v[78:79], v68 offset0:9 offset1:10
	ds_read2_b32 v[80:81], v68 offset0:11 offset1:12
	ds_read2_b32 v[82:83], v68 offset0:13 offset1:14
	ds_read2_b32 v[84:85], v68 offset0:15 offset1:16
	ds_read2_b32 v[86:87], v68 offset0:17 offset1:18
	ds_read2_b32 v[88:89], v68 offset0:19 offset1:20
	ds_read2_b32 v[90:91], v68 offset0:21 offset1:22
	ds_read2_b32 v[92:93], v68 offset0:23 offset1:24
	ds_read2_b32 v[94:95], v68 offset0:25 offset1:26
	ds_read2_b32 v[96:97], v68 offset0:27 offset1:28
	ds_read2_b32 v[98:99], v68 offset0:29 offset1:30
	ds_read2_b32 v[100:101], v68 offset0:31 offset1:32
	s_waitcnt lgkmcnt(14)
	v_mov_b32_e32 v102, v71
	v_mov_b32_e32 v103, v72
	v_add_u32_e32 v68, 0x90, v68
	s_waitcnt vmcnt(15)
	v_fmac_f32_e32 v69, v162, v70
	v_pk_fma_f32 v[34:35], v[162:163], v[102:103], v[34:35] op_sel_hi:[0,1,1]
	v_pk_fma_f32 v[32:33], v[162:163], v[38:39], v[32:33] op_sel_hi:[0,1,1]
	s_waitcnt lgkmcnt(13)
	v_pk_fma_f32 v[30:31], v[162:163], v[74:75], v[30:31] op_sel_hi:[0,1,1]
	s_waitcnt lgkmcnt(12)
	v_pk_fma_f32 v[28:29], v[162:163], v[76:77], v[28:29] op_sel_hi:[0,1,1]
	s_waitcnt lgkmcnt(11)
	v_pk_fma_f32 v[26:27], v[162:163], v[78:79], v[26:27] op_sel_hi:[0,1,1]
	s_waitcnt lgkmcnt(10)
	v_pk_fma_f32 v[24:25], v[162:163], v[80:81], v[24:25] op_sel_hi:[0,1,1]
	s_waitcnt lgkmcnt(9)
	v_pk_fma_f32 v[22:23], v[162:163], v[82:83], v[22:23] op_sel_hi:[0,1,1]
	s_waitcnt lgkmcnt(8)
	v_pk_fma_f32 v[20:21], v[162:163], v[84:85], v[20:21] op_sel_hi:[0,1,1]
	s_waitcnt lgkmcnt(7)
	v_pk_fma_f32 v[18:19], v[162:163], v[86:87], v[18:19] op_sel_hi:[0,1,1]
	s_waitcnt lgkmcnt(6)
	v_pk_fma_f32 v[16:17], v[162:163], v[88:89], v[16:17] op_sel_hi:[0,1,1]
	s_waitcnt lgkmcnt(5)
	v_pk_fma_f32 v[14:15], v[162:163], v[90:91], v[14:15] op_sel_hi:[0,1,1]
	s_waitcnt lgkmcnt(4)
	v_pk_fma_f32 v[12:13], v[162:163], v[92:93], v[12:13] op_sel_hi:[0,1,1]
	s_waitcnt lgkmcnt(3)
	v_pk_fma_f32 v[10:11], v[162:163], v[94:95], v[10:11] op_sel_hi:[0,1,1]
	s_waitcnt lgkmcnt(2)
	v_pk_fma_f32 v[8:9], v[162:163], v[96:97], v[8:9] op_sel_hi:[0,1,1]
	s_waitcnt lgkmcnt(1)
	v_pk_fma_f32 v[6:7], v[162:163], v[98:99], v[6:7] op_sel_hi:[0,1,1]
	s_waitcnt lgkmcnt(0)
	v_pk_fma_f32 v[4:5], v[162:163], v[100:101], v[4:5] op_sel_hi:[0,1,1]
	s_cbranch_scc1 .Lmk_b_s5
	global_load_dword v162, v[36:37], off
	v_lshl_add_u64 v[36:37], v[36:37], 0, s[26:27]
; __device__ void mod_item(const Params& p, int item, float* lds, int wave) {
;     ...
;         for (int kk = kg * 64; kk < kg * 64 + 64; ++kk) {
;             const float w = p.ada_w[(size_t)(half * 512 + kk) * MODW + col0 + col];
; #pragma unroll
;             for (int b = 0; b < NB; ++b) acc[b] += lds[kk * 36 + b] * w;
.Lmk_b_s5:
	ds_read_b96 v[70:72], v68
	ds_read2_b32 v[38:39], v68 offset0:3 offset1:4
	ds_read2_b32 v[74:75], v68 offset0:5 offset1:6
	ds_read2_b32 v[76:77], v68 offset0:7 offset1:8
	ds_read2_b32 v[78:79], v68 offset0:9 offset1:10
	ds_read2_b32 v[80:81], v68 offset0:11 offset1:12
	ds_read2_b32 v[82:83], v68 offset0:13 offset1:14
	ds_read2_b32 v[84:85], v68 offset0:15 offset1:16
	ds_read2_b32 v[86:87], v68 offset0:17 offset1:18
	ds_read2_b32 v[88:89], v68 offset0:19 offset1:20
	ds_read2_b32 v[90:91], v68 offset0:21 offset1:22
	ds_read2_b32 v[92:93], v68 offset0:23 offset1:24
	ds_read2_b32 v[94:95], v68 offset0:25 offset1:26
	ds_read2_b32 v[96:97], v68 offset0:27 offset1:28
	ds_read2_b32 v[98:99], v68 offset0:29 offset1:30
	ds_read2_b32 v[100:101], v68 offset0:31 offset1:32
	s_waitcnt lgkmcnt(14)
	v_mov_b32_e32 v102, v71
	v_mov_b32_e32 v103, v72
	v_add_u32_e32 v68, 0x90, v68
	s_waitcnt vmcnt(15)
	v_fmac_f32_e32 v69, v164, v70
	v_pk_fma_f32 v[34:35], v[164:165], v[102:103], v[34:35] op_sel_hi:[0,1,1]
	v_pk_fma_f32 v[32:33], v[164:165], v[38:39], v[32:33] op_sel_hi:[0,1,1]
	s_waitcnt lgkmcnt(13)
	v_pk_fma_f32 v[30:31], v[164:165], v[74:75], v[30:31] op_sel_hi:[0,1,1]
	s_waitcnt lgkmcnt(12)
	v_pk_fma_f32 v[28:29], v[164:165], v[76:77], v[28:29] op_sel_hi:[0,1,1]
	s_waitcnt lgkmcnt(11)
	v_pk_fma_f32 v[26:27], v[164:165], v[78:79], v[26:27] op_sel_hi:[0,1,1]
	s_waitcnt lgkmcnt(10)
	v_pk_fma_f32 v[24:25], v[164:165], v[80:81], v[24:25] op_sel_hi:[0,1,1]
	s_waitcnt lgkmcnt(9)
	v_pk_fma_f32 v[22:23], v[164:165], v[82:83], v[22:23] op_sel_hi:[0,1,1]
	s_waitcnt lgkmcnt(8)
	v_pk_fma_f32 v[20:21], v[164:165], v[84:85], v[20:21] op_sel_hi:[0,1,1]
	s_waitcnt lgkmcnt(7)
	v_pk_fma_f32 v[18:19], v[164:165], v[86:87], v[18:19] op_sel_hi:[0,1,1]
	s_waitcnt lgkmcnt(6)
	v_pk_fma_f32 v[16:17], v[164:165], v[88:89], v[16:17] op_sel_hi:[0,1,1]
	s_waitcnt lgkmcnt(5)
	v_pk_fma_f32 v[14:15], v[164:165], v[90:91], v[14:15] op_sel_hi:[0,1,1]
	s_waitcnt lgkmcnt(4)
	v_pk_fma_f32 v[12:13], v[164:165], v[92:93], v[12:13] op_sel_hi:[0,1,1]
	s_waitcnt lgkmcnt(3)
	v_pk_fma_f32 v[10:11], v[164:165], v[94:95], v[10:11] op_sel_hi:[0,1,1]
	s_waitcnt lgkmcnt(2)
	v_pk_fma_f32 v[8:9], v[164:165], v[96:97], v[8:9] op_sel_hi:[0,1,1]
	s_waitcnt lgkmcnt(1)
	v_pk_fma_f32 v[6:7], v[164:165], v[98:99], v[6:7] op_sel_hi:[0,1,1]
	s_waitcnt lgkmcnt(0)
	v_pk_fma_f32 v[4:5], v[164:165], v[100:101], v[4:5] op_sel_hi:[0,1,1]
	s_cbranch_scc1 .Lmk_b_s6
	global_load_dword v164, v[36:37], off
	v_lshl_add_u64 v[36:37], v[36:37], 0, s[26:27]
.Lmk_b_s6:
	ds_read_b96 v[70:72], v68
	ds_read2_b32 v[38:39], v68 offset0:3 offset1:4
	ds_read2_b32 v[74:75], v68 offset0:5 offset1:6
	ds_read2_b32 v[76:77], v68 offset0:7 offset1:8
	ds_read2_b32 v[78:79], v68 offset0:9 offset1:10
	ds_read2_b32 v[80:81], v68 offset0:11 offset1:12
	ds_read2_b32 v[82:83], v68 offset0:13 offset1:14
	ds_read2_b32 v[84:85], v68 offset0:15 offset1:16
	ds_read2_b32 v[86:87], v68 offset0:17 offset1:18
	ds_read2_b32 v[88:89], v68 offset0:19 offset1:20
	ds_read2_b32 v[90:91], v68 offset0:21 offset1:22
	ds_read2_b32 v[92:93], v68 offset0:23 offset1:24
	ds_read2_b32 v[94:95], v68 offset0:25 offset1:26
	ds_read2_b32 v[96:97], v68 offset0:27 offset1:28
	ds_read2_b32 v[98:99], v68 offset0:29 offset1:30
	ds_read2_b32 v[100:101], v68 offset0:31 offset1:32
	s_waitcnt lgkmcnt(14)
	v_mov_b32_e32 v102, v71
	v_mov_b32_e32 v103, v72
	v_add_u32_e32 v68, 0x90, v68
	s_waitcnt vmcnt(15)
	v_fmac_f32_e32 v69, v166, v70
	v_pk_fma_f32 v[34:35], v[166:167], v[102:103], v[34:35] op_sel_hi:[0,1,1]
	v_pk_fma_f32 v[32:33], v[166:167], v[38:39], v[32:33] op_sel_hi:[0,1,1]
	s_waitcnt lgkmcnt(13)
	v_pk_fma_f32 v[30:31], v[166:167], v[74:75], v[30:31] op_sel_hi:[0,1,1]
	s_waitcnt lgkmcnt(12)
	v_pk_fma_f32 v[28:29], v[166:167], v[76:77], v[28:29] op_sel_hi:[0,1,1]
	s_waitcnt lgkmcnt(11)
	v_pk_fma_f32 v[26:27], v[166:167], v[78:79], v[26:27] op_sel_hi:[0,1,1]
	s_waitcnt lgkmcnt(10)
	v_pk_fma_f32 v[24:25], v[166:167], v[80:81], v[24:25] op_sel_hi:[0,1,1]
	s_waitcnt lgkmcnt(9)
	v_pk_fma_f32 v[22:23], v[166:167], v[82:83], v[22:23] op_sel_hi:[0,1,1]
	s_waitcnt lgkmcnt(8)
	v_pk_fma_f32 v[20:21], v[166:167], v[84:85], v[20:21] op_sel_hi:[0,1,1]
	s_waitcnt lgkmcnt(7)
	v_pk_fma_f32 v[18:19], v[166:167], v[86:87], v[18:19] op_sel_hi:[0,1,1]
	s_waitcnt lgkmcnt(6)
	v_pk_fma_f32 v[16:17], v[166:167], v[88:89], v[16:17] op_sel_hi:[0,1,1]
	s_waitcnt lgkmcnt(5)
	v_pk_fma_f32 v[14:15], v[166:167], v[90:91], v[14:15] op_sel_hi:[0,1,1]
	s_waitcnt lgkmcnt(4)
	v_pk_fma_f32 v[12:13], v[166:167], v[92:93], v[12:13] op_sel_hi:[0,1,1]
	s_waitcnt lgkmcnt(3)
	v_pk_fma_f32 v[10:11], v[166:167], v[94:95], v[10:11] op_sel_hi:[0,1,1]
	s_waitcnt lgkmcnt(2)
	v_pk_fma_f32 v[8:9], v[166:167], v[96:97], v[8:9] op_sel_hi:[0,1,1]
	s_waitcnt lgkmcnt(1)
	v_pk_fma_f32 v[6:7], v[166:167], v[98:99], v[6:7] op_sel_hi:[0,1,1]
	s_waitcnt lgkmcnt(0)
	v_pk_fma_f32 v[4:5], v[166:167], v[100:101], v[4:5] op_sel_hi:[0,1,1]
	s_cbranch_scc1 .Lmk_b_s7
	global_load_dword v166, v[36:37], off
	v_lshl_add_u64 v[36:37], v[36:37], 0, s[26:27]
; __device__ void mod_item(const Params& p, int item, float* lds, int wave) {
;     ...
;         for (int kk = kg * 64; kk < kg * 64 + 64; ++kk) {
;             const float w = p.ada_w[(size_t)(half * 512 + kk) * MODW + col0 + col];
; #pragma unroll
;             for (int b = 0; b < NB; ++b) acc[b] += lds[kk * 36 + b] * w;
.Lmk_b_s7:
	ds_read_b96 v[70:72], v68
	ds_read2_b32 v[38:39], v68 offset0:3 offset1:4
	ds_read2_b32 v[74:75], v68 offset0:5 offset1:6
	ds_read2_b32 v[76:77], v68 offset0:7 offset1:8
	ds_read2_b32 v[78:79], v68 offset0:9 offset1:10
	ds_read2_b32 v[80:81], v68 offset0:11 offset1:12
	ds_read2_b32 v[82:83], v68 offset0:13 offset1:14
	ds_read2_b32 v[84:85], v68 offset0:15 offset1:16
	ds_read2_b32 v[86:87], v68 offset0:17 offset1:18
	ds_read2_b32 v[88:89], v68 offset0:19 offset1:20
	ds_read2_b32 v[90:91], v68 offset0:21 offset1:22
	ds_read2_b32 v[92:93], v68 offset0:23 offset1:24
	ds_read2_b32 v[94:95], v68 offset0:25 offset1:26
	ds_read2_b32 v[96:97], v68 offset0:27 offset1:28
	ds_read2_b32 v[98:99], v68 offset0:29 offset1:30
	ds_read2_b32 v[100:101], v68 offset0:31 offset1:32
	s_waitcnt lgkmcnt(14)
	v_mov_b32_e32 v102, v71
	v_mov_b32_e32 v103, v72
	v_add_u32_e32 v68, 0x90, v68
	s_waitcnt vmcnt(15)
	v_fmac_f32_e32 v69, v168, v70
	v_pk_fma_f32 v[34:35], v[168:169], v[102:103], v[34:35] op_sel_hi:[0,1,1]
	v_pk_fma_f32 v[32:33], v[168:169], v[38:39], v[32:33] op_sel_hi:[0,1,1]
	s_waitcnt lgkmcnt(13)
	v_pk_fma_f32 v[30:31], v[168:169], v[74:75], v[30:31] op_sel_hi:[0,1,1]
	s_waitcnt lgkmcnt(12)
	v_pk_fma_f32 v[28:29], v[168:169], v[76:77], v[28:29] op_sel_hi:[0,1,1]
	s_waitcnt lgkmcnt(11)
	v_pk_fma_f32 v[26:27], v[168:169], v[78:79], v[26:27] op_sel_hi:[0,1,1]
	s_waitcnt lgkmcnt(10)
	v_pk_fma_f32 v[24:25], v[168:169], v[80:81], v[24:25] op_sel_hi:[0,1,1]
	s_waitcnt lgkmcnt(9)
	v_pk_fma_f32 v[22:23], v[168:169], v[82:83], v[22:23] op_sel_hi:[0,1,1]
	s_waitcnt lgkmcnt(8)
	v_pk_fma_f32 v[20:21], v[168:169], v[84:85], v[20:21] op_sel_hi:[0,1,1]
	s_waitcnt lgkmcnt(7)
	v_pk_fma_f32 v[18:19], v[168:169], v[86:87], v[18:19] op_sel_hi:[0,1,1]
	s_waitcnt lgkmcnt(6)
	v_pk_fma_f32 v[16:17], v[168:169], v[88:89], v[16:17] op_sel_hi:[0,1,1]
	s_waitcnt lgkmcnt(5)
	v_pk_fma_f32 v[14:15], v[168:169], v[90:91], v[14:15] op_sel_hi:[0,1,1]
	s_waitcnt lgkmcnt(4)
	v_pk_fma_f32 v[12:13], v[168:169], v[92:93], v[12:13] op_sel_hi:[0,1,1]
	s_waitcnt lgkmcnt(3)
	v_pk_fma_f32 v[10:11], v[168:169], v[94:95], v[10:11] op_sel_hi:[0,1,1]
	s_waitcnt lgkmcnt(2)
	v_pk_fma_f32 v[8:9], v[168:169], v[96:97], v[8:9] op_sel_hi:[0,1,1]
	s_waitcnt lgkmcnt(1)
	v_pk_fma_f32 v[6:7], v[168:169], v[98:99], v[6:7] op_sel_hi:[0,1,1]
	s_waitcnt lgkmcnt(0)
	v_pk_fma_f32 v[4:5], v[168:169], v[100:101], v[4:5] op_sel_hi:[0,1,1]
	s_cbranch_scc1 .Lmk_b_s8
	global_load_dword v168, v[36:37], off
	v_lshl_add_u64 v[36:37], v[36:37], 0, s[26:27]
.Lmk_b_s8:
	ds_read_b96 v[70:72], v68
	ds_read2_b32 v[38:39], v68 offset0:3 offset1:4
	ds_read2_b32 v[74:75], v68 offset0:5 offset1:6
	ds_read2_b32 v[76:77], v68 offset0:7 offset1:8
	ds_read2_b32 v[78:79], v68 offset0:9 offset1:10
	ds_read2_b32 v[80:81], v68 offset0:11 offset1:12
	ds_read2_b32 v[82:83], v68 offset0:13 offset1:14
	ds_read2_b32 v[84:85], v68 offset0:15 offset1:16
	ds_read2_b32 v[86:87], v68 offset0:17 offset1:18
	ds_read2_b32 v[88:89], v68 offset0:19 offset1:20
	ds_read2_b32 v[90:91], v68 offset0:21 offset1:22
	ds_read2_b32 v[92:93], v68 offset0:23 offset1:24
	ds_read2_b32 v[94:95], v68 offset0:25 offset1:26
	ds_read2_b32 v[96:97], v68 offset0:27 offset1:28
	ds_read2_b32 v[98:99], v68 offset0:29 offset1:30
	ds_read2_b32 v[100:101], v68 offset0:31 offset1:32
	s_waitcnt lgkmcnt(14)
	v_mov_b32_e32 v102, v71
	v_mov_b32_e32 v103, v72
	v_add_u32_e32 v68, 0x90, v68
	s_waitcnt vmcnt(15)
	v_fmac_f32_e32 v69, v170, v70
	v_pk_fma_f32 v[34:35], v[170:171], v[102:103], v[34:35] op_sel_hi:[0,1,1]
	v_pk_fma_f32 v[32:33], v[170:171], v[38:39], v[32:33] op_sel_hi:[0,1,1]
	s_waitcnt lgkmcnt(13)
	v_pk_fma_f32 v[30:31], v[170:171], v[74:75], v[30:31] op_sel_hi:[0,1,1]
	s_waitcnt lgkmcnt(12)
	v_pk_fma_f32 v[28:29], v[170:171], v[76:77], v[28:29] op_sel_hi:[0,1,1]
	s_waitcnt lgkmcnt(11)
	v_pk_fma_f32 v[26:27], v[170:171], v[78:79], v[26:27] op_sel_hi:[0,1,1]
	s_waitcnt lgkmcnt(10)
	v_pk_fma_f32 v[24:25], v[170:171], v[80:81], v[24:25] op_sel_hi:[0,1,1]
	s_waitcnt lgkmcnt(9)
	v_pk_fma_f32 v[22:23], v[170:171], v[82:83], v[22:23] op_sel_hi:[0,1,1]
	s_waitcnt lgkmcnt(8)
	v_pk_fma_f32 v[20:21], v[170:171], v[84:85], v[20:21] op_sel_hi:[0,1,1]
	s_waitcnt lgkmcnt(7)
	v_pk_fma_f32 v[18:19], v[170:171], v[86:87], v[18:19] op_sel_hi:[0,1,1]
	s_waitcnt lgkmcnt(6)
	v_pk_fma_f32 v[16:17], v[170:171], v[88:89], v[16:17] op_sel_hi:[0,1,1]
	s_waitcnt lgkmcnt(5)
	v_pk_fma_f32 v[14:15], v[170:171], v[90:91], v[14:15] op_sel_hi:[0,1,1]
	s_waitcnt lgkmcnt(4)
	v_pk_fma_f32 v[12:13], v[170:171], v[92:93], v[12:13] op_sel_hi:[0,1,1]
	s_waitcnt lgkmcnt(3)
	v_pk_fma_f32 v[10:11], v[170:171], v[94:95], v[10:11] op_sel_hi:[0,1,1]
	s_waitcnt lgkmcnt(2)
	v_pk_fma_f32 v[8:9], v[170:171], v[96:97], v[8:9] op_sel_hi:[0,1,1]
	s_waitcnt lgkmcnt(1)
	v_pk_fma_f32 v[6:7], v[170:171], v[98:99], v[6:7] op_sel_hi:[0,1,1]
	s_waitcnt lgkmcnt(0)
	v_pk_fma_f32 v[4:5], v[170:171], v[100:101], v[4:5] op_sel_hi:[0,1,1]
	s_cbranch_scc1 .Lmk_b_s9
	global_load_dword v170, v[36:37], off
	v_lshl_add_u64 v[36:37], v[36:37], 0, s[26:27]
; __device__ void mod_item(const Params& p, int item, float* lds, int wave) {
;     ...
;         for (int kk = kg * 64; kk < kg * 64 + 64; ++kk) {
;             const float w = p.ada_w[(size_t)(half * 512 + kk) * MODW + col0 + col];
; #pragma unroll
;             for (int b = 0; b < NB; ++b) acc[b] += lds[kk * 36 + b] * w;
.Lmk_b_s9:
	ds_read_b96 v[70:72], v68
	ds_read2_b32 v[38:39], v68 offset0:3 offset1:4
	ds_read2_b32 v[74:75], v68 offset0:5 offset1:6
	ds_read2_b32 v[76:77], v68 offset0:7 offset1:8
	ds_read2_b32 v[78:79], v68 offset0:9 offset1:10
	ds_read2_b32 v[80:81], v68 offset0:11 offset1:12
	ds_read2_b32 v[82:83], v68 offset0:13 offset1:14
	ds_read2_b32 v[84:85], v68 offset0:15 offset1:16
	ds_read2_b32 v[86:87], v68 offset0:17 offset1:18
	ds_read2_b32 v[88:89], v68 offset0:19 offset1:20
	ds_read2_b32 v[90:91], v68 offset0:21 offset1:22
	ds_read2_b32 v[92:93], v68 offset0:23 offset1:24
	ds_read2_b32 v[94:95], v68 offset0:25 offset1:26
	ds_read2_b32 v[96:97], v68 offset0:27 offset1:28
	ds_read2_b32 v[98:99], v68 offset0:29 offset1:30
	ds_read2_b32 v[100:101], v68 offset0:31 offset1:32
	s_waitcnt lgkmcnt(14)
	v_mov_b32_e32 v102, v71
	v_mov_b32_e32 v103, v72
	v_add_u32_e32 v68, 0x90, v68
	s_waitcnt vmcnt(15)
	v_fmac_f32_e32 v69, v172, v70
	v_pk_fma_f32 v[34:35], v[172:173], v[102:103], v[34:35] op_sel_hi:[0,1,1]
	v_pk_fma_f32 v[32:33], v[172:173], v[38:39], v[32:33] op_sel_hi:[0,1,1]
	s_waitcnt lgkmcnt(13)
	v_pk_fma_f32 v[30:31], v[172:173], v[74:75], v[30:31] op_sel_hi:[0,1,1]
	s_waitcnt lgkmcnt(12)
	v_pk_fma_f32 v[28:29], v[172:173], v[76:77], v[28:29] op_sel_hi:[0,1,1]
	s_waitcnt lgkmcnt(11)
	v_pk_fma_f32 v[26:27], v[172:173], v[78:79], v[26:27] op_sel_hi:[0,1,1]
	s_waitcnt lgkmcnt(10)
	v_pk_fma_f32 v[24:25], v[172:173], v[80:81], v[24:25] op_sel_hi:[0,1,1]
	s_waitcnt lgkmcnt(9)
	v_pk_fma_f32 v[22:23], v[172:173], v[82:83], v[22:23] op_sel_hi:[0,1,1]
	s_waitcnt lgkmcnt(8)
	v_pk_fma_f32 v[20:21], v[172:173], v[84:85], v[20:21] op_sel_hi:[0,1,1]
	s_waitcnt lgkmcnt(7)
	v_pk_fma_f32 v[18:19], v[172:173], v[86:87], v[18:19] op_sel_hi:[0,1,1]
	s_waitcnt lgkmcnt(6)
	v_pk_fma_f32 v[16:17], v[172:173], v[88:89], v[16:17] op_sel_hi:[0,1,1]
	s_waitcnt lgkmcnt(5)
	v_pk_fma_f32 v[14:15], v[172:173], v[90:91], v[14:15] op_sel_hi:[0,1,1]
	s_waitcnt lgkmcnt(4)
	v_pk_fma_f32 v[12:13], v[172:173], v[92:93], v[12:13] op_sel_hi:[0,1,1]
	s_waitcnt lgkmcnt(3)
	v_pk_fma_f32 v[10:11], v[172:173], v[94:95], v[10:11] op_sel_hi:[0,1,1]
	s_waitcnt lgkmcnt(2)
	v_pk_fma_f32 v[8:9], v[172:173], v[96:97], v[8:9] op_sel_hi:[0,1,1]
	s_waitcnt lgkmcnt(1)
	v_pk_fma_f32 v[6:7], v[172:173], v[98:99], v[6:7] op_sel_hi:[0,1,1]
	s_waitcnt lgkmcnt(0)
	v_pk_fma_f32 v[4:5], v[172:173], v[100:101], v[4:5] op_sel_hi:[0,1,1]
	s_cbranch_scc1 .Lmk_b_s10
	global_load_dword v172, v[36:37], off
	v_lshl_add_u64 v[36:37], v[36:37], 0, s[26:27]
.Lmk_b_s10:
	ds_read_b96 v[70:72], v68
	ds_read2_b32 v[38:39], v68 offset0:3 offset1:4
	ds_read2_b32 v[74:75], v68 offset0:5 offset1:6
	ds_read2_b32 v[76:77], v68 offset0:7 offset1:8
	ds_read2_b32 v[78:79], v68 offset0:9 offset1:10
	ds_read2_b32 v[80:81], v68 offset0:11 offset1:12
	ds_read2_b32 v[82:83], v68 offset0:13 offset1:14
	ds_read2_b32 v[84:85], v68 offset0:15 offset1:16
	ds_read2_b32 v[86:87], v68 offset0:17 offset1:18
	ds_read2_b32 v[88:89], v68 offset0:19 offset1:20
	ds_read2_b32 v[90:91], v68 offset0:21 offset1:22
	ds_read2_b32 v[92:93], v68 offset0:23 offset1:24
	ds_read2_b32 v[94:95], v68 offset0:25 offset1:26
	ds_read2_b32 v[96:97], v68 offset0:27 offset1:28
	ds_read2_b32 v[98:99], v68 offset0:29 offset1:30
	ds_read2_b32 v[100:101], v68 offset0:31 offset1:32
	s_waitcnt lgkmcnt(14)
	v_mov_b32_e32 v102, v71
	v_mov_b32_e32 v103, v72
	v_add_u32_e32 v68, 0x90, v68
	s_waitcnt vmcnt(15)
	v_fmac_f32_e32 v69, v174, v70
	v_pk_fma_f32 v[34:35], v[174:175], v[102:103], v[34:35] op_sel_hi:[0,1,1]
	v_pk_fma_f32 v[32:33], v[174:175], v[38:39], v[32:33] op_sel_hi:[0,1,1]
	s_waitcnt lgkmcnt(13)
	v_pk_fma_f32 v[30:31], v[174:175], v[74:75], v[30:31] op_sel_hi:[0,1,1]
	s_waitcnt lgkmcnt(12)
	v_pk_fma_f32 v[28:29], v[174:175], v[76:77], v[28:29] op_sel_hi:[0,1,1]
	s_waitcnt lgkmcnt(11)
	v_pk_fma_f32 v[26:27], v[174:175], v[78:79], v[26:27] op_sel_hi:[0,1,1]
	s_waitcnt lgkmcnt(10)
	v_pk_fma_f32 v[24:25], v[174:175], v[80:81], v[24:25] op_sel_hi:[0,1,1]
	s_waitcnt lgkmcnt(9)
	v_pk_fma_f32 v[22:23], v[174:175], v[82:83], v[22:23] op_sel_hi:[0,1,1]
	s_waitcnt lgkmcnt(8)
	v_pk_fma_f32 v[20:21], v[174:175], v[84:85], v[20:21] op_sel_hi:[0,1,1]
	s_waitcnt lgkmcnt(7)
	v_pk_fma_f32 v[18:19], v[174:175], v[86:87], v[18:19] op_sel_hi:[0,1,1]
	s_waitcnt lgkmcnt(6)
	v_pk_fma_f32 v[16:17], v[174:175], v[88:89], v[16:17] op_sel_hi:[0,1,1]
	s_waitcnt lgkmcnt(5)
	v_pk_fma_f32 v[14:15], v[174:175], v[90:91], v[14:15] op_sel_hi:[0,1,1]
	s_waitcnt lgkmcnt(4)
	v_pk_fma_f32 v[12:13], v[174:175], v[92:93], v[12:13] op_sel_hi:[0,1,1]
	s_waitcnt lgkmcnt(3)
	v_pk_fma_f32 v[10:11], v[174:175], v[94:95], v[10:11] op_sel_hi:[0,1,1]
	s_waitcnt lgkmcnt(2)
	v_pk_fma_f32 v[8:9], v[174:175], v[96:97], v[8:9] op_sel_hi:[0,1,1]
	s_waitcnt lgkmcnt(1)
	v_pk_fma_f32 v[6:7], v[174:175], v[98:99], v[6:7] op_sel_hi:[0,1,1]
	s_waitcnt lgkmcnt(0)
	v_pk_fma_f32 v[4:5], v[174:175], v[100:101], v[4:5] op_sel_hi:[0,1,1]
	s_cbranch_scc1 .Lmk_b_s11
	global_load_dword v174, v[36:37], off
	v_lshl_add_u64 v[36:37], v[36:37], 0, s[26:27]
; __device__ void mod_item(const Params& p, int item, float* lds, int wave) {
;     ...
;         for (int kk = kg * 64; kk < kg * 64 + 64; ++kk) {
;             const float w = p.ada_w[(size_t)(half * 512 + kk) * MODW + col0 + col];
; #pragma unroll
;             for (int b = 0; b < NB; ++b) acc[b] += lds[kk * 36 + b] * w;
.Lmk_b_s11:
	ds_read_b96 v[70:72], v68
	ds_read2_b32 v[38:39], v68 offset0:3 offset1:4
	ds_read2_b32 v[74:75], v68 offset0:5 offset1:6
	ds_read2_b32 v[76:77], v68 offset0:7 offset1:8
	ds_read2_b32 v[78:79], v68 offset0:9 offset1:10
	ds_read2_b32 v[80:81], v68 offset0:11 offset1:12
	ds_read2_b32 v[82:83], v68 offset0:13 offset1:14
	ds_read2_b32 v[84:85], v68 offset0:15 offset1:16
	ds_read2_b32 v[86:87], v68 offset0:17 offset1:18
	ds_read2_b32 v[88:89], v68 offset0:19 offset1:20
	ds_read2_b32 v[90:91], v68 offset0:21 offset1:22
	ds_read2_b32 v[92:93], v68 offset0:23 offset1:24
	ds_read2_b32 v[94:95], v68 offset0:25 offset1:26
	ds_read2_b32 v[96:97], v68 offset0:27 offset1:28
	ds_read2_b32 v[98:99], v68 offset0:29 offset1:30
	ds_read2_b32 v[100:101], v68 offset0:31 offset1:32
	s_waitcnt lgkmcnt(14)
	v_mov_b32_e32 v102, v71
	v_mov_b32_e32 v103, v72
	v_add_u32_e32 v68, 0x90, v68
	s_waitcnt vmcnt(15)
	v_fmac_f32_e32 v69, v176, v70
	v_pk_fma_f32 v[34:35], v[176:177], v[102:103], v[34:35] op_sel_hi:[0,1,1]
	v_pk_fma_f32 v[32:33], v[176:177], v[38:39], v[32:33] op_sel_hi:[0,1,1]
	s_waitcnt lgkmcnt(13)
	v_pk_fma_f32 v[30:31], v[176:177], v[74:75], v[30:31] op_sel_hi:[0,1,1]
	s_waitcnt lgkmcnt(12)
	v_pk_fma_f32 v[28:29], v[176:177], v[76:77], v[28:29] op_sel_hi:[0,1,1]
	s_waitcnt lgkmcnt(11)
	v_pk_fma_f32 v[26:27], v[176:177], v[78:79], v[26:27] op_sel_hi:[0,1,1]
	s_waitcnt lgkmcnt(10)
	v_pk_fma_f32 v[24:25], v[176:177], v[80:81], v[24:25] op_sel_hi:[0,1,1]
	s_waitcnt lgkmcnt(9)
	v_pk_fma_f32 v[22:23], v[176:177], v[82:83], v[22:23] op_sel_hi:[0,1,1]
	s_waitcnt lgkmcnt(8)
	v_pk_fma_f32 v[20:21], v[176:177], v[84:85], v[20:21] op_sel_hi:[0,1,1]
	s_waitcnt lgkmcnt(7)
	v_pk_fma_f32 v[18:19], v[176:177], v[86:87], v[18:19] op_sel_hi:[0,1,1]
	s_waitcnt lgkmcnt(6)
	v_pk_fma_f32 v[16:17], v[176:177], v[88:89], v[16:17] op_sel_hi:[0,1,1]
	s_waitcnt lgkmcnt(5)
	v_pk_fma_f32 v[14:15], v[176:177], v[90:91], v[14:15] op_sel_hi:[0,1,1]
	s_waitcnt lgkmcnt(4)
	v_pk_fma_f32 v[12:13], v[176:177], v[92:93], v[12:13] op_sel_hi:[0,1,1]
	s_waitcnt lgkmcnt(3)
	v_pk_fma_f32 v[10:11], v[176:177], v[94:95], v[10:11] op_sel_hi:[0,1,1]
	s_waitcnt lgkmcnt(2)
	v_pk_fma_f32 v[8:9], v[176:177], v[96:97], v[8:9] op_sel_hi:[0,1,1]
	s_waitcnt lgkmcnt(1)
	v_pk_fma_f32 v[6:7], v[176:177], v[98:99], v[6:7] op_sel_hi:[0,1,1]
	s_waitcnt lgkmcnt(0)
	v_pk_fma_f32 v[4:5], v[176:177], v[100:101], v[4:5] op_sel_hi:[0,1,1]
	s_cbranch_scc1 .Lmk_b_s12
	global_load_dword v176, v[36:37], off
	v_lshl_add_u64 v[36:37], v[36:37], 0, s[26:27]
.Lmk_b_s12:
	ds_read_b96 v[70:72], v68
	ds_read2_b32 v[38:39], v68 offset0:3 offset1:4
	ds_read2_b32 v[74:75], v68 offset0:5 offset1:6
	ds_read2_b32 v[76:77], v68 offset0:7 offset1:8
	ds_read2_b32 v[78:79], v68 offset0:9 offset1:10
	ds_read2_b32 v[80:81], v68 offset0:11 offset1:12
	ds_read2_b32 v[82:83], v68 offset0:13 offset1:14
	ds_read2_b32 v[84:85], v68 offset0:15 offset1:16
	ds_read2_b32 v[86:87], v68 offset0:17 offset1:18
	ds_read2_b32 v[88:89], v68 offset0:19 offset1:20
	ds_read2_b32 v[90:91], v68 offset0:21 offset1:22
	ds_read2_b32 v[92:93], v68 offset0:23 offset1:24
	ds_read2_b32 v[94:95], v68 offset0:25 offset1:26
	ds_read2_b32 v[96:97], v68 offset0:27 offset1:28
	ds_read2_b32 v[98:99], v68 offset0:29 offset1:30
	ds_read2_b32 v[100:101], v68 offset0:31 offset1:32
	s_waitcnt lgkmcnt(14)
	v_mov_b32_e32 v102, v71
	v_mov_b32_e32 v103, v72
	v_add_u32_e32 v68, 0x90, v68
	s_waitcnt vmcnt(15)
	v_fmac_f32_e32 v69, v178, v70
	v_pk_fma_f32 v[34:35], v[178:179], v[102:103], v[34:35] op_sel_hi:[0,1,1]
	v_pk_fma_f32 v[32:33], v[178:179], v[38:39], v[32:33] op_sel_hi:[0,1,1]
	s_waitcnt lgkmcnt(13)
	v_pk_fma_f32 v[30:31], v[178:179], v[74:75], v[30:31] op_sel_hi:[0,1,1]
	s_waitcnt lgkmcnt(12)
	v_pk_fma_f32 v[28:29], v[178:179], v[76:77], v[28:29] op_sel_hi:[0,1,1]
	s_waitcnt lgkmcnt(11)
	v_pk_fma_f32 v[26:27], v[178:179], v[78:79], v[26:27] op_sel_hi:[0,1,1]
	s_waitcnt lgkmcnt(10)
	v_pk_fma_f32 v[24:25], v[178:179], v[80:81], v[24:25] op_sel_hi:[0,1,1]
	s_waitcnt lgkmcnt(9)
	v_pk_fma_f32 v[22:23], v[178:179], v[82:83], v[22:23] op_sel_hi:[0,1,1]
	s_waitcnt lgkmcnt(8)
	v_pk_fma_f32 v[20:21], v[178:179], v[84:85], v[20:21] op_sel_hi:[0,1,1]
	s_waitcnt lgkmcnt(7)
	v_pk_fma_f32 v[18:19], v[178:179], v[86:87], v[18:19] op_sel_hi:[0,1,1]
	s_waitcnt lgkmcnt(6)
	v_pk_fma_f32 v[16:17], v[178:179], v[88:89], v[16:17] op_sel_hi:[0,1,1]
	s_waitcnt lgkmcnt(5)
	v_pk_fma_f32 v[14:15], v[178:179], v[90:91], v[14:15] op_sel_hi:[0,1,1]
	s_waitcnt lgkmcnt(4)
	v_pk_fma_f32 v[12:13], v[178:179], v[92:93], v[12:13] op_sel_hi:[0,1,1]
	s_waitcnt lgkmcnt(3)
	v_pk_fma_f32 v[10:11], v[178:179], v[94:95], v[10:11] op_sel_hi:[0,1,1]
	s_waitcnt lgkmcnt(2)
	v_pk_fma_f32 v[8:9], v[178:179], v[96:97], v[8:9] op_sel_hi:[0,1,1]
	s_waitcnt lgkmcnt(1)
	v_pk_fma_f32 v[6:7], v[178:179], v[98:99], v[6:7] op_sel_hi:[0,1,1]
	s_waitcnt lgkmcnt(0)
	v_pk_fma_f32 v[4:5], v[178:179], v[100:101], v[4:5] op_sel_hi:[0,1,1]
	s_cbranch_scc1 .Lmk_b_s13
	global_load_dword v178, v[36:37], off
	v_lshl_add_u64 v[36:37], v[36:37], 0, s[26:27]
; __device__ void mod_item(const Params& p, int item, float* lds, int wave) {
;     ...
;         for (int kk = kg * 64; kk < kg * 64 + 64; ++kk) {
;             const float w = p.ada_w[(size_t)(half * 512 + kk) * MODW + col0 + col];
; #pragma unroll
;             for (int b = 0; b < NB; ++b) acc[b] += lds[kk * 36 + b] * w;
;         }
;     }
;     __syncthreads();
; #pragma unroll
;     for (int b = 0; b < NB; ++b) lds[(kg * NB + b) * 64 + col] = acc[b];
;     __syncthreads();
;     for (int e = tid; e < NB * 64; e += NTHR) { const int b = e >> 6, cc = e & 63; float s = 0.f;
; #pragma unroll
;         for (int k = 0; k < 8; ++k) s += lds[(k * NB + b) * 64 + cc];
;         mod[b * MODW + col0 + cc] = s + p.ada_b[col0 + cc]; }
.Lmk_b_s13:
	ds_read_b96 v[70:72], v68
	ds_read2_b32 v[38:39], v68 offset0:3 offset1:4
	ds_read2_b32 v[74:75], v68 offset0:5 offset1:6
	ds_read2_b32 v[76:77], v68 offset0:7 offset1:8
	ds_read2_b32 v[78:79], v68 offset0:9 offset1:10
	ds_read2_b32 v[80:81], v68 offset0:11 offset1:12
	ds_read2_b32 v[82:83], v68 offset0:13 offset1:14
	ds_read2_b32 v[84:85], v68 offset0:15 offset1:16
	ds_read2_b32 v[86:87], v68 offset0:17 offset1:18
	ds_read2_b32 v[88:89], v68 offset0:19 offset1:20
	ds_read2_b32 v[90:91], v68 offset0:21 offset1:22
	ds_read2_b32 v[92:93], v68 offset0:23 offset1:24
	ds_read2_b32 v[94:95], v68 offset0:25 offset1:26
	ds_read2_b32 v[96:97], v68 offset0:27 offset1:28
	ds_read2_b32 v[98:99], v68 offset0:29 offset1:30
	ds_read2_b32 v[100:101], v68 offset0:31 offset1:32
	s_waitcnt lgkmcnt(14)
	v_mov_b32_e32 v102, v71
	v_mov_b32_e32 v103, v72
	v_add_u32_e32 v68, 0x90, v68
	s_waitcnt vmcnt(15)
	v_fmac_f32_e32 v69, v180, v70
	v_pk_fma_f32 v[34:35], v[180:181], v[102:103], v[34:35] op_sel_hi:[0,1,1]
	v_pk_fma_f32 v[32:33], v[180:181], v[38:39], v[32:33] op_sel_hi:[0,1,1]
	s_waitcnt lgkmcnt(13)
	v_pk_fma_f32 v[30:31], v[180:181], v[74:75], v[30:31] op_sel_hi:[0,1,1]
	s_waitcnt lgkmcnt(12)
	v_pk_fma_f32 v[28:29], v[180:181], v[76:77], v[28:29] op_sel_hi:[0,1,1]
	s_waitcnt lgkmcnt(11)
	v_pk_fma_f32 v[26:27], v[180:181], v[78:79], v[26:27] op_sel_hi:[0,1,1]
	s_waitcnt lgkmcnt(10)
	v_pk_fma_f32 v[24:25], v[180:181], v[80:81], v[24:25] op_sel_hi:[0,1,1]
	s_waitcnt lgkmcnt(9)
	v_pk_fma_f32 v[22:23], v[180:181], v[82:83], v[22:23] op_sel_hi:[0,1,1]
	s_waitcnt lgkmcnt(8)
	v_pk_fma_f32 v[20:21], v[180:181], v[84:85], v[20:21] op_sel_hi:[0,1,1]
	s_waitcnt lgkmcnt(7)
	v_pk_fma_f32 v[18:19], v[180:181], v[86:87], v[18:19] op_sel_hi:[0,1,1]
	s_waitcnt lgkmcnt(6)
	v_pk_fma_f32 v[16:17], v[180:181], v[88:89], v[16:17] op_sel_hi:[0,1,1]
	s_waitcnt lgkmcnt(5)
	v_pk_fma_f32 v[14:15], v[180:181], v[90:91], v[14:15] op_sel_hi:[0,1,1]
	s_waitcnt lgkmcnt(4)
	v_pk_fma_f32 v[12:13], v[180:181], v[92:93], v[12:13] op_sel_hi:[0,1,1]
	s_waitcnt lgkmcnt(3)
	v_pk_fma_f32 v[10:11], v[180:181], v[94:95], v[10:11] op_sel_hi:[0,1,1]
	s_waitcnt lgkmcnt(2)
	v_pk_fma_f32 v[8:9], v[180:181], v[96:97], v[8:9] op_sel_hi:[0,1,1]
	s_waitcnt lgkmcnt(1)
	v_pk_fma_f32 v[6:7], v[180:181], v[98:99], v[6:7] op_sel_hi:[0,1,1]
	s_waitcnt lgkmcnt(0)
	v_pk_fma_f32 v[4:5], v[180:181], v[100:101], v[4:5] op_sel_hi:[0,1,1]
	s_cbranch_scc1 .Lmk_b_s14
	global_load_dword v180, v[36:37], off
	v_lshl_add_u64 v[36:37], v[36:37], 0, s[26:27]
.Lmk_b_s14:
	ds_read_b96 v[70:72], v68
	ds_read2_b32 v[38:39], v68 offset0:3 offset1:4
	ds_read2_b32 v[74:75], v68 offset0:5 offset1:6
	ds_read2_b32 v[76:77], v68 offset0:7 offset1:8
	ds_read2_b32 v[78:79], v68 offset0:9 offset1:10
	ds_read2_b32 v[80:81], v68 offset0:11 offset1:12
	ds_read2_b32 v[82:83], v68 offset0:13 offset1:14
	ds_read2_b32 v[84:85], v68 offset0:15 offset1:16
	ds_read2_b32 v[86:87], v68 offset0:17 offset1:18
	ds_read2_b32 v[88:89], v68 offset0:19 offset1:20
	ds_read2_b32 v[90:91], v68 offset0:21 offset1:22
	ds_read2_b32 v[92:93], v68 offset0:23 offset1:24
	ds_read2_b32 v[94:95], v68 offset0:25 offset1:26
	ds_read2_b32 v[96:97], v68 offset0:27 offset1:28
	ds_read2_b32 v[98:99], v68 offset0:29 offset1:30
	ds_read2_b32 v[100:101], v68 offset0:31 offset1:32
	s_waitcnt lgkmcnt(14)
	v_mov_b32_e32 v102, v71
	v_mov_b32_e32 v103, v72
	v_add_u32_e32 v68, 0x90, v68
	s_waitcnt vmcnt(15)
	v_fmac_f32_e32 v69, v182, v70
	v_pk_fma_f32 v[34:35], v[182:183], v[102:103], v[34:35] op_sel_hi:[0,1,1]
	v_pk_fma_f32 v[32:33], v[182:183], v[38:39], v[32:33] op_sel_hi:[0,1,1]
	s_waitcnt lgkmcnt(13)
	v_pk_fma_f32 v[30:31], v[182:183], v[74:75], v[30:31] op_sel_hi:[0,1,1]
	s_waitcnt lgkmcnt(12)
	v_pk_fma_f32 v[28:29], v[182:183], v[76:77], v[28:29] op_sel_hi:[0,1,1]
	s_waitcnt lgkmcnt(11)
	v_pk_fma_f32 v[26:27], v[182:183], v[78:79], v[26:27] op_sel_hi:[0,1,1]
	s_waitcnt lgkmcnt(10)
	v_pk_fma_f32 v[24:25], v[182:183], v[80:81], v[24:25] op_sel_hi:[0,1,1]
	s_waitcnt lgkmcnt(9)
	v_pk_fma_f32 v[22:23], v[182:183], v[82:83], v[22:23] op_sel_hi:[0,1,1]
	s_waitcnt lgkmcnt(8)
	v_pk_fma_f32 v[20:21], v[182:183], v[84:85], v[20:21] op_sel_hi:[0,1,1]
	s_waitcnt lgkmcnt(7)
	v_pk_fma_f32 v[18:19], v[182:183], v[86:87], v[18:19] op_sel_hi:[0,1,1]
	s_waitcnt lgkmcnt(6)
	v_pk_fma_f32 v[16:17], v[182:183], v[88:89], v[16:17] op_sel_hi:[0,1,1]
	s_waitcnt lgkmcnt(5)
	v_pk_fma_f32 v[14:15], v[182:183], v[90:91], v[14:15] op_sel_hi:[0,1,1]
	s_waitcnt lgkmcnt(4)
	v_pk_fma_f32 v[12:13], v[182:183], v[92:93], v[12:13] op_sel_hi:[0,1,1]
	s_waitcnt lgkmcnt(3)
	v_pk_fma_f32 v[10:11], v[182:183], v[94:95], v[10:11] op_sel_hi:[0,1,1]
	s_waitcnt lgkmcnt(2)
	v_pk_fma_f32 v[8:9], v[182:183], v[96:97], v[8:9] op_sel_hi:[0,1,1]
	s_waitcnt lgkmcnt(1)
	v_pk_fma_f32 v[6:7], v[182:183], v[98:99], v[6:7] op_sel_hi:[0,1,1]
	s_waitcnt lgkmcnt(0)
	v_pk_fma_f32 v[4:5], v[182:183], v[100:101], v[4:5] op_sel_hi:[0,1,1]
	s_cbranch_scc1 .Lmk_b_s15
	global_load_dword v182, v[36:37], off
	v_lshl_add_u64 v[36:37], v[36:37], 0, s[26:27]
.Lmk_b_s15:
	s_add_i32 s98, s98, 1
	s_cmp_lt_u32 s98, 4
	s_cbranch_scc1 .Lmk_b_loop
	s_or_b64 exec, exec, s[0:1]
	v_lshl_add_u32 v36, v2, 2, 0
	s_movk_i32 s0, 0x2100
	v_mad_u64_u32 v[38:39], s[0:1], v3, s0, v[36:37]
	s_movk_i32 s0, 0x840
	s_nop 0
	v_cmp_gt_i32_e32 vcc, s0, v65
	s_barrier
	ds_write2st64_b32 v38, v69, v34 offset1:1
	ds_write2st64_b32 v38, v35, v32 offset0:2 offset1:3
	ds_write2st64_b32 v38, v33, v30 offset0:4 offset1:5
	ds_write2st64_b32 v38, v31, v28 offset0:6 offset1:7
	ds_write2st64_b32 v38, v29, v26 offset0:8 offset1:9
	ds_write2st64_b32 v38, v27, v24 offset0:10 offset1:11
	ds_write2st64_b32 v38, v25, v22 offset0:12 offset1:13
	ds_write2st64_b32 v38, v23, v20 offset0:14 offset1:15
	ds_write2st64_b32 v38, v21, v18 offset0:16 offset1:17
	ds_write2st64_b32 v38, v19, v16 offset0:18 offset1:19
	ds_write2st64_b32 v38, v17, v14 offset0:20 offset1:21
	ds_write2st64_b32 v38, v15, v12 offset0:22 offset1:23
	ds_write2st64_b32 v38, v13, v10 offset0:24 offset1:25
	ds_write2st64_b32 v38, v11, v8 offset0:26 offset1:27
	ds_write2st64_b32 v38, v9, v6 offset0:28 offset1:29
	ds_write2st64_b32 v38, v7, v4 offset0:30 offset1:31
	ds_write_b32 v38, v5 offset:8192
	s_waitcnt lgkmcnt(0)
	s_barrier
	s_and_saveexec_b64 s[0:1], vcc
	s_cbranch_execz .LBB0_50
	v_readlane_b32 s4, v253, 12
	v_or_b32_e32 v0, s24, v2
	v_readlane_b32 s5, v253, 13
	v_readlane_b32 s14, v253, 22
	v_readlane_b32 s15, v253, 23
	s_mov_b64 s[4:5], 0
	v_readlane_b32 s6, v253, 14
	v_lshl_add_u64 v[2:3], v[0:1], 2, s[14:15]
	v_readlane_b32 s7, v253, 15
	v_readlane_b32 s8, v253, 16
	v_readlane_b32 s9, v253, 17
	v_readlane_b32 s10, v253, 18
	v_readlane_b32 s11, v253, 19
	v_readlane_b32 s12, v253, 20
	v_readlane_b32 s13, v253, 21
	v_readlane_b32 s16, v253, 24
	v_readlane_b32 s17, v253, 25
	v_readlane_b32 s18, v253, 26
	v_readlane_b32 s19, v253, 27

; __global__ void __launch_bounds__(NTHR, 2) fwd_kernel(Params p) {
	.amdhsa_kernel _Z10fwd_kernel6Params
		.amdhsa_group_segment_fixed_size 0
		.amdhsa_private_segment_fixed_size 0
		.amdhsa_kernarg_size 504
		.amdhsa_user_sgpr_count 2
		.amdhsa_user_sgpr_dispatch_ptr 0
		.amdhsa_user_sgpr_queue_ptr 0
		.amdhsa_user_sgpr_kernarg_segment_ptr 1
		.amdhsa_user_sgpr_dispatch_id 0
		.amdhsa_user_sgpr_kernarg_preload_length 0
		.amdhsa_user_sgpr_kernarg_preload_offset 0
		.amdhsa_user_sgpr_private_segment_size 0
		.amdhsa_uses_dynamic_stack 0
		.amdhsa_enable_private_segment 0
		.amdhsa_system_sgpr_workgroup_id_x 1
		.amdhsa_system_sgpr_workgroup_id_y 0
		.amdhsa_system_sgpr_workgroup_id_z 0
		.amdhsa_system_sgpr_workgroup_info 0
		.amdhsa_system_vgpr_workitem_id 2
		.amdhsa_next_free_vgpr 255
		.amdhsa_next_free_sgpr 102
		.amdhsa_accum_offset 256
		.amdhsa_reserve_vcc 1
		.amdhsa_float_round_mode_32 0
		.amdhsa_float_round_mode_16_64 0
		.amdhsa_float_denorm_mode_32 3
		.amdhsa_float_denorm_mode_16_64 3
		.amdhsa_dx10_clamp 1
		.amdhsa_ieee_mode 1
		.amdhsa_fp16_overflow 0
		.amdhsa_tg_split 0
		.amdhsa_exception_fp_ieee_invalid_op 0
		.amdhsa_exception_fp_denorm_src 0
		.amdhsa_exception_fp_ieee_div_zero 0
		.amdhsa_exception_fp_ieee_overflow 0
		.amdhsa_exception_fp_ieee_underflow 0
		.amdhsa_exception_fp_ieee_inexact 0
		.amdhsa_exception_int_div_zero 0
	.end_amdhsa_kernel

; __global__ void __launch_bounds__(NTHR, 2) fwd_kernel(Params p) {
amdhsa.kernels:
  - .agpr_count:     0
    .args:
      - .offset:         0
        .size:           248
        .value_kind:     by_value
      - .offset:         248
        .size:           4
        .value_kind:     hidden_block_count_x
      - .offset:         252
        .size:           4
        .value_kind:     hidden_block_count_y
      - .offset:         256
        .size:           4
        .value_kind:     hidden_block_count_z
      - .offset:         260
        .size:           2
        .value_kind:     hidden_group_size_x
      - .offset:         262
        .size:           2
        .value_kind:     hidden_group_size_y
      - .offset:         264
        .size:           2
        .value_kind:     hidden_group_size_z
      - .offset:         266
        .size:           2
        .value_kind:     hidden_remainder_x
      - .offset:         268
        .size:           2
        .value_kind:     hidden_remainder_y
      - .offset:         270
        .size:           2
        .value_kind:     hidden_remainder_z
      - .offset:         288
        .size:           8
        .value_kind:     hidden_global_offset_x
      - .offset:         296
        .size:           8
        .value_kind:     hidden_global_offset_y
      - .offset:         304
        .size:           8
        .value_kind:     hidden_global_offset_z
      - .offset:         312
        .size:           2
        .value_kind:     hidden_grid_dims
      - .offset:         336
        .size:           8
        .value_kind:     hidden_multigrid_sync_arg
      - .offset:         368
        .size:           4
        .value_kind:     hidden_dynamic_lds_size
    .group_segment_fixed_size: 0
    .kernarg_segment_align: 8
    .kernarg_segment_size: 504
    .language:       OpenCL C
    .language_version:
      - 2
      - 0
    .max_flat_workgroup_size: 512
    .name:           _Z10fwd_kernel6Params
    .private_segment_fixed_size: 0
    .sgpr_count:     108
    .sgpr_spill_count: 139
    .symbol:         _Z10fwd_kernel6Params.kd
    .uniform_work_group_size: 1
    .uses_dynamic_stack: false
    .vgpr_count:     255
    .vgpr_spill_count: 0
    .wavefront_size: 64
